# P1 store loop specialised per mode; write-through (sc1) stores before grid barriers in P0, P1, attention; batched EpiMerge loads
# speedup vs baseline: 1.0304x; 1.0120x over previous
.LBB0_17:
	v_lshl_add_u64 v[62:63], v[34:35], 0, s[18:19]
	v_lshl_add_u64 v[64:65], v[32:33], 0, s[18:19]
	v_lshl_add_u64 v[66:67], v[30:31], 0, s[18:19]
	v_lshl_add_u64 v[68:69], v[28:29], 0, s[18:19]
	v_lshl_add_u64 v[70:71], v[26:27], 0, s[18:19]
	v_lshl_add_u64 v[72:73], v[24:25], 0, s[18:19]
	v_lshl_add_u64 v[74:75], v[22:23], 0, s[18:19]
	v_lshl_add_u64 v[76:77], v[20:21], 0, s[18:19]
	v_lshl_add_u64 v[78:79], v[18:19], 0, s[18:19]
	v_lshl_add_u64 v[80:81], v[16:17], 0, s[18:19]
	v_lshl_add_u64 v[82:83], v[14:15], 0, s[18:19]
	v_lshl_add_u64 v[84:85], v[12:13], 0, s[18:19]
	v_lshl_add_u64 v[86:87], v[10:11], 0, s[18:19]
	v_lshl_add_u64 v[88:89], v[8:9], 0, s[18:19]
	v_lshl_add_u64 v[90:91], v[6:7], 0, s[18:19]
	v_lshl_add_u64 v[92:93], v[4:5], 0, s[18:19]
	global_load_dword v94, v[62:63], off nt
	global_load_dword v95, v[64:65], off nt
	global_load_dword v96, v[66:67], off nt
	global_load_dword v97, v[68:69], off nt
	global_load_dword v98, v[70:71], off nt
	global_load_dword v99, v[72:73], off nt
	global_load_dword v100, v[74:75], off nt
	global_load_dword v101, v[76:77], off nt
	global_load_dword v102, v[78:79], off nt
	global_load_dword v103, v[80:81], off nt
	global_load_dword v104, v[82:83], off nt
	global_load_dword v105, v[84:85], off nt
	global_load_dword v106, v[86:87], off nt
	global_load_dword v107, v[88:89], off nt
	global_load_dword v108, v[90:91], off nt
	global_load_dword v62, v[92:93], off nt
	s_add_u32 s18, s18, 0xc0000
	s_addc_u32 s19, s19, 0
	v_add_u32_e32 v63, 0x400, v61
	v_add_u32_e32 v64, 0x800, v61
	v_add_u32_e32 v65, 0xc00, v61
	s_cmp_lg_u32 s18, 0x180000
	s_waitcnt vmcnt(14)
	ds_write2_b32 v61, v94, v95 offset1:66
	s_waitcnt vmcnt(12)
	ds_write2_b32 v61, v96, v97 offset0:132 offset1:198
	s_waitcnt vmcnt(10)
	ds_write2_b32 v63, v98, v99 offset0:8 offset1:74
	s_waitcnt vmcnt(8)
	ds_write2_b32 v63, v100, v101 offset0:140 offset1:206
	s_waitcnt vmcnt(6)
	ds_write2_b32 v64, v102, v103 offset0:16 offset1:82
	s_waitcnt vmcnt(4)
	ds_write2_b32 v64, v104, v105 offset0:148 offset1:214
	s_waitcnt vmcnt(2)
	ds_write2_b32 v65, v106, v107 offset0:24 offset1:90
	s_waitcnt vmcnt(0)
	ds_write2_b32 v65, v108, v62 offset0:156 offset1:222
	v_add_u32_e32 v61, 0x1080, v61
	s_cbranch_scc1 .LBB0_17
	s_waitcnt lgkmcnt(0)
	ds_read2_b32 v[8:9], v38 offset1:8
	ds_read2_b32 v[12:13], v38 offset0:33 offset1:41
	ds_read2_b32 v[14:15], v38 offset0:66 offset1:74
	ds_read2_b32 v[16:17], v38 offset0:99 offset1:107
	ds_read2_b32 v[18:19], v38 offset0:132 offset1:140
	ds_read2_b32 v[20:21], v38 offset0:165 offset1:173
	s_waitcnt lgkmcnt(5)
	v_bfe_u32 v4, v8, 16, 1
	v_add3_u32 v4, v8, v4, s22
	s_waitcnt lgkmcnt(4)
	v_bfe_u32 v5, v12, 16, 1
	v_lshrrev_b32_e32 v4, 16, v4
	v_add3_u32 v5, v12, v5, s22
	v_and_or_b32 v4, v5, s23, v4
	s_waitcnt lgkmcnt(3)
	v_bfe_u32 v5, v14, 16, 1
	v_add3_u32 v5, v14, v5, s22
	s_waitcnt lgkmcnt(2)
	v_bfe_u32 v6, v16, 16, 1
	ds_read2_b32 v[22:23], v38 offset0:198 offset1:206
	v_lshrrev_b32_e32 v5, 16, v5
	v_add3_u32 v6, v16, v6, s22
	ds_read2_b32 v[24:25], v38 offset0:231 offset1:239
	v_and_or_b32 v5, v6, s23, v5
	s_waitcnt lgkmcnt(3)
	v_bfe_u32 v6, v18, 16, 1
	v_add3_u32 v6, v18, v6, s22
	s_waitcnt lgkmcnt(2)
	v_bfe_u32 v7, v20, 16, 1
	v_lshrrev_b32_e32 v6, 16, v6
	v_add3_u32 v7, v20, v7, s22
	v_and_or_b32 v6, v7, s23, v6
	s_waitcnt lgkmcnt(1)
	v_bfe_u32 v7, v22, 16, 1
	v_or_b32_e32 v26, s8, v37
	s_ashr_i32 s13, s12, 31
	v_add3_u32 v7, v22, v7, s22
	s_waitcnt lgkmcnt(0)
	v_bfe_u32 v8, v24, 16, 1
	v_ashrrev_i32_e32 v27, 31, v26
	v_lshl_add_u64 v[10:11], s[12:13], 1, v[0:1]
	v_lshrrev_b32_e32 v7, 16, v7
	v_add3_u32 v8, v24, v8, s22
	v_lshlrev_b64 v[26:27], 11, v[26:27]
	v_and_or_b32 v7, v8, s23, v7
	v_lshl_add_u64 v[26:27], v[10:11], 0, v[26:27]
	global_store_dwordx4 v[26:27], v[4:7], off sc1
	v_bfe_u32 v8, v25, 16, 1
	v_add3_u32 v8, v25, v8, s22
	v_bfe_u32 v4, v9, 16, 1
	v_add3_u32 v4, v9, v4, s22
	v_bfe_u32 v5, v13, 16, 1
	v_lshrrev_b32_e32 v4, 16, v4
	v_add3_u32 v5, v13, v5, s22
	v_and_or_b32 v4, v5, s23, v4
	v_bfe_u32 v5, v15, 16, 1
	v_add3_u32 v5, v15, v5, s22
	v_bfe_u32 v6, v17, 16, 1
	v_lshrrev_b32_e32 v5, 16, v5
	v_add3_u32 v6, v17, v6, s22
	v_and_or_b32 v5, v6, s23, v5
	v_bfe_u32 v6, v19, 16, 1
	v_add3_u32 v6, v19, v6, s22
	v_bfe_u32 v7, v21, 16, 1
	v_lshrrev_b32_e32 v6, 16, v6
	v_add3_u32 v7, v21, v7, s22
	v_and_or_b32 v6, v7, s23, v6
	v_bfe_u32 v7, v23, 16, 1
	v_add3_u32 v7, v23, v7, s22
	v_lshrrev_b32_e32 v7, 16, v7
	v_and_or_b32 v7, v8, s23, v7
	v_or_b32_e32 v8, s8, v39
	v_ashrrev_i32_e32 v9, 31, v8
	v_lshlrev_b64 v[8:9], 11, v[8:9]
	ds_read2_b32 v[12:13], v38 offset0:16 offset1:24
	v_lshl_add_u64 v[8:9], v[10:11], 0, v[8:9]
	global_store_dwordx4 v[8:9], v[4:7], off sc1
	ds_read2_b32 v[8:9], v38 offset0:49 offset1:57
	ds_read2_b32 v[14:15], v38 offset0:82 offset1:90
	ds_read2_b32 v[16:17], v38 offset0:115 offset1:123
	s_waitcnt lgkmcnt(3)
	v_bfe_u32 v4, v12, 16, 1
	v_add3_u32 v4, v12, v4, s22
	s_waitcnt lgkmcnt(2)
	v_bfe_u32 v5, v8, 16, 1
	ds_read2_b32 v[18:19], v38 offset0:148 offset1:156
	v_lshrrev_b32_e32 v4, 16, v4
	v_add3_u32 v5, v8, v5, s22
	ds_read2_b32 v[20:21], v38 offset0:181 offset1:189
	v_and_or_b32 v4, v5, s23, v4
	s_waitcnt lgkmcnt(3)
	v_bfe_u32 v5, v14, 16, 1
	v_add3_u32 v5, v14, v5, s22
	s_waitcnt lgkmcnt(2)
	v_bfe_u32 v6, v16, 16, 1
	ds_read2_b32 v[22:23], v38 offset0:214 offset1:222
	v_lshrrev_b32_e32 v5, 16, v5
	v_add3_u32 v6, v16, v6, s22
	ds_read2_b32 v[24:25], v38 offset0:247 offset1:255
	v_and_or_b32 v5, v6, s23, v5
	s_waitcnt lgkmcnt(3)
	v_bfe_u32 v6, v18, 16, 1
	v_add3_u32 v6, v18, v6, s22
	s_waitcnt lgkmcnt(2)
	v_bfe_u32 v7, v20, 16, 1
	v_lshrrev_b32_e32 v6, 16, v6
	v_add3_u32 v7, v20, v7, s22
	v_and_or_b32 v6, v7, s23, v6
	s_waitcnt lgkmcnt(1)
	v_bfe_u32 v7, v22, 16, 1
	v_or_b32_e32 v26, s8, v41
	v_add3_u32 v7, v22, v7, s22
	s_waitcnt lgkmcnt(0)
	v_bfe_u32 v8, v24, 16, 1
	v_ashrrev_i32_e32 v27, 31, v26
	v_lshrrev_b32_e32 v7, 16, v7
	v_add3_u32 v8, v24, v8, s22
	v_lshlrev_b64 v[26:27], 11, v[26:27]
	v_and_or_b32 v7, v8, s23, v7
	v_lshl_add_u64 v[26:27], v[10:11], 0, v[26:27]
	global_store_dwordx4 v[26:27], v[4:7], off sc1
	v_bfe_u32 v8, v25, 16, 1
	v_add3_u32 v8, v25, v8, s22
	v_bfe_u32 v4, v13, 16, 1
	v_add3_u32 v4, v13, v4, s22
	v_bfe_u32 v5, v9, 16, 1
	v_lshrrev_b32_e32 v4, 16, v4
	v_add3_u32 v5, v9, v5, s22
	v_and_or_b32 v4, v5, s23, v4
	v_bfe_u32 v5, v15, 16, 1
	v_add3_u32 v5, v15, v5, s22
	v_bfe_u32 v6, v17, 16, 1
	v_lshrrev_b32_e32 v5, 16, v5
	v_add3_u32 v6, v17, v6, s22
	v_and_or_b32 v5, v6, s23, v5
	v_bfe_u32 v6, v19, 16, 1
	v_add3_u32 v6, v19, v6, s22
	v_bfe_u32 v7, v21, 16, 1
	v_lshrrev_b32_e32 v6, 16, v6
	v_add3_u32 v7, v21, v7, s22
	v_and_or_b32 v6, v7, s23, v6
	v_bfe_u32 v7, v23, 16, 1
	v_add3_u32 v7, v23, v7, s22
	v_lshrrev_b32_e32 v7, 16, v7
	v_and_or_b32 v7, v8, s23, v7
	v_or_b32_e32 v8, s8, v42
	v_ashrrev_i32_e32 v9, 31, v8
	v_lshlrev_b64 v[8:9], 11, v[8:9]
	v_lshl_add_u64 v[8:9], v[10:11], 0, v[8:9]
	global_store_dwordx4 v[8:9], v[4:7], off sc1
	s_waitcnt lgkmcnt(0)
	s_add_i32 s25, s25, s24
	s_cmpk_gt_i32 s25, 0xbff
	s_cbranch_scc0 .LBB0_16

.LBB0_22:
	global_load_dwordx4 v[52:55], v[44:45], off offset:-2048 nt
	global_load_dwordx4 v[56:59], v[44:45], off offset:-1024 nt
	global_load_dwordx4 v[36:39], v[44:45], off nt
	global_load_dwordx4 v[32:35], v[44:45], off offset:1024 nt
	s_add_i32 s4, s24, s27
	s_cmpk_lt_i32 s4, 0x4000
	s_cselect_b32 s34, s4, s27
	s_ashr_i32 s35, s34, 31
	s_lshl_b64 s[34:35], s[34:35], 12
	v_lshl_add_u64 v[50:51], v[42:43], 0, s[34:35]
	global_load_dwordx4 v[28:31], v[50:51], off nt
	global_load_dwordx4 v[24:27], v[50:51], off offset:1024 nt
	global_load_dwordx4 v[20:23], v[50:51], off offset:2048 nt
	global_load_dwordx4 v[16:19], v[50:51], off offset:3072 nt
	s_cmpk_gt_i32 s4, 0x3fff
	s_waitcnt vmcnt(7)
	v_mul_f32_e32 v50, v53, v53
	v_mul_f32_e32 v51, v55, v55
	s_waitcnt vmcnt(6)
	v_mul_f32_e32 v60, v57, v57
	v_mul_f32_e32 v61, v59, v59
	s_waitcnt vmcnt(5)
	v_mul_f32_e32 v62, v37, v37
	v_mul_f32_e32 v63, v39, v39
	v_fmac_f32_e32 v50, v52, v52
	v_fmac_f32_e32 v51, v54, v54
	v_fmac_f32_e32 v60, v56, v56
	v_fmac_f32_e32 v61, v58, v58
	s_waitcnt vmcnt(4)
	v_mul_f32_e32 v64, v33, v33
	v_mul_f32_e32 v65, v35, v35
	v_fmac_f32_e32 v62, v36, v36
	v_fmac_f32_e32 v63, v38, v38
	v_add_f32_e32 v50, v50, v51
	v_add_f32_e32 v51, v60, v61
	v_fmac_f32_e32 v64, v32, v32
	v_fmac_f32_e32 v65, v34, v34
	v_add_f32_e32 v60, v62, v63
	v_add_f32_e32 v50, v50, v51
	v_add_f32_e32 v61, v64, v65
	v_add_f32_e32 v50, v50, v60
	v_add_f32_e32 v50, v50, v61
	ds_swizzle_b32 v67, v50 offset:swizzle(SWAP,1)
	s_waitcnt vmcnt(3)
	v_mul_f32_e32 v51, v29, v29
	v_mul_f32_e32 v60, v31, v31
	s_waitcnt vmcnt(2)
	v_mul_f32_e32 v61, v25, v25
	v_mul_f32_e32 v62, v27, v27
	v_fmac_f32_e32 v51, v28, v28
	v_fmac_f32_e32 v60, v30, v30
	v_fmac_f32_e32 v61, v24, v24
	v_fmac_f32_e32 v62, v26, v26
	v_add_f32_e32 v51, v51, v60
	v_add_f32_e32 v60, v61, v62
	s_waitcnt lgkmcnt(0)
	v_add_f32_e32 v50, v50, v67
	s_waitcnt vmcnt(1)
	v_mul_f32_e32 v63, v21, v21
	v_mul_f32_e32 v64, v23, v23
	v_add_f32_e32 v51, v51, v60
	ds_swizzle_b32 v60, v50 offset:swizzle(SWAP,2)
	s_waitcnt vmcnt(0)
	v_mul_f32_e32 v65, v17, v17
	v_mul_f32_e32 v66, v19, v19
	v_fmac_f32_e32 v63, v20, v20
	v_fmac_f32_e32 v64, v22, v22
	v_fmac_f32_e32 v65, v16, v16
	v_fmac_f32_e32 v66, v18, v18
	v_add_f32_e32 v61, v63, v64
	v_add_f32_e32 v62, v65, v66
	v_add_f32_e32 v51, v51, v61
	v_add_f32_e32 v51, v51, v62
	ds_swizzle_b32 v61, v51 offset:swizzle(SWAP,1)
	s_waitcnt lgkmcnt(1)
	v_add_f32_e32 v50, v50, v60
	ds_swizzle_b32 v60, v50 offset:swizzle(SWAP,4)
	s_waitcnt lgkmcnt(1)
	v_add_f32_e32 v51, v51, v61
	ds_swizzle_b32 v61, v51 offset:swizzle(SWAP,2)
	s_waitcnt lgkmcnt(1)
	v_add_f32_e32 v60, v50, v60
	ds_swizzle_b32 v62, v60 offset:swizzle(SWAP,8)
	s_waitcnt lgkmcnt(1)
	v_add_f32_e32 v61, v51, v61
	ds_swizzle_b32 v63, v61 offset:swizzle(SWAP,4)
	s_waitcnt lgkmcnt(1)
	v_add_f32_e32 v62, v60, v62
	ds_swizzle_b32 v64, v62 offset:swizzle(SWAP,16)
	v_lshl_add_u64 v[50:51], s[12:13], 0, v[40:41]
	v_add_co_u32_e32 v60, vcc, s26, v50
	s_waitcnt lgkmcnt(1)
	v_add_f32_e32 v63, v61, v63
	ds_swizzle_b32 v65, v63 offset:swizzle(SWAP,8)
	s_waitcnt lgkmcnt(1)
	v_add_f32_e32 v50, v62, v64
	v_mov_b32_e32 v62, v50
	s_nop 1
	v_permlane32_swap_b32_e32 v50, v62
	v_add_f32_e32 v50, v50, v62
	v_addc_co_u32_e32 v61, vcc, 0, v51, vcc
	v_fmamk_f32 v50, v50, 0x3a800000, v48
	s_waitcnt lgkmcnt(0)
	v_add_f32_e32 v51, v63, v65
	v_mul_f32_e32 v62, 0x4f800000, v50
	v_cmp_gt_f32_e32 vcc, s7, v50
	ds_swizzle_b32 v63, v51 offset:swizzle(SWAP,16)
	s_nop 0
	v_cndmask_b32_e32 v62, v50, v62, vcc
	v_sqrt_f32_e32 v64, v62
	s_waitcnt lgkmcnt(0)
	v_add_f32_e32 v50, v51, v63
	v_mov_b32_e32 v51, v50
	v_add_u32_e32 v63, -1, v64
	v_add_u32_e32 v65, 1, v64
	v_fma_f32 v66, -v63, v64, v62
	v_fma_f32 v67, -v65, v64, v62
	v_cmp_ge_f32_e64 s[4:5], 0, v66
	v_permlane32_swap_b32_e32 v50, v51
	s_nop 0
	v_cndmask_b32_e64 v63, v64, v63, s[4:5]
	v_cmp_lt_f32_e64 s[4:5], 0, v67
	s_nop 1
	v_cndmask_b32_e64 v63, v63, v65, s[4:5]
	v_mul_f32_e32 v64, 0x37800000, v63
	v_cndmask_b32_e32 v63, v63, v64, vcc
	v_cmp_class_f32_e32 vcc, v62, v49
	s_nop 1
	v_cndmask_b32_e32 v62, v63, v62, vcc
	v_div_scale_f32 v63, s[4:5], v62, v62, 1.0
	v_rcp_f32_e32 v64, v63
	v_div_scale_f32 v65, vcc, 1.0, v62, 1.0
	v_fma_f32 v66, -v63, v64, 1.0
	v_fmac_f32_e32 v64, v66, v64
	v_mul_f32_e32 v66, v65, v64
	v_fma_f32 v67, -v63, v66, v65
	v_fmac_f32_e32 v66, v67, v64
	v_fma_f32 v63, -v63, v66, v65
	v_div_fmas_f32 v63, v63, v64, v66
	v_div_fixup_f32 v62, v63, v62, 1.0
	v_pk_mul_f32 v[52:53], v[52:53], v[62:63] op_sel_hi:[1,0]
	v_pk_mul_f32 v[54:55], v[54:55], v[62:63] op_sel_hi:[1,0]
	v_pk_mul_f32 v[52:53], v[0:1], v[52:53]
	v_pk_mul_f32 v[54:55], v[2:3], v[54:55]
	v_pk_mul_f32 v[56:57], v[56:57], v[62:63] op_sel_hi:[1,0]
	v_pk_mul_f32 v[58:59], v[58:59], v[62:63] op_sel_hi:[1,0]
	v_bfe_u32 v63, v52, 16, 1
	v_bfe_u32 v65, v54, 16, 1
	v_bfe_u32 v64, v53, 16, 1
	v_bfe_u32 v66, v55, 16, 1
	v_add3_u32 v52, v52, v63, s9
	v_add3_u32 v54, v54, v65, s9
	v_pk_mul_f32 v[58:59], v[6:7], v[58:59]
	v_add3_u32 v53, v53, v64, s9
	v_add3_u32 v55, v55, v66, s9
	v_lshrrev_b32_e32 v52, 16, v52
	v_lshrrev_b32_e32 v54, 16, v54
	v_bfe_u32 v69, v58, 16, 1
	v_and_or_b32 v52, v53, s25, v52
	v_and_or_b32 v53, v55, s25, v54
	v_add3_u32 v58, v58, v69, s9
	global_store_dwordx2 v[60:61], v[52:53], off sc1
	v_bfe_u32 v53, v59, 16, 1
	v_pk_mul_f32 v[36:37], v[36:37], v[62:63] op_sel_hi:[1,0]
	v_lshrrev_b32_e32 v52, 16, v58
	v_add3_u32 v53, v59, v53, s9
	v_pk_mul_f32 v[36:37], v[8:9], v[36:37]
	v_and_or_b32 v55, v53, s25, v52
	v_bfe_u32 v52, v36, 16, 1
	v_pk_mul_f32 v[38:39], v[38:39], v[62:63] op_sel_hi:[1,0]
	v_add3_u32 v36, v36, v52, s9
	v_bfe_u32 v52, v37, 16, 1
	v_pk_mul_f32 v[38:39], v[10:11], v[38:39]
	v_lshrrev_b32_e32 v36, 16, v36
	v_add3_u32 v37, v37, v52, s9
	v_and_or_b32 v36, v37, s25, v36
	v_bfe_u32 v37, v38, 16, 1
	v_add3_u32 v37, v38, v37, s9
	v_bfe_u32 v38, v39, 16, 1
	v_lshrrev_b32_e32 v37, 16, v37
	v_add3_u32 v38, v39, v38, s9
	v_pk_mul_f32 v[32:33], v[32:33], v[62:63] op_sel_hi:[1,0]
	v_and_or_b32 v37, v38, s25, v37
	v_pk_mul_f32 v[32:33], v[12:13], v[32:33]
	global_store_dwordx2 v[60:61], v[36:37], off offset:1024 sc1
	v_bfe_u32 v36, v32, 16, 1
	v_pk_mul_f32 v[34:35], v[34:35], v[62:63] op_sel_hi:[1,0]
	v_add3_u32 v32, v32, v36, s9
	v_bfe_u32 v36, v33, 16, 1
	v_pk_mul_f32 v[56:57], v[4:5], v[56:57]
	v_pk_mul_f32 v[34:35], v[14:15], v[34:35]
	v_lshrrev_b32_e32 v32, 16, v32
	v_add3_u32 v33, v33, v36, s9
	v_bfe_u32 v67, v56, 16, 1
	v_and_or_b32 v32, v33, s25, v32
	v_bfe_u32 v33, v34, 16, 1
	v_bfe_u32 v68, v57, 16, 1
	v_add3_u32 v56, v56, v67, s9
	v_add3_u32 v33, v34, v33, s9
	v_bfe_u32 v34, v35, 16, 1
	v_add3_u32 v57, v57, v68, s9
	v_lshrrev_b32_e32 v56, 16, v56
	v_lshrrev_b32_e32 v33, 16, v33
	v_add3_u32 v34, v35, v34, s9
	v_and_or_b32 v54, v57, s25, v56
	v_and_or_b32 v33, v34, s25, v33
	global_store_dwordx2 v[60:61], v[54:55], off offset:512 sc1
	global_store_dwordx2 v[60:61], v[32:33], off offset:1536 sc1
	s_cbranch_scc1 .LBB0_21
	v_add_f32_e32 v32, v50, v51
	v_fmamk_f32 v32, v32, 0x3a800000, v48
	v_mul_f32_e32 v33, 0x4f800000, v32
	v_cmp_gt_f32_e32 vcc, s7, v32
	s_nop 1
	v_cndmask_b32_e32 v32, v32, v33, vcc
	v_sqrt_f32_e32 v33, v32
	s_nop 0
	v_add_u32_e32 v34, -1, v33
	v_fma_f32 v36, -v34, v33, v32
	v_add_u32_e32 v35, 1, v33
	v_cmp_ge_f32_e64 s[4:5], 0, v36
	s_nop 1
	v_cndmask_b32_e64 v34, v33, v34, s[4:5]
	v_fma_f32 v33, -v35, v33, v32
	v_cmp_lt_f32_e64 s[4:5], 0, v33
	s_nop 1
	v_cndmask_b32_e64 v33, v34, v35, s[4:5]
	v_mul_f32_e32 v34, 0x37800000, v33
	v_cndmask_b32_e32 v33, v33, v34, vcc
	v_cmp_class_f32_e32 vcc, v32, v49
	s_nop 1
	v_cndmask_b32_e32 v32, v33, v32, vcc
	v_div_scale_f32 v33, s[4:5], v32, v32, 1.0
	v_rcp_f32_e32 v34, v33
	s_nop 0
	v_fma_f32 v35, -v33, v34, 1.0
	v_fmac_f32_e32 v34, v35, v34
	v_div_scale_f32 v35, vcc, 1.0, v32, 1.0
	v_mul_f32_e32 v36, v35, v34
	v_fma_f32 v37, -v33, v36, v35
	v_fmac_f32_e32 v36, v37, v34
	v_fma_f32 v33, -v33, v36, v35
	v_div_fmas_f32 v33, v33, v34, v36
	v_div_fixup_f32 v32, v33, v32, 1.0
	v_pk_mul_f32 v[28:29], v[28:29], v[32:33] op_sel_hi:[1,0]
	v_pk_mul_f32 v[30:31], v[30:31], v[32:33] op_sel_hi:[1,0]
	v_pk_mul_f32 v[28:29], v[0:1], v[28:29]
	v_pk_mul_f32 v[30:31], v[2:3], v[30:31]
	v_bfe_u32 v33, v28, 16, 1
	v_add3_u32 v28, v28, v33, s9
	v_bfe_u32 v33, v29, 16, 1
	v_lshrrev_b32_e32 v28, 16, v28
	v_add3_u32 v29, v29, v33, s9
	v_and_or_b32 v28, v29, s25, v28
	v_bfe_u32 v29, v30, 16, 1
	v_add3_u32 v29, v30, v29, s9
	v_bfe_u32 v30, v31, 16, 1
	v_lshl_add_u64 v[34:35], s[20:21], 0, v[40:41]
	v_lshrrev_b32_e32 v29, 16, v29
	v_add3_u32 v30, v31, v30, s9
	v_and_or_b32 v29, v30, s25, v29
	v_add_co_u32_e32 v30, vcc, s26, v34
	v_pk_mul_f32 v[24:25], v[24:25], v[32:33] op_sel_hi:[1,0]
	s_nop 0
	v_addc_co_u32_e32 v31, vcc, 0, v35, vcc
	v_pk_mul_f32 v[24:25], v[4:5], v[24:25]
	global_store_dwordx2 v[30:31], v[28:29], off sc1
	v_bfe_u32 v28, v24, 16, 1
	v_pk_mul_f32 v[26:27], v[26:27], v[32:33] op_sel_hi:[1,0]
	v_add3_u32 v24, v24, v28, s9
	v_bfe_u32 v28, v25, 16, 1
	v_pk_mul_f32 v[26:27], v[6:7], v[26:27]
	v_lshrrev_b32_e32 v24, 16, v24
	v_add3_u32 v25, v25, v28, s9
	v_and_or_b32 v24, v25, s25, v24
	v_bfe_u32 v25, v26, 16, 1
	v_add3_u32 v25, v26, v25, s9
	v_bfe_u32 v26, v27, 16, 1
	v_lshrrev_b32_e32 v25, 16, v25
	v_add3_u32 v26, v27, v26, s9
	v_pk_mul_f32 v[20:21], v[20:21], v[32:33] op_sel_hi:[1,0]
	v_and_or_b32 v25, v26, s25, v25
	v_pk_mul_f32 v[20:21], v[8:9], v[20:21]
	global_store_dwordx2 v[30:31], v[24:25], off offset:512 sc1
	v_bfe_u32 v24, v20, 16, 1
	v_pk_mul_f32 v[22:23], v[22:23], v[32:33] op_sel_hi:[1,0]
	v_add3_u32 v20, v20, v24, s9
	v_bfe_u32 v24, v21, 16, 1
	v_pk_mul_f32 v[22:23], v[10:11], v[22:23]
	v_lshrrev_b32_e32 v20, 16, v20
	v_add3_u32 v21, v21, v24, s9
	v_and_or_b32 v20, v21, s25, v20
	v_bfe_u32 v21, v22, 16, 1
	v_add3_u32 v21, v22, v21, s9
	v_bfe_u32 v22, v23, 16, 1
	v_lshrrev_b32_e32 v21, 16, v21
	v_add3_u32 v22, v23, v22, s9
	v_pk_mul_f32 v[16:17], v[16:17], v[32:33] op_sel_hi:[1,0]
	v_and_or_b32 v21, v22, s25, v21
	v_pk_mul_f32 v[16:17], v[12:13], v[16:17]
	global_store_dwordx2 v[30:31], v[20:21], off offset:1024 sc1
	v_bfe_u32 v20, v16, 16, 1
	v_pk_mul_f32 v[18:19], v[18:19], v[32:33] op_sel_hi:[1,0]
	v_add3_u32 v16, v16, v20, s9
	v_bfe_u32 v20, v17, 16, 1
	v_pk_mul_f32 v[18:19], v[14:15], v[18:19]
	v_lshrrev_b32_e32 v16, 16, v16
	v_add3_u32 v17, v17, v20, s9
	v_and_or_b32 v16, v17, s25, v16
	v_bfe_u32 v17, v18, 16, 1
	v_add3_u32 v17, v18, v17, s9
	v_bfe_u32 v18, v19, 16, 1
	v_lshrrev_b32_e32 v17, 16, v17
	v_add3_u32 v18, v19, v18, s9
	v_and_or_b32 v17, v18, s25, v17
	global_store_dwordx2 v[30:31], v[16:17], off offset:1536 sc1
	s_branch .LBB0_21

.LBB0_143:
	s_cmp_lg_u32 s12, 1
	s_cselect_b64 s[46:47], -1, 0
	s_or_b64 s[46:47], s[26:27], s[46:47]
	v_lshl_add_u32 v187, s40, 8, v178
	s_and_b64 vcc, exec, s[46:47]
	s_cbranch_vccnz .LBB0_147
	v_lshlrev_b32_e32 v128, 6, v187
	v_and_b32_e32 v160, 0x7f3c0, v128
	global_load_dwordx4 v[148:151], v160, s[18:19] offset:32
	global_load_dwordx4 v[136:139], v160, s[18:19] offset:48
	global_load_dwordx4 v[188:191], v160, s[18:19] offset:1056
	global_load_dwordx4 v[192:195], v160, s[18:19]
	global_load_dwordx4 v[196:199], v160, s[18:19] offset:16
	global_load_dwordx4 v[200:203], v160, s[18:19] offset:1024
	global_load_dwordx4 v[144:147], v160, s[18:19] offset:1072
	global_load_dwordx4 v[140:143], v160, s[18:19] offset:1040
	global_load_dwordx4 v[128:131], v160, s[18:19] offset:2064
	global_load_dwordx4 v[204:207], v160, s[18:19] offset:2048
	global_load_dwordx4 v[132:135], v160, s[18:19] offset:2096
	global_load_dwordx4 v[208:211], v160, s[18:19] offset:2080
	ds_swizzle_b32 v212, v124 offset:swizzle(SWAP,16)
	ds_swizzle_b32 v213, v125 offset:swizzle(SWAP,16)
	ds_swizzle_b32 v214, v126 offset:swizzle(SWAP,16)
	ds_swizzle_b32 v215, v127 offset:swizzle(SWAP,16)
	ds_swizzle_b32 v220, v116 offset:swizzle(SWAP,16)
	ds_swizzle_b32 v221, v117 offset:swizzle(SWAP,16)
	ds_swizzle_b32 v222, v118 offset:swizzle(SWAP,16)
	ds_swizzle_b32 v223, v119 offset:swizzle(SWAP,16)
	ds_swizzle_b32 v216, v120 offset:swizzle(SWAP,16)
	ds_swizzle_b32 v217, v121 offset:swizzle(SWAP,16)
	ds_swizzle_b32 v218, v122 offset:swizzle(SWAP,16)
	ds_swizzle_b32 v219, v123 offset:swizzle(SWAP,16)
	ds_swizzle_b32 v224, v112 offset:swizzle(SWAP,16)
	ds_swizzle_b32 v225, v113 offset:swizzle(SWAP,16)
	ds_swizzle_b32 v226, v114 offset:swizzle(SWAP,16)
	ds_swizzle_b32 v227, v115 offset:swizzle(SWAP,16)
	ds_swizzle_b32 v232, v104 offset:swizzle(SWAP,16)
	ds_swizzle_b32 v233, v105 offset:swizzle(SWAP,16)
	ds_swizzle_b32 v234, v106 offset:swizzle(SWAP,16)
	ds_swizzle_b32 v235, v107 offset:swizzle(SWAP,16)
	ds_swizzle_b32 v228, v108 offset:swizzle(SWAP,16)
	ds_swizzle_b32 v229, v109 offset:swizzle(SWAP,16)
	ds_swizzle_b32 v230, v110 offset:swizzle(SWAP,16)
	ds_swizzle_b32 v231, v111 offset:swizzle(SWAP,16)
	s_waitcnt vmcnt(0) lgkmcnt(0)
	v_pk_mul_f32 v[214:215], v[150:151], v[214:215]
	v_pk_mul_f32 v[212:213], v[148:149], v[212:213]
	v_pk_mul_f32 v[150:151], v[150:151], v[222:223]
	v_pk_mul_f32 v[148:149], v[148:149], v[220:221]
	v_pk_mul_f32 v[150:151], v[164:165], v[150:151]
	v_pk_mul_f32 v[148:149], v[162:163], v[148:149]
	v_pk_mul_f32 v[218:219], v[138:139], v[218:219]
	v_pk_mul_f32 v[216:217], v[136:137], v[216:217]
	v_pk_mul_f32 v[138:139], v[138:139], v[226:227]
	v_pk_mul_f32 v[136:137], v[136:137], v[224:225]
	v_pk_fma_f32 v[150:151], v[118:119], v[194:195], v[150:151]
	v_pk_fma_f32 v[148:149], v[116:117], v[192:193], v[148:149]
	v_pk_mul_f32 v[136:137], v[162:163], v[136:137]
	v_pk_mul_f32 v[138:139], v[164:165], v[138:139]
	v_cndmask_b32_e64 v119, v119, v151, s[4:5]
	v_cndmask_b32_e64 v118, v118, v150, s[4:5]
	v_cndmask_b32_e64 v117, v117, v149, s[4:5]
	v_cndmask_b32_e64 v116, v116, v148, s[4:5]
	ds_swizzle_b32 v148, v100 offset:swizzle(SWAP,16)
	ds_swizzle_b32 v150, v102 offset:swizzle(SWAP,16)
	ds_swizzle_b32 v151, v103 offset:swizzle(SWAP,16)
	ds_swizzle_b32 v149, v101 offset:swizzle(SWAP,16)
	v_pk_fma_f32 v[138:139], v[114:115], v[198:199], v[138:139]
	v_pk_fma_f32 v[136:137], v[112:113], v[196:197], v[136:137]
	v_cndmask_b32_e64 v115, v115, v139, s[4:5]
	v_cndmask_b32_e64 v114, v114, v138, s[4:5]
	v_cndmask_b32_e64 v113, v113, v137, s[4:5]
	v_cndmask_b32_e64 v112, v112, v136, s[4:5]
	v_pk_mul_f32 v[136:137], v[146:147], v[234:235]
	v_pk_mul_f32 v[138:139], v[144:145], v[232:233]
	v_pk_mul_f32 v[136:137], v[164:165], v[136:137]
	v_pk_mul_f32 v[138:139], v[162:163], v[138:139]
	v_pk_fma_f32 v[136:137], v[106:107], v[142:143], v[136:137]
	v_pk_fma_f32 v[138:139], v[104:105], v[140:141], v[138:139]
	v_cndmask_b32_e64 v107, v107, v137, s[4:5]
	v_cndmask_b32_e64 v106, v106, v136, s[4:5]
	v_cndmask_b32_e64 v105, v105, v139, s[4:5]
	v_cndmask_b32_e64 v104, v104, v138, s[4:5]
	s_waitcnt lgkmcnt(1)
	v_pk_mul_f32 v[136:137], v[190:191], v[150:151]
	s_waitcnt lgkmcnt(0)
	v_pk_mul_f32 v[138:139], v[188:189], v[148:149]
	v_pk_mul_f32 v[136:137], v[164:165], v[136:137]
	v_pk_mul_f32 v[138:139], v[162:163], v[138:139]
	v_pk_fma_f32 v[136:137], v[102:103], v[202:203], v[136:137]
	v_pk_fma_f32 v[138:139], v[100:101], v[200:201], v[138:139]
	ds_swizzle_b32 v148, v96 offset:swizzle(SWAP,16)
	ds_swizzle_b32 v150, v98 offset:swizzle(SWAP,16)
	ds_swizzle_b32 v151, v99 offset:swizzle(SWAP,16)
	ds_swizzle_b32 v149, v97 offset:swizzle(SWAP,16)
	v_pk_mul_f32 v[220:221], v[190:191], v[230:231]
	v_pk_mul_f32 v[222:223], v[188:189], v[228:229]
	v_cndmask_b32_e64 v103, v103, v137, s[4:5]
	v_cndmask_b32_e64 v102, v102, v136, s[4:5]
	v_cndmask_b32_e64 v101, v101, v139, s[4:5]
	v_cndmask_b32_e64 v100, v100, v138, s[4:5]
	global_load_dwordx4 v[136:139], v160, s[18:19] offset:3120
	global_load_dwordx4 v[188:191], v160, s[18:19] offset:3104
	v_pk_mul_f32 v[212:213], v[162:163], v[212:213]
	v_pk_mul_f32 v[214:215], v[164:165], v[214:215]
	v_pk_mul_f32 v[222:223], v[162:163], v[222:223]
	v_pk_mul_f32 v[220:221], v[164:165], v[220:221]
	v_pk_fma_f32 v[214:215], v[126:127], v[194:195], v[214:215]
	v_pk_fma_f32 v[212:213], v[124:125], v[192:193], v[212:213]
	v_pk_fma_f32 v[192:193], v[110:111], v[202:203], v[220:221]
	v_pk_fma_f32 v[194:195], v[108:109], v[200:201], v[222:223]
	v_cndmask_b32_e64 v111, v111, v193, s[4:5]
	v_cndmask_b32_e64 v110, v110, v192, s[4:5]
	v_cndmask_b32_e64 v109, v109, v195, s[4:5]
	v_cndmask_b32_e64 v108, v108, v194, s[4:5]
	s_waitcnt lgkmcnt(1)
	v_pk_mul_f32 v[150:151], v[146:147], v[150:151]
	s_waitcnt lgkmcnt(0)
	v_pk_mul_f32 v[148:149], v[144:145], v[148:149]
	global_load_dwordx4 v[144:147], v160, s[18:19] offset:3088
	global_load_dwordx4 v[192:195], v160, s[18:19] offset:3072
	v_pk_mul_f32 v[150:151], v[164:165], v[150:151]
	v_pk_mul_f32 v[148:149], v[162:163], v[148:149]
	v_pk_fma_f32 v[142:143], v[98:99], v[142:143], v[150:151]
	ds_swizzle_b32 v150, v94 offset:swizzle(SWAP,16)
	ds_swizzle_b32 v151, v95 offset:swizzle(SWAP,16)
	v_pk_fma_f32 v[140:141], v[96:97], v[140:141], v[148:149]
	ds_swizzle_b32 v148, v92 offset:swizzle(SWAP,16)
	ds_swizzle_b32 v149, v93 offset:swizzle(SWAP,16)
	v_cndmask_b32_e64 v97, v97, v141, s[4:5]
	v_cndmask_b32_e64 v96, v96, v140, s[4:5]
	s_waitcnt lgkmcnt(2)
	v_pk_mul_f32 v[140:141], v[210:211], v[150:151]
	ds_swizzle_b32 v150, v90 offset:swizzle(SWAP,16)
	ds_swizzle_b32 v151, v91 offset:swizzle(SWAP,16)
	v_cndmask_b32_e64 v99, v99, v143, s[4:5]
	v_cndmask_b32_e64 v98, v98, v142, s[4:5]
	s_waitcnt lgkmcnt(2)
	v_pk_mul_f32 v[142:143], v[208:209], v[148:149]
	ds_swizzle_b32 v148, v88 offset:swizzle(SWAP,16)
	ds_swizzle_b32 v149, v89 offset:swizzle(SWAP,16)
	v_pk_mul_f32 v[140:141], v[164:165], v[140:141]
	v_pk_mul_f32 v[142:143], v[162:163], v[142:143]
	v_pk_fma_f32 v[140:141], v[94:95], v[206:207], v[140:141]
	v_pk_fma_f32 v[142:143], v[92:93], v[204:205], v[142:143]
	v_cndmask_b32_e64 v95, v95, v141, s[4:5]
	v_cndmask_b32_e64 v94, v94, v140, s[4:5]
	s_waitcnt lgkmcnt(2)
	v_pk_mul_f32 v[140:141], v[134:135], v[150:151]
	ds_swizzle_b32 v150, v86 offset:swizzle(SWAP,16)
	ds_swizzle_b32 v151, v87 offset:swizzle(SWAP,16)
	v_cndmask_b32_e64 v93, v93, v143, s[4:5]
	v_cndmask_b32_e64 v92, v92, v142, s[4:5]
	s_waitcnt lgkmcnt(2)
	v_pk_mul_f32 v[142:143], v[132:133], v[148:149]
	ds_swizzle_b32 v148, v84 offset:swizzle(SWAP,16)
	ds_swizzle_b32 v149, v85 offset:swizzle(SWAP,16)
	v_pk_mul_f32 v[140:141], v[164:165], v[140:141]
	v_pk_mul_f32 v[142:143], v[162:163], v[142:143]
	v_pk_fma_f32 v[140:141], v[90:91], v[130:131], v[140:141]
	v_pk_fma_f32 v[142:143], v[88:89], v[128:129], v[142:143]
	v_cndmask_b32_e64 v91, v91, v141, s[4:5]
	v_cndmask_b32_e64 v90, v90, v140, s[4:5]
	s_waitcnt lgkmcnt(2)
	v_pk_mul_f32 v[140:141], v[210:211], v[150:151]
	v_cndmask_b32_e64 v89, v89, v143, s[4:5]
	v_pk_mul_f32 v[140:141], v[164:165], v[140:141]
	v_cndmask_b32_e64 v88, v88, v142, s[4:5]
	s_waitcnt lgkmcnt(0)
	v_pk_mul_f32 v[142:143], v[208:209], v[148:149]
	v_pk_fma_f32 v[140:141], v[86:87], v[206:207], v[140:141]
	ds_swizzle_b32 v208, v82 offset:swizzle(SWAP,16)
	ds_swizzle_b32 v209, v83 offset:swizzle(SWAP,16)
	v_cndmask_b32_e64 v86, v86, v140, s[4:5]
	ds_swizzle_b32 v206, v80 offset:swizzle(SWAP,16)
	v_lshl_add_u32 v140, v187, 4, v186
	ds_swizzle_b32 v207, v81 offset:swizzle(SWAP,16)
	v_and_b32_e32 v140, 0x1fcf0, v140
	v_pk_mul_f32 v[216:217], v[162:163], v[216:217]
	v_pk_mul_f32 v[218:219], v[164:165], v[218:219]
	v_pk_mul_f32 v[142:143], v[162:163], v[142:143]
	v_lshlrev_b32_e32 v160, 2, v140
	v_pk_fma_f32 v[218:219], v[122:123], v[198:199], v[218:219]
	v_pk_fma_f32 v[216:217], v[120:121], v[196:197], v[216:217]
	v_pk_fma_f32 v[204:205], v[84:85], v[204:205], v[142:143]
	v_cndmask_b32_e64 v87, v87, v141, s[4:5]
	global_load_dwordx4 v[140:143], v160, s[18:19] offset:48
	global_load_dwordx4 v[196:199], v160, s[18:19] offset:32
	s_waitcnt lgkmcnt(2)
	v_pk_mul_f32 v[134:135], v[134:135], v[208:209]
	s_waitcnt lgkmcnt(0)
	v_pk_mul_f32 v[132:133], v[132:133], v[206:207]
	v_pk_mul_f32 v[134:135], v[164:165], v[134:135]
	v_pk_mul_f32 v[132:133], v[162:163], v[132:133]
	v_pk_fma_f32 v[130:131], v[82:83], v[130:131], v[134:135]
	ds_swizzle_b32 v134, v78 offset:swizzle(SWAP,16)
	ds_swizzle_b32 v135, v79 offset:swizzle(SWAP,16)
	global_load_dwordx4 v[148:151], v160, s[18:19] offset:16
	global_load_dwordx4 v[200:203], v160, s[18:19]
	v_pk_fma_f32 v[128:129], v[80:81], v[128:129], v[132:133]
	ds_swizzle_b32 v132, v76 offset:swizzle(SWAP,16)
	ds_swizzle_b32 v133, v77 offset:swizzle(SWAP,16)
	v_cndmask_b32_e64 v81, v81, v129, s[4:5]
	v_cndmask_b32_e64 v80, v80, v128, s[4:5]
	s_waitcnt vmcnt(6) lgkmcnt(2)
	v_pk_mul_f32 v[128:129], v[190:191], v[134:135]
	ds_swizzle_b32 v134, v74 offset:swizzle(SWAP,16)
	ds_swizzle_b32 v135, v75 offset:swizzle(SWAP,16)
	v_cndmask_b32_e64 v83, v83, v131, s[4:5]
	v_cndmask_b32_e64 v82, v82, v130, s[4:5]
	s_waitcnt lgkmcnt(2)
	v_pk_mul_f32 v[130:131], v[188:189], v[132:133]
	ds_swizzle_b32 v132, v72 offset:swizzle(SWAP,16)
	ds_swizzle_b32 v133, v73 offset:swizzle(SWAP,16)
	v_pk_mul_f32 v[128:129], v[164:165], v[128:129]
	v_pk_mul_f32 v[130:131], v[162:163], v[130:131]
	s_waitcnt vmcnt(4)
	v_pk_fma_f32 v[128:129], v[78:79], v[194:195], v[128:129]
	v_pk_fma_f32 v[130:131], v[76:77], v[192:193], v[130:131]
	v_cndmask_b32_e64 v79, v79, v129, s[4:5]
	v_cndmask_b32_e64 v78, v78, v128, s[4:5]
	s_waitcnt lgkmcnt(2)
	v_pk_mul_f32 v[128:129], v[138:139], v[134:135]
	ds_swizzle_b32 v134, v70 offset:swizzle(SWAP,16)
	ds_swizzle_b32 v135, v71 offset:swizzle(SWAP,16)
	v_cndmask_b32_e64 v77, v77, v131, s[4:5]
	v_cndmask_b32_e64 v76, v76, v130, s[4:5]
	s_waitcnt lgkmcnt(2)
	v_pk_mul_f32 v[130:131], v[136:137], v[132:133]
	ds_swizzle_b32 v132, v68 offset:swizzle(SWAP,16)
	ds_swizzle_b32 v133, v69 offset:swizzle(SWAP,16)
	v_pk_mul_f32 v[128:129], v[164:165], v[128:129]
	v_pk_mul_f32 v[130:131], v[162:163], v[130:131]
	v_pk_fma_f32 v[128:129], v[74:75], v[146:147], v[128:129]
	v_pk_fma_f32 v[130:131], v[72:73], v[144:145], v[130:131]
	v_cndmask_b32_e64 v75, v75, v129, s[4:5]
	v_cndmask_b32_e64 v74, v74, v128, s[4:5]
	s_waitcnt lgkmcnt(2)
	v_pk_mul_f32 v[128:129], v[190:191], v[134:135]
	v_cndmask_b32_e64 v73, v73, v131, s[4:5]
	v_cndmask_b32_e64 v72, v72, v130, s[4:5]
	s_waitcnt lgkmcnt(0)
	v_pk_mul_f32 v[130:131], v[188:189], v[132:133]
	v_pk_mul_f32 v[128:129], v[164:165], v[128:129]
	v_pk_mul_f32 v[130:131], v[162:163], v[130:131]
	v_pk_fma_f32 v[128:129], v[70:71], v[194:195], v[128:129]
	v_cndmask_b32_e64 v85, v85, v205, s[4:5]
	v_cndmask_b32_e64 v84, v84, v204, s[4:5]
	v_pk_fma_f32 v[204:205], v[68:69], v[192:193], v[130:131]
	v_cndmask_b32_e64 v71, v71, v129, s[4:5]
	v_cndmask_b32_e64 v70, v70, v128, s[4:5]
	global_load_dwordx4 v[128:131], v160, s[18:19] offset:1072
	global_load_dwordx4 v[188:191], v160, s[18:19] offset:1056
	global_load_dwordx4 v[132:135], v160, s[18:19] offset:1040
	global_load_dwordx4 v[192:195], v160, s[18:19] offset:1024
	ds_swizzle_b32 v208, v66 offset:swizzle(SWAP,16)
	ds_swizzle_b32 v209, v67 offset:swizzle(SWAP,16)
	ds_swizzle_b32 v206, v64 offset:swizzle(SWAP,16)
	ds_swizzle_b32 v207, v65 offset:swizzle(SWAP,16)
	v_cndmask_b32_e64 v69, v69, v205, s[4:5]
	v_cndmask_b32_e64 v68, v68, v204, s[4:5]
	s_waitcnt lgkmcnt(2)
	v_pk_mul_f32 v[138:139], v[138:139], v[208:209]
	ds_swizzle_b32 v208, v50 offset:swizzle(SWAP,16)
	s_waitcnt lgkmcnt(1)
	v_pk_mul_f32 v[136:137], v[136:137], v[206:207]
	v_pk_mul_f32 v[138:139], v[164:165], v[138:139]
	v_pk_mul_f32 v[136:137], v[162:163], v[136:137]
	v_pk_fma_f32 v[138:139], v[66:67], v[146:147], v[138:139]
	ds_swizzle_b32 v146, v62 offset:swizzle(SWAP,16)
	ds_swizzle_b32 v147, v63 offset:swizzle(SWAP,16)
	v_pk_fma_f32 v[136:137], v[64:65], v[144:145], v[136:137]
	ds_swizzle_b32 v144, v60 offset:swizzle(SWAP,16)
	ds_swizzle_b32 v145, v61 offset:swizzle(SWAP,16)
	v_cndmask_b32_e64 v65, v65, v137, s[4:5]
	v_cndmask_b32_e64 v64, v64, v136, s[4:5]
	v_cndmask_b32_e64 v67, v67, v139, s[4:5]
	v_cndmask_b32_e64 v66, v66, v138, s[4:5]
	ds_swizzle_b32 v206, v48 offset:swizzle(SWAP,16)
	ds_swizzle_b32 v209, v51 offset:swizzle(SWAP,16)
	ds_swizzle_b32 v207, v49 offset:swizzle(SWAP,16)
	s_waitcnt vmcnt(6) lgkmcnt(5)
	v_pk_mul_f32 v[136:137], v[198:199], v[146:147]
	ds_swizzle_b32 v146, v58 offset:swizzle(SWAP,16)
	ds_swizzle_b32 v147, v59 offset:swizzle(SWAP,16)
	s_waitcnt lgkmcnt(5)
	v_pk_mul_f32 v[138:139], v[196:197], v[144:145]
	ds_swizzle_b32 v144, v56 offset:swizzle(SWAP,16)
	ds_swizzle_b32 v145, v57 offset:swizzle(SWAP,16)
	v_pk_mul_f32 v[136:137], v[164:165], v[136:137]
	v_pk_mul_f32 v[138:139], v[162:163], v[138:139]
	s_waitcnt vmcnt(4)
	v_pk_fma_f32 v[136:137], v[62:63], v[202:203], v[136:137]
	v_pk_fma_f32 v[138:139], v[60:61], v[200:201], v[138:139]
	v_cndmask_b32_e64 v63, v63, v137, s[4:5]
	v_cndmask_b32_e64 v62, v62, v136, s[4:5]
	s_waitcnt lgkmcnt(2)
	v_pk_mul_f32 v[136:137], v[142:143], v[146:147]
	ds_swizzle_b32 v146, v54 offset:swizzle(SWAP,16)
	ds_swizzle_b32 v147, v55 offset:swizzle(SWAP,16)
	v_cndmask_b32_e64 v61, v61, v139, s[4:5]
	v_cndmask_b32_e64 v60, v60, v138, s[4:5]
	s_waitcnt lgkmcnt(2)
	v_pk_mul_f32 v[138:139], v[140:141], v[144:145]
	ds_swizzle_b32 v144, v52 offset:swizzle(SWAP,16)
	ds_swizzle_b32 v145, v53 offset:swizzle(SWAP,16)
	v_pk_mul_f32 v[136:137], v[164:165], v[136:137]
	v_pk_mul_f32 v[138:139], v[162:163], v[138:139]
	v_pk_fma_f32 v[136:137], v[58:59], v[150:151], v[136:137]
	v_pk_fma_f32 v[138:139], v[56:57], v[148:149], v[138:139]
	v_cndmask_b32_e64 v59, v59, v137, s[4:5]
	v_cndmask_b32_e64 v58, v58, v136, s[4:5]
	s_waitcnt lgkmcnt(2)
	v_pk_mul_f32 v[136:137], v[198:199], v[146:147]
	v_cndmask_b32_e64 v57, v57, v139, s[4:5]
	v_cndmask_b32_e64 v56, v56, v138, s[4:5]
	s_waitcnt lgkmcnt(0)
	v_pk_mul_f32 v[138:139], v[196:197], v[144:145]
	v_pk_mul_f32 v[136:137], v[164:165], v[136:137]
	v_pk_mul_f32 v[138:139], v[162:163], v[138:139]
	v_pk_fma_f32 v[136:137], v[54:55], v[202:203], v[136:137]
	v_pk_fma_f32 v[204:205], v[52:53], v[200:201], v[138:139]
	v_cndmask_b32_e64 v55, v55, v137, s[4:5]
	v_cndmask_b32_e64 v54, v54, v136, s[4:5]
	global_load_dwordx4 v[136:139], v160, s[18:19] offset:2096
	global_load_dwordx4 v[144:147], v160, s[18:19] offset:2080
	v_pk_mul_f32 v[142:143], v[142:143], v[208:209]
	v_pk_mul_f32 v[140:141], v[140:141], v[206:207]
	v_pk_mul_f32 v[142:143], v[164:165], v[142:143]
	v_pk_mul_f32 v[140:141], v[162:163], v[140:141]
	v_pk_fma_f32 v[142:143], v[50:51], v[150:151], v[142:143]
	v_pk_fma_f32 v[140:141], v[48:49], v[148:149], v[140:141]
	ds_swizzle_b32 v148, v44 offset:swizzle(SWAP,16)
	ds_swizzle_b32 v150, v46 offset:swizzle(SWAP,16)
	ds_swizzle_b32 v151, v47 offset:swizzle(SWAP,16)
	ds_swizzle_b32 v149, v45 offset:swizzle(SWAP,16)
	global_load_dwordx4 v[196:199], v160, s[18:19] offset:2064
	global_load_dwordx4 v[200:203], v160, s[18:19] offset:2048
	v_cndmask_b32_e64 v51, v51, v143, s[4:5]
	v_cndmask_b32_e64 v50, v50, v142, s[4:5]
	v_cndmask_b32_e64 v49, v49, v141, s[4:5]
	v_cndmask_b32_e64 v48, v48, v140, s[4:5]
	v_cndmask_b32_e64 v53, v53, v205, s[4:5]
	v_cndmask_b32_e64 v52, v52, v204, s[4:5]
	s_waitcnt vmcnt(6) lgkmcnt(1)
	v_pk_mul_f32 v[140:141], v[190:191], v[150:151]
	s_waitcnt lgkmcnt(0)
	v_pk_mul_f32 v[142:143], v[188:189], v[148:149]
	ds_swizzle_b32 v148, v40 offset:swizzle(SWAP,16)
	ds_swizzle_b32 v150, v42 offset:swizzle(SWAP,16)
	ds_swizzle_b32 v151, v43 offset:swizzle(SWAP,16)
	ds_swizzle_b32 v149, v41 offset:swizzle(SWAP,16)
	v_pk_mul_f32 v[140:141], v[164:165], v[140:141]
	v_pk_mul_f32 v[142:143], v[162:163], v[142:143]
	s_waitcnt vmcnt(4)
	v_pk_fma_f32 v[140:141], v[46:47], v[194:195], v[140:141]
	v_pk_fma_f32 v[142:143], v[44:45], v[192:193], v[142:143]
	v_cndmask_b32_e64 v47, v47, v141, s[4:5]
	v_cndmask_b32_e64 v46, v46, v140, s[4:5]
	v_cndmask_b32_e64 v45, v45, v143, s[4:5]
	v_cndmask_b32_e64 v44, v44, v142, s[4:5]
	s_waitcnt lgkmcnt(1)
	v_pk_mul_f32 v[140:141], v[130:131], v[150:151]
	s_waitcnt lgkmcnt(0)
	v_pk_mul_f32 v[142:143], v[128:129], v[148:149]
	ds_swizzle_b32 v148, v36 offset:swizzle(SWAP,16)
	ds_swizzle_b32 v150, v38 offset:swizzle(SWAP,16)
	ds_swizzle_b32 v151, v39 offset:swizzle(SWAP,16)
	ds_swizzle_b32 v149, v37 offset:swizzle(SWAP,16)
	v_pk_mul_f32 v[140:141], v[164:165], v[140:141]
	v_pk_mul_f32 v[142:143], v[162:163], v[142:143]
	v_pk_fma_f32 v[140:141], v[42:43], v[134:135], v[140:141]
	v_pk_fma_f32 v[142:143], v[40:41], v[132:133], v[142:143]
	v_cndmask_b32_e64 v43, v43, v141, s[4:5]
	v_cndmask_b32_e64 v42, v42, v140, s[4:5]
	v_cndmask_b32_e64 v41, v41, v143, s[4:5]
	v_cndmask_b32_e64 v40, v40, v142, s[4:5]
	s_waitcnt lgkmcnt(1)
	v_pk_mul_f32 v[140:141], v[190:191], v[150:151]
	s_waitcnt lgkmcnt(0)
	v_pk_mul_f32 v[142:143], v[188:189], v[148:149]
	v_pk_mul_f32 v[140:141], v[164:165], v[140:141]
	v_pk_mul_f32 v[142:143], v[162:163], v[142:143]
	v_pk_fma_f32 v[204:205], v[38:39], v[194:195], v[140:141]
	v_pk_fma_f32 v[206:207], v[36:37], v[192:193], v[142:143]
	global_load_dwordx4 v[140:143], v160, s[18:19] offset:3120
	global_load_dwordx4 v[148:151], v160, s[18:19] offset:3104
	global_load_dwordx4 v[188:191], v160, s[18:19] offset:3088
	global_load_dwordx4 v[192:195], v160, s[18:19] offset:3072
	ds_swizzle_b32 v208, v32 offset:swizzle(SWAP,16)
	ds_swizzle_b32 v210, v34 offset:swizzle(SWAP,16)
	ds_swizzle_b32 v211, v35 offset:swizzle(SWAP,16)
	ds_swizzle_b32 v209, v33 offset:swizzle(SWAP,16)
	v_cndmask_b32_e64 v127, v127, v215, s[4:5]
	v_cndmask_b32_e64 v126, v126, v214, s[4:5]
	v_cndmask_b32_e64 v125, v125, v213, s[4:5]
	s_waitcnt lgkmcnt(1)
	v_pk_mul_f32 v[130:131], v[130:131], v[210:211]
	s_waitcnt lgkmcnt(0)
	v_pk_mul_f32 v[128:129], v[128:129], v[208:209]
	v_pk_mul_f32 v[130:131], v[164:165], v[130:131]
	v_pk_mul_f32 v[128:129], v[162:163], v[128:129]
	v_pk_fma_f32 v[130:131], v[34:35], v[134:135], v[130:131]
	v_pk_fma_f32 v[128:129], v[32:33], v[132:133], v[128:129]
	ds_swizzle_b32 v132, v28 offset:swizzle(SWAP,16)
	ds_swizzle_b32 v134, v30 offset:swizzle(SWAP,16)
	ds_swizzle_b32 v135, v31 offset:swizzle(SWAP,16)
	ds_swizzle_b32 v133, v29 offset:swizzle(SWAP,16)
	v_cndmask_b32_e64 v35, v35, v131, s[4:5]
	v_cndmask_b32_e64 v34, v34, v130, s[4:5]
	v_cndmask_b32_e64 v33, v33, v129, s[4:5]
	v_cndmask_b32_e64 v32, v32, v128, s[4:5]
	v_cndmask_b32_e64 v124, v124, v212, s[4:5]
	v_cndmask_b32_e64 v123, v123, v219, s[4:5]
	v_cndmask_b32_e64 v122, v122, v218, s[4:5]
	v_cndmask_b32_e64 v121, v121, v217, s[4:5]
	v_cndmask_b32_e64 v120, v120, v216, s[4:5]
	s_waitcnt vmcnt(6) lgkmcnt(1)
	v_pk_mul_f32 v[128:129], v[146:147], v[134:135]
	s_waitcnt lgkmcnt(0)
	v_pk_mul_f32 v[130:131], v[144:145], v[132:133]
	ds_swizzle_b32 v132, v24 offset:swizzle(SWAP,16)
	ds_swizzle_b32 v134, v26 offset:swizzle(SWAP,16)
	ds_swizzle_b32 v135, v27 offset:swizzle(SWAP,16)
	ds_swizzle_b32 v133, v25 offset:swizzle(SWAP,16)
	v_pk_mul_f32 v[128:129], v[164:165], v[128:129]
	v_pk_mul_f32 v[130:131], v[162:163], v[130:131]
	v_cndmask_b32_e64 v39, v39, v205, s[4:5]
	v_cndmask_b32_e64 v38, v38, v204, s[4:5]
	v_cndmask_b32_e64 v37, v37, v207, s[4:5]
	s_waitcnt vmcnt(4)
	v_pk_fma_f32 v[128:129], v[30:31], v[202:203], v[128:129]
	v_pk_fma_f32 v[130:131], v[28:29], v[200:201], v[130:131]
	v_cndmask_b32_e64 v31, v31, v129, s[4:5]
	v_cndmask_b32_e64 v30, v30, v128, s[4:5]
	v_cndmask_b32_e64 v29, v29, v131, s[4:5]
	v_cndmask_b32_e64 v28, v28, v130, s[4:5]
	s_waitcnt lgkmcnt(1)
	v_pk_mul_f32 v[128:129], v[138:139], v[134:135]
	s_waitcnt lgkmcnt(0)
	v_pk_mul_f32 v[130:131], v[136:137], v[132:133]
	ds_swizzle_b32 v132, v20 offset:swizzle(SWAP,16)
	ds_swizzle_b32 v134, v22 offset:swizzle(SWAP,16)
	ds_swizzle_b32 v135, v23 offset:swizzle(SWAP,16)
	ds_swizzle_b32 v133, v21 offset:swizzle(SWAP,16)
	v_pk_mul_f32 v[128:129], v[164:165], v[128:129]
	v_pk_mul_f32 v[130:131], v[162:163], v[130:131]
	v_pk_fma_f32 v[128:129], v[26:27], v[198:199], v[128:129]
	v_pk_fma_f32 v[130:131], v[24:25], v[196:197], v[130:131]
	v_cndmask_b32_e64 v27, v27, v129, s[4:5]
	v_cndmask_b32_e64 v26, v26, v128, s[4:5]
	v_cndmask_b32_e64 v25, v25, v131, s[4:5]
	v_cndmask_b32_e64 v24, v24, v130, s[4:5]
	s_waitcnt lgkmcnt(1)
	v_pk_mul_f32 v[128:129], v[146:147], v[134:135]
	s_waitcnt lgkmcnt(0)
	v_pk_mul_f32 v[130:131], v[144:145], v[132:133]
	ds_swizzle_b32 v132, v16 offset:swizzle(SWAP,16)
	ds_swizzle_b32 v134, v18 offset:swizzle(SWAP,16)
	ds_swizzle_b32 v135, v19 offset:swizzle(SWAP,16)
	ds_swizzle_b32 v133, v17 offset:swizzle(SWAP,16)
	v_pk_mul_f32 v[128:129], v[164:165], v[128:129]
	v_pk_mul_f32 v[130:131], v[162:163], v[130:131]
	v_pk_fma_f32 v[128:129], v[22:23], v[202:203], v[128:129]
	v_pk_fma_f32 v[130:131], v[20:21], v[200:201], v[130:131]
	v_cndmask_b32_e64 v23, v23, v129, s[4:5]
	v_cndmask_b32_e64 v22, v22, v128, s[4:5]
	v_cndmask_b32_e64 v21, v21, v131, s[4:5]
	v_cndmask_b32_e64 v20, v20, v130, s[4:5]
	s_waitcnt lgkmcnt(1)
	v_pk_mul_f32 v[128:129], v[138:139], v[134:135]
	s_waitcnt lgkmcnt(0)
	v_pk_mul_f32 v[130:131], v[136:137], v[132:133]
	ds_swizzle_b32 v132, v12 offset:swizzle(SWAP,16)
	ds_swizzle_b32 v134, v14 offset:swizzle(SWAP,16)
	ds_swizzle_b32 v135, v15 offset:swizzle(SWAP,16)
	ds_swizzle_b32 v133, v13 offset:swizzle(SWAP,16)
	v_pk_mul_f32 v[128:129], v[164:165], v[128:129]
	v_pk_mul_f32 v[130:131], v[162:163], v[130:131]
	v_pk_fma_f32 v[128:129], v[18:19], v[198:199], v[128:129]
	v_pk_fma_f32 v[130:131], v[16:17], v[196:197], v[130:131]
	v_cndmask_b32_e64 v19, v19, v129, s[4:5]
	v_cndmask_b32_e64 v18, v18, v128, s[4:5]
	v_cndmask_b32_e64 v17, v17, v131, s[4:5]
	v_cndmask_b32_e64 v16, v16, v130, s[4:5]
	s_waitcnt vmcnt(2) lgkmcnt(1)
	v_pk_mul_f32 v[128:129], v[150:151], v[134:135]
	s_waitcnt lgkmcnt(0)
	v_pk_mul_f32 v[130:131], v[148:149], v[132:133]
	ds_swizzle_b32 v132, v8 offset:swizzle(SWAP,16)
	ds_swizzle_b32 v134, v10 offset:swizzle(SWAP,16)
	ds_swizzle_b32 v135, v11 offset:swizzle(SWAP,16)
	ds_swizzle_b32 v133, v9 offset:swizzle(SWAP,16)
	v_pk_mul_f32 v[128:129], v[164:165], v[128:129]
	v_pk_mul_f32 v[130:131], v[162:163], v[130:131]
	s_waitcnt vmcnt(0)
	v_pk_fma_f32 v[128:129], v[14:15], v[194:195], v[128:129]
	v_pk_fma_f32 v[130:131], v[12:13], v[192:193], v[130:131]
	v_cndmask_b32_e64 v15, v15, v129, s[4:5]
	v_cndmask_b32_e64 v14, v14, v128, s[4:5]
	v_cndmask_b32_e64 v13, v13, v131, s[4:5]
	v_cndmask_b32_e64 v12, v12, v130, s[4:5]
	s_waitcnt lgkmcnt(1)
	v_pk_mul_f32 v[128:129], v[142:143], v[134:135]
	s_waitcnt lgkmcnt(0)
	v_pk_mul_f32 v[130:131], v[140:141], v[132:133]
	ds_swizzle_b32 v132, v4 offset:swizzle(SWAP,16)
	ds_swizzle_b32 v134, v6 offset:swizzle(SWAP,16)
	ds_swizzle_b32 v135, v7 offset:swizzle(SWAP,16)
	ds_swizzle_b32 v133, v5 offset:swizzle(SWAP,16)
	v_pk_mul_f32 v[128:129], v[164:165], v[128:129]
	v_pk_mul_f32 v[130:131], v[162:163], v[130:131]
	v_pk_fma_f32 v[128:129], v[10:11], v[190:191], v[128:129]
	v_pk_fma_f32 v[130:131], v[8:9], v[188:189], v[130:131]
	v_cndmask_b32_e64 v11, v11, v129, s[4:5]
	v_cndmask_b32_e64 v10, v10, v128, s[4:5]
	v_cndmask_b32_e64 v9, v9, v131, s[4:5]
	v_cndmask_b32_e64 v8, v8, v130, s[4:5]
	s_waitcnt lgkmcnt(1)
	v_pk_mul_f32 v[128:129], v[150:151], v[134:135]
	s_waitcnt lgkmcnt(0)
	v_pk_mul_f32 v[130:131], v[148:149], v[132:133]
	ds_swizzle_b32 v132, v0 offset:swizzle(SWAP,16)
	ds_swizzle_b32 v134, v2 offset:swizzle(SWAP,16)
	ds_swizzle_b32 v135, v3 offset:swizzle(SWAP,16)
	ds_swizzle_b32 v133, v1 offset:swizzle(SWAP,16)
	v_pk_mul_f32 v[128:129], v[164:165], v[128:129]
	v_pk_mul_f32 v[130:131], v[162:163], v[130:131]
	v_pk_fma_f32 v[128:129], v[6:7], v[194:195], v[128:129]
	v_pk_fma_f32 v[130:131], v[4:5], v[192:193], v[130:131]
	v_cndmask_b32_e64 v7, v7, v129, s[4:5]
	v_cndmask_b32_e64 v6, v6, v128, s[4:5]
	v_cndmask_b32_e64 v5, v5, v131, s[4:5]
	v_cndmask_b32_e64 v4, v4, v130, s[4:5]
	s_waitcnt lgkmcnt(1)
	v_pk_mul_f32 v[128:129], v[142:143], v[134:135]
	s_waitcnt lgkmcnt(0)
	v_pk_mul_f32 v[130:131], v[140:141], v[132:133]
	v_pk_mul_f32 v[128:129], v[164:165], v[128:129]
	v_pk_mul_f32 v[130:131], v[162:163], v[130:131]
	v_pk_fma_f32 v[128:129], v[2:3], v[190:191], v[128:129]
	v_pk_fma_f32 v[130:131], v[0:1], v[188:189], v[130:131]
	v_cndmask_b32_e64 v36, v36, v206, s[4:5]
	v_cndmask_b32_e64 v3, v3, v129, s[4:5]
	v_cndmask_b32_e64 v2, v2, v128, s[4:5]
	v_cndmask_b32_e64 v1, v1, v131, s[4:5]
	v_cndmask_b32_e64 v0, v0, v130, s[4:5]
	s_and_b32 s31, s42, -2
	s_cmp_lg_u32 s31, 10
	s_cbranch_scc0 .LBB0_148
.LBB0_145:
	s_branch .LBB0_185
.LBB0_147:
	s_and_b32 s31, s42, -2
	s_cmp_lg_u32 s31, 10
	s_cbranch_scc1 .LBB0_145

.LBB0_185:
	s_waitcnt lgkmcnt(0)
	v_or_b32_e32 v130, s29, v181
	v_mov_b32_e32 v131, 0
	v_lshl_add_u64 v[130:131], v[130:131], 1, s[44:45]
	v_mad_i64_i32 v[132:133], s[100:101], s38, v187, 0
	v_lshl_add_u64 v[128:129], v[132:133], 1, v[130:131]
	s_lshl_b32 s94, s38, 5
	s_mov_b32 s95, 0
	s_mul_i32 s96, s38, 0xa0
	s_mov_b32 s97, 0
	v_readfirstlane_b32 s98, v176
	s_nop 1
	s_cmp_gt_i32 s12, 2
	s_cbranch_scc1 .Lp1st_sigmoid
	s_cmp_eq_u32 s12, 2
	s_cbranch_scc1 .Lp1st_silu
	s_cmp_eq_u32 s98, 1.0
	s_cbranch_scc1 .Lp1st_plain
	v_mul_f32_e32 v140, s98, v124
	v_mul_f32_e32 v141, s98, v125
	v_mul_f32_e32 v142, s98, v126
	v_mul_f32_e32 v143, s98, v127
	v_mul_f32_e32 v144, s98, v120
	v_mul_f32_e32 v145, s98, v121
	v_mul_f32_e32 v146, s98, v122
	v_mul_f32_e32 v147, s98, v123
	v_cvt_pk_bf16_f32 v132, v140, v141
	v_cvt_pk_bf16_f32 v133, v142, v143
	v_cvt_pk_bf16_f32 v134, v144, v145
	v_cvt_pk_bf16_f32 v135, v146, v147
	global_store_dwordx4 v[128:129], v[132:135], off sc1
	v_mul_f32_e32 v140, s98, v116
	v_mul_f32_e32 v141, s98, v117
	v_mul_f32_e32 v142, s98, v118
	v_mul_f32_e32 v143, s98, v119
	v_mul_f32_e32 v144, s98, v112
	v_mul_f32_e32 v145, s98, v113
	v_mul_f32_e32 v146, s98, v114
	v_mul_f32_e32 v147, s98, v115
	v_cvt_pk_bf16_f32 v136, v140, v141
	v_cvt_pk_bf16_f32 v137, v142, v143
	v_cvt_pk_bf16_f32 v138, v144, v145
	v_cvt_pk_bf16_f32 v139, v146, v147
	global_store_dwordx4 v[128:129], v[136:139], off offset:256 sc1
	v_lshl_add_u64 v[128:129], v[128:129], 0, s[94:95]
	v_mul_f32_e32 v140, s98, v108
	v_mul_f32_e32 v141, s98, v109
	v_mul_f32_e32 v142, s98, v110
	v_mul_f32_e32 v143, s98, v111
	v_mul_f32_e32 v144, s98, v104
	v_mul_f32_e32 v145, s98, v105
	v_mul_f32_e32 v146, s98, v106
	v_mul_f32_e32 v147, s98, v107
	v_cvt_pk_bf16_f32 v132, v140, v141
	v_cvt_pk_bf16_f32 v133, v142, v143
	v_cvt_pk_bf16_f32 v134, v144, v145
	v_cvt_pk_bf16_f32 v135, v146, v147
	global_store_dwordx4 v[128:129], v[132:135], off sc1
	v_mul_f32_e32 v140, s98, v100
	v_mul_f32_e32 v141, s98, v101
	v_mul_f32_e32 v142, s98, v102
	v_mul_f32_e32 v143, s98, v103
	v_mul_f32_e32 v144, s98, v96
	v_mul_f32_e32 v145, s98, v97
	v_mul_f32_e32 v146, s98, v98
	v_mul_f32_e32 v147, s98, v99
	v_cvt_pk_bf16_f32 v136, v140, v141
	v_cvt_pk_bf16_f32 v137, v142, v143
	v_cvt_pk_bf16_f32 v138, v144, v145
	v_cvt_pk_bf16_f32 v139, v146, v147
	global_store_dwordx4 v[128:129], v[136:139], off offset:256 sc1
	v_lshl_add_u64 v[128:129], v[128:129], 0, s[94:95]
	v_mul_f32_e32 v140, s98, v92
	v_mul_f32_e32 v141, s98, v93
	v_mul_f32_e32 v142, s98, v94
	v_mul_f32_e32 v143, s98, v95
	v_mul_f32_e32 v144, s98, v88
	v_mul_f32_e32 v145, s98, v89
	v_mul_f32_e32 v146, s98, v90
	v_mul_f32_e32 v147, s98, v91
	v_cvt_pk_bf16_f32 v132, v140, v141
	v_cvt_pk_bf16_f32 v133, v142, v143
	v_cvt_pk_bf16_f32 v134, v144, v145
	v_cvt_pk_bf16_f32 v135, v146, v147
	global_store_dwordx4 v[128:129], v[132:135], off sc1
	v_mul_f32_e32 v140, s98, v84
	v_mul_f32_e32 v141, s98, v85
	v_mul_f32_e32 v142, s98, v86
	v_mul_f32_e32 v143, s98, v87
	v_mul_f32_e32 v144, s98, v80
	v_mul_f32_e32 v145, s98, v81
	v_mul_f32_e32 v146, s98, v82
	v_mul_f32_e32 v147, s98, v83
	v_cvt_pk_bf16_f32 v136, v140, v141
	v_cvt_pk_bf16_f32 v137, v142, v143
	v_cvt_pk_bf16_f32 v138, v144, v145
	v_cvt_pk_bf16_f32 v139, v146, v147
	global_store_dwordx4 v[128:129], v[136:139], off offset:256 sc1
	v_lshl_add_u64 v[128:129], v[128:129], 0, s[94:95]
	v_mul_f32_e32 v140, s98, v76
	v_mul_f32_e32 v141, s98, v77
	v_mul_f32_e32 v142, s98, v78
	v_mul_f32_e32 v143, s98, v79
	v_mul_f32_e32 v144, s98, v72
	v_mul_f32_e32 v145, s98, v73
	v_mul_f32_e32 v146, s98, v74
	v_mul_f32_e32 v147, s98, v75
	v_cvt_pk_bf16_f32 v132, v140, v141
	v_cvt_pk_bf16_f32 v133, v142, v143
	v_cvt_pk_bf16_f32 v134, v144, v145
	v_cvt_pk_bf16_f32 v135, v146, v147
	global_store_dwordx4 v[128:129], v[132:135], off sc1
	v_mul_f32_e32 v140, s98, v68
	v_mul_f32_e32 v141, s98, v69
	v_mul_f32_e32 v142, s98, v70
	v_mul_f32_e32 v143, s98, v71
	v_mul_f32_e32 v144, s98, v64
	v_mul_f32_e32 v145, s98, v65
	v_mul_f32_e32 v146, s98, v66
	v_mul_f32_e32 v147, s98, v67
	v_cvt_pk_bf16_f32 v136, v140, v141
	v_cvt_pk_bf16_f32 v137, v142, v143
	v_cvt_pk_bf16_f32 v138, v144, v145
	v_cvt_pk_bf16_f32 v139, v146, v147
	global_store_dwordx4 v[128:129], v[136:139], off offset:256 sc1
	v_lshl_add_u64 v[128:129], v[128:129], 0, s[96:97]
	v_mul_f32_e32 v140, s98, v60
	v_mul_f32_e32 v141, s98, v61
	v_mul_f32_e32 v142, s98, v62
	v_mul_f32_e32 v143, s98, v63
	v_mul_f32_e32 v144, s98, v56
	v_mul_f32_e32 v145, s98, v57
	v_mul_f32_e32 v146, s98, v58
	v_mul_f32_e32 v147, s98, v59
	v_cvt_pk_bf16_f32 v132, v140, v141
	v_cvt_pk_bf16_f32 v133, v142, v143
	v_cvt_pk_bf16_f32 v134, v144, v145
	v_cvt_pk_bf16_f32 v135, v146, v147
	global_store_dwordx4 v[128:129], v[132:135], off sc1
	v_mul_f32_e32 v140, s98, v52
	v_mul_f32_e32 v141, s98, v53
	v_mul_f32_e32 v142, s98, v54
	v_mul_f32_e32 v143, s98, v55
	v_mul_f32_e32 v144, s98, v48
	v_mul_f32_e32 v145, s98, v49
	v_mul_f32_e32 v146, s98, v50
	v_mul_f32_e32 v147, s98, v51
	v_cvt_pk_bf16_f32 v136, v140, v141
	v_cvt_pk_bf16_f32 v137, v142, v143
	v_cvt_pk_bf16_f32 v138, v144, v145
	v_cvt_pk_bf16_f32 v139, v146, v147
	global_store_dwordx4 v[128:129], v[136:139], off offset:256 sc1
	v_lshl_add_u64 v[128:129], v[128:129], 0, s[94:95]
	v_mul_f32_e32 v140, s98, v44
	v_mul_f32_e32 v141, s98, v45
	v_mul_f32_e32 v142, s98, v46
	v_mul_f32_e32 v143, s98, v47
	v_mul_f32_e32 v144, s98, v40
	v_mul_f32_e32 v145, s98, v41
	v_mul_f32_e32 v146, s98, v42
	v_mul_f32_e32 v147, s98, v43
	v_cvt_pk_bf16_f32 v132, v140, v141
	v_cvt_pk_bf16_f32 v133, v142, v143
	v_cvt_pk_bf16_f32 v134, v144, v145
	v_cvt_pk_bf16_f32 v135, v146, v147
	global_store_dwordx4 v[128:129], v[132:135], off sc1
	v_mul_f32_e32 v140, s98, v36
	v_mul_f32_e32 v141, s98, v37
	v_mul_f32_e32 v142, s98, v38
	v_mul_f32_e32 v143, s98, v39
	v_mul_f32_e32 v144, s98, v32
	v_mul_f32_e32 v145, s98, v33
	v_mul_f32_e32 v146, s98, v34
	v_mul_f32_e32 v147, s98, v35
	v_cvt_pk_bf16_f32 v136, v140, v141
	v_cvt_pk_bf16_f32 v137, v142, v143
	v_cvt_pk_bf16_f32 v138, v144, v145
	v_cvt_pk_bf16_f32 v139, v146, v147
	global_store_dwordx4 v[128:129], v[136:139], off offset:256 sc1
	v_lshl_add_u64 v[128:129], v[128:129], 0, s[94:95]
	v_mul_f32_e32 v140, s98, v28
	v_mul_f32_e32 v141, s98, v29
	v_mul_f32_e32 v142, s98, v30
	v_mul_f32_e32 v143, s98, v31
	v_mul_f32_e32 v144, s98, v24
	v_mul_f32_e32 v145, s98, v25
	v_mul_f32_e32 v146, s98, v26
	v_mul_f32_e32 v147, s98, v27
	v_cvt_pk_bf16_f32 v132, v140, v141
	v_cvt_pk_bf16_f32 v133, v142, v143
	v_cvt_pk_bf16_f32 v134, v144, v145
	v_cvt_pk_bf16_f32 v135, v146, v147
	global_store_dwordx4 v[128:129], v[132:135], off sc1
	v_mul_f32_e32 v140, s98, v20
	v_mul_f32_e32 v141, s98, v21
	v_mul_f32_e32 v142, s98, v22
	v_mul_f32_e32 v143, s98, v23
	v_mul_f32_e32 v144, s98, v16
	v_mul_f32_e32 v145, s98, v17
	v_mul_f32_e32 v146, s98, v18
	v_mul_f32_e32 v147, s98, v19
	v_cvt_pk_bf16_f32 v136, v140, v141
	v_cvt_pk_bf16_f32 v137, v142, v143
	v_cvt_pk_bf16_f32 v138, v144, v145
	v_cvt_pk_bf16_f32 v139, v146, v147
	global_store_dwordx4 v[128:129], v[136:139], off offset:256 sc1
	v_lshl_add_u64 v[128:129], v[128:129], 0, s[94:95]
	v_mul_f32_e32 v140, s98, v12
	v_mul_f32_e32 v141, s98, v13
	v_mul_f32_e32 v142, s98, v14
	v_mul_f32_e32 v143, s98, v15
	v_mul_f32_e32 v144, s98, v8
	v_mul_f32_e32 v145, s98, v9
	v_mul_f32_e32 v146, s98, v10
	v_mul_f32_e32 v147, s98, v11
	v_cvt_pk_bf16_f32 v132, v140, v141
	v_cvt_pk_bf16_f32 v133, v142, v143
	v_cvt_pk_bf16_f32 v134, v144, v145
	v_cvt_pk_bf16_f32 v135, v146, v147
	global_store_dwordx4 v[128:129], v[132:135], off sc1
	v_mul_f32_e32 v140, s98, v4
	v_mul_f32_e32 v141, s98, v5
	v_mul_f32_e32 v142, s98, v6
	v_mul_f32_e32 v143, s98, v7
	v_mul_f32_e32 v144, s98, v0
	v_mul_f32_e32 v145, s98, v1
	v_mul_f32_e32 v146, s98, v2
	v_mul_f32_e32 v147, s98, v3
	v_cvt_pk_bf16_f32 v136, v140, v141
	v_cvt_pk_bf16_f32 v137, v142, v143
	v_cvt_pk_bf16_f32 v138, v144, v145
	v_cvt_pk_bf16_f32 v139, v146, v147
	global_store_dwordx4 v[128:129], v[136:139], off offset:256 sc1
	s_branch .Lp1st_done
.Lp1st_plain:
	v_cvt_pk_bf16_f32 v132, v124, v125
	v_cvt_pk_bf16_f32 v133, v126, v127
	v_cvt_pk_bf16_f32 v134, v120, v121
	v_cvt_pk_bf16_f32 v135, v122, v123
	global_store_dwordx4 v[128:129], v[132:135], off sc1
	v_cvt_pk_bf16_f32 v136, v116, v117
	v_cvt_pk_bf16_f32 v137, v118, v119
	v_cvt_pk_bf16_f32 v138, v112, v113
	v_cvt_pk_bf16_f32 v139, v114, v115
	global_store_dwordx4 v[128:129], v[136:139], off offset:256 sc1
	v_lshl_add_u64 v[128:129], v[128:129], 0, s[94:95]
	v_cvt_pk_bf16_f32 v132, v108, v109
	v_cvt_pk_bf16_f32 v133, v110, v111
	v_cvt_pk_bf16_f32 v134, v104, v105
	v_cvt_pk_bf16_f32 v135, v106, v107
	global_store_dwordx4 v[128:129], v[132:135], off sc1
	v_cvt_pk_bf16_f32 v136, v100, v101
	v_cvt_pk_bf16_f32 v137, v102, v103
	v_cvt_pk_bf16_f32 v138, v96, v97
	v_cvt_pk_bf16_f32 v139, v98, v99
	global_store_dwordx4 v[128:129], v[136:139], off offset:256 sc1
	v_lshl_add_u64 v[128:129], v[128:129], 0, s[94:95]
	v_cvt_pk_bf16_f32 v132, v92, v93
	v_cvt_pk_bf16_f32 v133, v94, v95
	v_cvt_pk_bf16_f32 v134, v88, v89
	v_cvt_pk_bf16_f32 v135, v90, v91
	global_store_dwordx4 v[128:129], v[132:135], off sc1
	v_cvt_pk_bf16_f32 v136, v84, v85
	v_cvt_pk_bf16_f32 v137, v86, v87
	v_cvt_pk_bf16_f32 v138, v80, v81
	v_cvt_pk_bf16_f32 v139, v82, v83
	global_store_dwordx4 v[128:129], v[136:139], off offset:256 sc1
	v_lshl_add_u64 v[128:129], v[128:129], 0, s[94:95]
	v_cvt_pk_bf16_f32 v132, v76, v77
	v_cvt_pk_bf16_f32 v133, v78, v79
	v_cvt_pk_bf16_f32 v134, v72, v73
	v_cvt_pk_bf16_f32 v135, v74, v75
	global_store_dwordx4 v[128:129], v[132:135], off sc1
	v_cvt_pk_bf16_f32 v136, v68, v69
	v_cvt_pk_bf16_f32 v137, v70, v71
	v_cvt_pk_bf16_f32 v138, v64, v65
	v_cvt_pk_bf16_f32 v139, v66, v67
	global_store_dwordx4 v[128:129], v[136:139], off offset:256 sc1
	v_lshl_add_u64 v[128:129], v[128:129], 0, s[96:97]
	v_cvt_pk_bf16_f32 v132, v60, v61
	v_cvt_pk_bf16_f32 v133, v62, v63
	v_cvt_pk_bf16_f32 v134, v56, v57
	v_cvt_pk_bf16_f32 v135, v58, v59
	global_store_dwordx4 v[128:129], v[132:135], off sc1
	v_cvt_pk_bf16_f32 v136, v52, v53
	v_cvt_pk_bf16_f32 v137, v54, v55
	v_cvt_pk_bf16_f32 v138, v48, v49
	v_cvt_pk_bf16_f32 v139, v50, v51
	global_store_dwordx4 v[128:129], v[136:139], off offset:256 sc1
	v_lshl_add_u64 v[128:129], v[128:129], 0, s[94:95]
	v_cvt_pk_bf16_f32 v132, v44, v45
	v_cvt_pk_bf16_f32 v133, v46, v47
	v_cvt_pk_bf16_f32 v134, v40, v41
	v_cvt_pk_bf16_f32 v135, v42, v43
	global_store_dwordx4 v[128:129], v[132:135], off sc1
	v_cvt_pk_bf16_f32 v136, v36, v37
	v_cvt_pk_bf16_f32 v137, v38, v39
	v_cvt_pk_bf16_f32 v138, v32, v33
	v_cvt_pk_bf16_f32 v139, v34, v35
	global_store_dwordx4 v[128:129], v[136:139], off offset:256 sc1
	v_lshl_add_u64 v[128:129], v[128:129], 0, s[94:95]
	v_cvt_pk_bf16_f32 v132, v28, v29
	v_cvt_pk_bf16_f32 v133, v30, v31
	v_cvt_pk_bf16_f32 v134, v24, v25
	v_cvt_pk_bf16_f32 v135, v26, v27
	global_store_dwordx4 v[128:129], v[132:135], off sc1
	v_cvt_pk_bf16_f32 v136, v20, v21
	v_cvt_pk_bf16_f32 v137, v22, v23
	v_cvt_pk_bf16_f32 v138, v16, v17
	v_cvt_pk_bf16_f32 v139, v18, v19
	global_store_dwordx4 v[128:129], v[136:139], off offset:256 sc1
	v_lshl_add_u64 v[128:129], v[128:129], 0, s[94:95]
	v_cvt_pk_bf16_f32 v132, v12, v13
	v_cvt_pk_bf16_f32 v133, v14, v15
	v_cvt_pk_bf16_f32 v134, v8, v9
	v_cvt_pk_bf16_f32 v135, v10, v11
	global_store_dwordx4 v[128:129], v[132:135], off sc1
	v_cvt_pk_bf16_f32 v136, v4, v5
	v_cvt_pk_bf16_f32 v137, v6, v7
	v_cvt_pk_bf16_f32 v138, v0, v1
	v_cvt_pk_bf16_f32 v139, v2, v3
	global_store_dwordx4 v[128:129], v[136:139], off offset:256 sc1
	s_branch .Lp1st_done
.Lp1st_silu:
	v_mul_f32_e32 v140, 0xbfb8aa3b, v124
	v_mul_f32_e32 v141, 0xbfb8aa3b, v125
	v_mul_f32_e32 v142, 0xbfb8aa3b, v126
	v_mul_f32_e32 v143, 0xbfb8aa3b, v127
	v_mul_f32_e32 v144, 0xbfb8aa3b, v120
	v_mul_f32_e32 v145, 0xbfb8aa3b, v121
	v_mul_f32_e32 v146, 0xbfb8aa3b, v122
	v_mul_f32_e32 v147, 0xbfb8aa3b, v123
	v_exp_f32_e32 v140, v140
	v_exp_f32_e32 v141, v141
	v_exp_f32_e32 v142, v142
	v_exp_f32_e32 v143, v143
	v_exp_f32_e32 v144, v144
	v_exp_f32_e32 v145, v145
	v_exp_f32_e32 v146, v146
	v_exp_f32_e32 v147, v147
	v_add_f32_e32 v140, 1.0, v140
	v_add_f32_e32 v141, 1.0, v141
	v_add_f32_e32 v142, 1.0, v142
	v_add_f32_e32 v143, 1.0, v143
	v_add_f32_e32 v144, 1.0, v144
	v_add_f32_e32 v145, 1.0, v145
	v_add_f32_e32 v146, 1.0, v146
	v_add_f32_e32 v147, 1.0, v147
	v_rcp_f32_e32 v140, v140
	v_rcp_f32_e32 v141, v141
	v_rcp_f32_e32 v142, v142
	v_rcp_f32_e32 v143, v143
	v_rcp_f32_e32 v144, v144
	v_rcp_f32_e32 v145, v145
	v_rcp_f32_e32 v146, v146
	v_rcp_f32_e32 v147, v147
	v_mul_f32_e32 v140, v124, v140
	v_mul_f32_e32 v141, v125, v141
	v_mul_f32_e32 v142, v126, v142
	v_mul_f32_e32 v143, v127, v143
	v_mul_f32_e32 v144, v120, v144
	v_mul_f32_e32 v145, v121, v145
	v_mul_f32_e32 v146, v122, v146
	v_mul_f32_e32 v147, v123, v147
	v_cvt_pk_bf16_f32 v132, v140, v141
	v_cvt_pk_bf16_f32 v133, v142, v143
	v_cvt_pk_bf16_f32 v134, v144, v145
	v_cvt_pk_bf16_f32 v135, v146, v147
	global_store_dwordx4 v[128:129], v[132:135], off sc1
	v_mul_f32_e32 v140, 0xbfb8aa3b, v116
	v_mul_f32_e32 v141, 0xbfb8aa3b, v117
	v_mul_f32_e32 v142, 0xbfb8aa3b, v118
	v_mul_f32_e32 v143, 0xbfb8aa3b, v119
	v_mul_f32_e32 v144, 0xbfb8aa3b, v112
	v_mul_f32_e32 v145, 0xbfb8aa3b, v113
	v_mul_f32_e32 v146, 0xbfb8aa3b, v114
	v_mul_f32_e32 v147, 0xbfb8aa3b, v115
	v_exp_f32_e32 v140, v140
	v_exp_f32_e32 v141, v141
	v_exp_f32_e32 v142, v142
	v_exp_f32_e32 v143, v143
	v_exp_f32_e32 v144, v144
	v_exp_f32_e32 v145, v145
	v_exp_f32_e32 v146, v146
	v_exp_f32_e32 v147, v147
	v_add_f32_e32 v140, 1.0, v140
	v_add_f32_e32 v141, 1.0, v141
	v_add_f32_e32 v142, 1.0, v142
	v_add_f32_e32 v143, 1.0, v143
	v_add_f32_e32 v144, 1.0, v144
	v_add_f32_e32 v145, 1.0, v145
	v_add_f32_e32 v146, 1.0, v146
	v_add_f32_e32 v147, 1.0, v147
	v_rcp_f32_e32 v140, v140
	v_rcp_f32_e32 v141, v141
	v_rcp_f32_e32 v142, v142
	v_rcp_f32_e32 v143, v143
	v_rcp_f32_e32 v144, v144
	v_rcp_f32_e32 v145, v145
	v_rcp_f32_e32 v146, v146
	v_rcp_f32_e32 v147, v147
	v_mul_f32_e32 v140, v116, v140
	v_mul_f32_e32 v141, v117, v141
	v_mul_f32_e32 v142, v118, v142
	v_mul_f32_e32 v143, v119, v143
	v_mul_f32_e32 v144, v112, v144
	v_mul_f32_e32 v145, v113, v145
	v_mul_f32_e32 v146, v114, v146
	v_mul_f32_e32 v147, v115, v147
	v_cvt_pk_bf16_f32 v136, v140, v141
	v_cvt_pk_bf16_f32 v137, v142, v143
	v_cvt_pk_bf16_f32 v138, v144, v145
	v_cvt_pk_bf16_f32 v139, v146, v147
	global_store_dwordx4 v[128:129], v[136:139], off offset:256 sc1
	v_lshl_add_u64 v[128:129], v[128:129], 0, s[94:95]
	v_mul_f32_e32 v140, 0xbfb8aa3b, v108
	v_mul_f32_e32 v141, 0xbfb8aa3b, v109
	v_mul_f32_e32 v142, 0xbfb8aa3b, v110
	v_mul_f32_e32 v143, 0xbfb8aa3b, v111
	v_mul_f32_e32 v144, 0xbfb8aa3b, v104
	v_mul_f32_e32 v145, 0xbfb8aa3b, v105
	v_mul_f32_e32 v146, 0xbfb8aa3b, v106
	v_mul_f32_e32 v147, 0xbfb8aa3b, v107
	v_exp_f32_e32 v140, v140
	v_exp_f32_e32 v141, v141
	v_exp_f32_e32 v142, v142
	v_exp_f32_e32 v143, v143
	v_exp_f32_e32 v144, v144
	v_exp_f32_e32 v145, v145
	v_exp_f32_e32 v146, v146
	v_exp_f32_e32 v147, v147
	v_add_f32_e32 v140, 1.0, v140
	v_add_f32_e32 v141, 1.0, v141
	v_add_f32_e32 v142, 1.0, v142
	v_add_f32_e32 v143, 1.0, v143
	v_add_f32_e32 v144, 1.0, v144
	v_add_f32_e32 v145, 1.0, v145
	v_add_f32_e32 v146, 1.0, v146
	v_add_f32_e32 v147, 1.0, v147
	v_rcp_f32_e32 v140, v140
	v_rcp_f32_e32 v141, v141
	v_rcp_f32_e32 v142, v142
	v_rcp_f32_e32 v143, v143
	v_rcp_f32_e32 v144, v144
	v_rcp_f32_e32 v145, v145
	v_rcp_f32_e32 v146, v146
	v_rcp_f32_e32 v147, v147
	v_mul_f32_e32 v140, v108, v140
	v_mul_f32_e32 v141, v109, v141
	v_mul_f32_e32 v142, v110, v142
	v_mul_f32_e32 v143, v111, v143
	v_mul_f32_e32 v144, v104, v144
	v_mul_f32_e32 v145, v105, v145
	v_mul_f32_e32 v146, v106, v146
	v_mul_f32_e32 v147, v107, v147
	v_cvt_pk_bf16_f32 v132, v140, v141
	v_cvt_pk_bf16_f32 v133, v142, v143
	v_cvt_pk_bf16_f32 v134, v144, v145
	v_cvt_pk_bf16_f32 v135, v146, v147
	global_store_dwordx4 v[128:129], v[132:135], off sc1
	v_mul_f32_e32 v140, 0xbfb8aa3b, v100
	v_mul_f32_e32 v141, 0xbfb8aa3b, v101
	v_mul_f32_e32 v142, 0xbfb8aa3b, v102
	v_mul_f32_e32 v143, 0xbfb8aa3b, v103
	v_mul_f32_e32 v144, 0xbfb8aa3b, v96
	v_mul_f32_e32 v145, 0xbfb8aa3b, v97
	v_mul_f32_e32 v146, 0xbfb8aa3b, v98
	v_mul_f32_e32 v147, 0xbfb8aa3b, v99
	v_exp_f32_e32 v140, v140
	v_exp_f32_e32 v141, v141
	v_exp_f32_e32 v142, v142
	v_exp_f32_e32 v143, v143
	v_exp_f32_e32 v144, v144
	v_exp_f32_e32 v145, v145
	v_exp_f32_e32 v146, v146
	v_exp_f32_e32 v147, v147
	v_add_f32_e32 v140, 1.0, v140
	v_add_f32_e32 v141, 1.0, v141
	v_add_f32_e32 v142, 1.0, v142
	v_add_f32_e32 v143, 1.0, v143
	v_add_f32_e32 v144, 1.0, v144
	v_add_f32_e32 v145, 1.0, v145
	v_add_f32_e32 v146, 1.0, v146
	v_add_f32_e32 v147, 1.0, v147
	v_rcp_f32_e32 v140, v140
	v_rcp_f32_e32 v141, v141
	v_rcp_f32_e32 v142, v142
	v_rcp_f32_e32 v143, v143
	v_rcp_f32_e32 v144, v144
	v_rcp_f32_e32 v145, v145
	v_rcp_f32_e32 v146, v146
	v_rcp_f32_e32 v147, v147
	v_mul_f32_e32 v140, v100, v140
	v_mul_f32_e32 v141, v101, v141
	v_mul_f32_e32 v142, v102, v142
	v_mul_f32_e32 v143, v103, v143
	v_mul_f32_e32 v144, v96, v144
	v_mul_f32_e32 v145, v97, v145
	v_mul_f32_e32 v146, v98, v146
	v_mul_f32_e32 v147, v99, v147
	v_cvt_pk_bf16_f32 v136, v140, v141
	v_cvt_pk_bf16_f32 v137, v142, v143
	v_cvt_pk_bf16_f32 v138, v144, v145
	v_cvt_pk_bf16_f32 v139, v146, v147
	global_store_dwordx4 v[128:129], v[136:139], off offset:256 sc1
	v_lshl_add_u64 v[128:129], v[128:129], 0, s[94:95]
	v_mul_f32_e32 v140, 0xbfb8aa3b, v92
	v_mul_f32_e32 v141, 0xbfb8aa3b, v93
	v_mul_f32_e32 v142, 0xbfb8aa3b, v94
	v_mul_f32_e32 v143, 0xbfb8aa3b, v95
	v_mul_f32_e32 v144, 0xbfb8aa3b, v88
	v_mul_f32_e32 v145, 0xbfb8aa3b, v89
	v_mul_f32_e32 v146, 0xbfb8aa3b, v90
	v_mul_f32_e32 v147, 0xbfb8aa3b, v91
	v_exp_f32_e32 v140, v140
	v_exp_f32_e32 v141, v141
	v_exp_f32_e32 v142, v142
	v_exp_f32_e32 v143, v143
	v_exp_f32_e32 v144, v144
	v_exp_f32_e32 v145, v145
	v_exp_f32_e32 v146, v146
	v_exp_f32_e32 v147, v147
	v_add_f32_e32 v140, 1.0, v140
	v_add_f32_e32 v141, 1.0, v141
	v_add_f32_e32 v142, 1.0, v142
	v_add_f32_e32 v143, 1.0, v143
	v_add_f32_e32 v144, 1.0, v144
	v_add_f32_e32 v145, 1.0, v145
	v_add_f32_e32 v146, 1.0, v146
	v_add_f32_e32 v147, 1.0, v147
	v_rcp_f32_e32 v140, v140
	v_rcp_f32_e32 v141, v141
	v_rcp_f32_e32 v142, v142
	v_rcp_f32_e32 v143, v143
	v_rcp_f32_e32 v144, v144
	v_rcp_f32_e32 v145, v145
	v_rcp_f32_e32 v146, v146
	v_rcp_f32_e32 v147, v147
	v_mul_f32_e32 v140, v92, v140
	v_mul_f32_e32 v141, v93, v141
	v_mul_f32_e32 v142, v94, v142
	v_mul_f32_e32 v143, v95, v143
	v_mul_f32_e32 v144, v88, v144
	v_mul_f32_e32 v145, v89, v145
	v_mul_f32_e32 v146, v90, v146
	v_mul_f32_e32 v147, v91, v147
	v_cvt_pk_bf16_f32 v132, v140, v141
	v_cvt_pk_bf16_f32 v133, v142, v143
	v_cvt_pk_bf16_f32 v134, v144, v145
	v_cvt_pk_bf16_f32 v135, v146, v147
	global_store_dwordx4 v[128:129], v[132:135], off sc1
	v_mul_f32_e32 v140, 0xbfb8aa3b, v84
	v_mul_f32_e32 v141, 0xbfb8aa3b, v85
	v_mul_f32_e32 v142, 0xbfb8aa3b, v86
	v_mul_f32_e32 v143, 0xbfb8aa3b, v87
	v_mul_f32_e32 v144, 0xbfb8aa3b, v80
	v_mul_f32_e32 v145, 0xbfb8aa3b, v81
	v_mul_f32_e32 v146, 0xbfb8aa3b, v82
	v_mul_f32_e32 v147, 0xbfb8aa3b, v83
	v_exp_f32_e32 v140, v140
	v_exp_f32_e32 v141, v141
	v_exp_f32_e32 v142, v142
	v_exp_f32_e32 v143, v143
	v_exp_f32_e32 v144, v144
	v_exp_f32_e32 v145, v145
	v_exp_f32_e32 v146, v146
	v_exp_f32_e32 v147, v147
	v_add_f32_e32 v140, 1.0, v140
	v_add_f32_e32 v141, 1.0, v141
	v_add_f32_e32 v142, 1.0, v142
	v_add_f32_e32 v143, 1.0, v143
	v_add_f32_e32 v144, 1.0, v144
	v_add_f32_e32 v145, 1.0, v145
	v_add_f32_e32 v146, 1.0, v146
	v_add_f32_e32 v147, 1.0, v147
	v_rcp_f32_e32 v140, v140
	v_rcp_f32_e32 v141, v141
	v_rcp_f32_e32 v142, v142
	v_rcp_f32_e32 v143, v143
	v_rcp_f32_e32 v144, v144
	v_rcp_f32_e32 v145, v145
	v_rcp_f32_e32 v146, v146
	v_rcp_f32_e32 v147, v147
	v_mul_f32_e32 v140, v84, v140
	v_mul_f32_e32 v141, v85, v141
	v_mul_f32_e32 v142, v86, v142
	v_mul_f32_e32 v143, v87, v143
	v_mul_f32_e32 v144, v80, v144
	v_mul_f32_e32 v145, v81, v145
	v_mul_f32_e32 v146, v82, v146
	v_mul_f32_e32 v147, v83, v147
	v_cvt_pk_bf16_f32 v136, v140, v141
	v_cvt_pk_bf16_f32 v137, v142, v143
	v_cvt_pk_bf16_f32 v138, v144, v145
	v_cvt_pk_bf16_f32 v139, v146, v147
	global_store_dwordx4 v[128:129], v[136:139], off offset:256 sc1
	v_lshl_add_u64 v[128:129], v[128:129], 0, s[94:95]
	v_mul_f32_e32 v140, 0xbfb8aa3b, v76
	v_mul_f32_e32 v141, 0xbfb8aa3b, v77
	v_mul_f32_e32 v142, 0xbfb8aa3b, v78
	v_mul_f32_e32 v143, 0xbfb8aa3b, v79
	v_mul_f32_e32 v144, 0xbfb8aa3b, v72
	v_mul_f32_e32 v145, 0xbfb8aa3b, v73
	v_mul_f32_e32 v146, 0xbfb8aa3b, v74
	v_mul_f32_e32 v147, 0xbfb8aa3b, v75
	v_exp_f32_e32 v140, v140
	v_exp_f32_e32 v141, v141
	v_exp_f32_e32 v142, v142
	v_exp_f32_e32 v143, v143
	v_exp_f32_e32 v144, v144
	v_exp_f32_e32 v145, v145
	v_exp_f32_e32 v146, v146
	v_exp_f32_e32 v147, v147
	v_add_f32_e32 v140, 1.0, v140
	v_add_f32_e32 v141, 1.0, v141
	v_add_f32_e32 v142, 1.0, v142
	v_add_f32_e32 v143, 1.0, v143
	v_add_f32_e32 v144, 1.0, v144
	v_add_f32_e32 v145, 1.0, v145
	v_add_f32_e32 v146, 1.0, v146
	v_add_f32_e32 v147, 1.0, v147
	v_rcp_f32_e32 v140, v140
	v_rcp_f32_e32 v141, v141
	v_rcp_f32_e32 v142, v142
	v_rcp_f32_e32 v143, v143
	v_rcp_f32_e32 v144, v144
	v_rcp_f32_e32 v145, v145
	v_rcp_f32_e32 v146, v146
	v_rcp_f32_e32 v147, v147
	v_mul_f32_e32 v140, v76, v140
	v_mul_f32_e32 v141, v77, v141
	v_mul_f32_e32 v142, v78, v142
	v_mul_f32_e32 v143, v79, v143
	v_mul_f32_e32 v144, v72, v144
	v_mul_f32_e32 v145, v73, v145
	v_mul_f32_e32 v146, v74, v146
	v_mul_f32_e32 v147, v75, v147
	v_cvt_pk_bf16_f32 v132, v140, v141
	v_cvt_pk_bf16_f32 v133, v142, v143
	v_cvt_pk_bf16_f32 v134, v144, v145
	v_cvt_pk_bf16_f32 v135, v146, v147
	global_store_dwordx4 v[128:129], v[132:135], off sc1
	v_mul_f32_e32 v140, 0xbfb8aa3b, v68
	v_mul_f32_e32 v141, 0xbfb8aa3b, v69
	v_mul_f32_e32 v142, 0xbfb8aa3b, v70
	v_mul_f32_e32 v143, 0xbfb8aa3b, v71
	v_mul_f32_e32 v144, 0xbfb8aa3b, v64
	v_mul_f32_e32 v145, 0xbfb8aa3b, v65
	v_mul_f32_e32 v146, 0xbfb8aa3b, v66
	v_mul_f32_e32 v147, 0xbfb8aa3b, v67
	v_exp_f32_e32 v140, v140
	v_exp_f32_e32 v141, v141
	v_exp_f32_e32 v142, v142
	v_exp_f32_e32 v143, v143
	v_exp_f32_e32 v144, v144
	v_exp_f32_e32 v145, v145
	v_exp_f32_e32 v146, v146
	v_exp_f32_e32 v147, v147
	v_add_f32_e32 v140, 1.0, v140
	v_add_f32_e32 v141, 1.0, v141
	v_add_f32_e32 v142, 1.0, v142
	v_add_f32_e32 v143, 1.0, v143
	v_add_f32_e32 v144, 1.0, v144
	v_add_f32_e32 v145, 1.0, v145
	v_add_f32_e32 v146, 1.0, v146
	v_add_f32_e32 v147, 1.0, v147
	v_rcp_f32_e32 v140, v140
	v_rcp_f32_e32 v141, v141
	v_rcp_f32_e32 v142, v142
	v_rcp_f32_e32 v143, v143
	v_rcp_f32_e32 v144, v144
	v_rcp_f32_e32 v145, v145
	v_rcp_f32_e32 v146, v146
	v_rcp_f32_e32 v147, v147
	v_mul_f32_e32 v140, v68, v140
	v_mul_f32_e32 v141, v69, v141
	v_mul_f32_e32 v142, v70, v142
	v_mul_f32_e32 v143, v71, v143
	v_mul_f32_e32 v144, v64, v144
	v_mul_f32_e32 v145, v65, v145
	v_mul_f32_e32 v146, v66, v146
	v_mul_f32_e32 v147, v67, v147
	v_cvt_pk_bf16_f32 v136, v140, v141
	v_cvt_pk_bf16_f32 v137, v142, v143
	v_cvt_pk_bf16_f32 v138, v144, v145
	v_cvt_pk_bf16_f32 v139, v146, v147
	global_store_dwordx4 v[128:129], v[136:139], off offset:256 sc1
	v_lshl_add_u64 v[128:129], v[128:129], 0, s[96:97]
	v_mul_f32_e32 v140, 0xbfb8aa3b, v60
	v_mul_f32_e32 v141, 0xbfb8aa3b, v61
	v_mul_f32_e32 v142, 0xbfb8aa3b, v62
	v_mul_f32_e32 v143, 0xbfb8aa3b, v63
	v_mul_f32_e32 v144, 0xbfb8aa3b, v56
	v_mul_f32_e32 v145, 0xbfb8aa3b, v57
	v_mul_f32_e32 v146, 0xbfb8aa3b, v58
	v_mul_f32_e32 v147, 0xbfb8aa3b, v59
	v_exp_f32_e32 v140, v140
	v_exp_f32_e32 v141, v141
	v_exp_f32_e32 v142, v142
	v_exp_f32_e32 v143, v143
	v_exp_f32_e32 v144, v144
	v_exp_f32_e32 v145, v145
	v_exp_f32_e32 v146, v146
	v_exp_f32_e32 v147, v147
	v_add_f32_e32 v140, 1.0, v140
	v_add_f32_e32 v141, 1.0, v141
	v_add_f32_e32 v142, 1.0, v142
	v_add_f32_e32 v143, 1.0, v143
	v_add_f32_e32 v144, 1.0, v144
	v_add_f32_e32 v145, 1.0, v145
	v_add_f32_e32 v146, 1.0, v146
	v_add_f32_e32 v147, 1.0, v147
	v_rcp_f32_e32 v140, v140
	v_rcp_f32_e32 v141, v141
	v_rcp_f32_e32 v142, v142
	v_rcp_f32_e32 v143, v143
	v_rcp_f32_e32 v144, v144
	v_rcp_f32_e32 v145, v145
	v_rcp_f32_e32 v146, v146
	v_rcp_f32_e32 v147, v147
	v_mul_f32_e32 v140, v60, v140
	v_mul_f32_e32 v141, v61, v141
	v_mul_f32_e32 v142, v62, v142
	v_mul_f32_e32 v143, v63, v143
	v_mul_f32_e32 v144, v56, v144
	v_mul_f32_e32 v145, v57, v145
	v_mul_f32_e32 v146, v58, v146
	v_mul_f32_e32 v147, v59, v147
	v_cvt_pk_bf16_f32 v132, v140, v141
	v_cvt_pk_bf16_f32 v133, v142, v143
	v_cvt_pk_bf16_f32 v134, v144, v145
	v_cvt_pk_bf16_f32 v135, v146, v147
	global_store_dwordx4 v[128:129], v[132:135], off sc1
	v_mul_f32_e32 v140, 0xbfb8aa3b, v52
	v_mul_f32_e32 v141, 0xbfb8aa3b, v53
	v_mul_f32_e32 v142, 0xbfb8aa3b, v54
	v_mul_f32_e32 v143, 0xbfb8aa3b, v55
	v_mul_f32_e32 v144, 0xbfb8aa3b, v48
	v_mul_f32_e32 v145, 0xbfb8aa3b, v49
	v_mul_f32_e32 v146, 0xbfb8aa3b, v50
	v_mul_f32_e32 v147, 0xbfb8aa3b, v51
	v_exp_f32_e32 v140, v140
	v_exp_f32_e32 v141, v141
	v_exp_f32_e32 v142, v142
	v_exp_f32_e32 v143, v143
	v_exp_f32_e32 v144, v144
	v_exp_f32_e32 v145, v145
	v_exp_f32_e32 v146, v146
	v_exp_f32_e32 v147, v147
	v_add_f32_e32 v140, 1.0, v140
	v_add_f32_e32 v141, 1.0, v141
	v_add_f32_e32 v142, 1.0, v142
	v_add_f32_e32 v143, 1.0, v143
	v_add_f32_e32 v144, 1.0, v144
	v_add_f32_e32 v145, 1.0, v145
	v_add_f32_e32 v146, 1.0, v146
	v_add_f32_e32 v147, 1.0, v147
	v_rcp_f32_e32 v140, v140
	v_rcp_f32_e32 v141, v141
	v_rcp_f32_e32 v142, v142
	v_rcp_f32_e32 v143, v143
	v_rcp_f32_e32 v144, v144
	v_rcp_f32_e32 v145, v145
	v_rcp_f32_e32 v146, v146
	v_rcp_f32_e32 v147, v147
	v_mul_f32_e32 v140, v52, v140
	v_mul_f32_e32 v141, v53, v141
	v_mul_f32_e32 v142, v54, v142
	v_mul_f32_e32 v143, v55, v143
	v_mul_f32_e32 v144, v48, v144
	v_mul_f32_e32 v145, v49, v145
	v_mul_f32_e32 v146, v50, v146
	v_mul_f32_e32 v147, v51, v147
	v_cvt_pk_bf16_f32 v136, v140, v141
	v_cvt_pk_bf16_f32 v137, v142, v143
	v_cvt_pk_bf16_f32 v138, v144, v145
	v_cvt_pk_bf16_f32 v139, v146, v147
	global_store_dwordx4 v[128:129], v[136:139], off offset:256 sc1
	v_lshl_add_u64 v[128:129], v[128:129], 0, s[94:95]
	v_mul_f32_e32 v140, 0xbfb8aa3b, v44
	v_mul_f32_e32 v141, 0xbfb8aa3b, v45
	v_mul_f32_e32 v142, 0xbfb8aa3b, v46
	v_mul_f32_e32 v143, 0xbfb8aa3b, v47
	v_mul_f32_e32 v144, 0xbfb8aa3b, v40
	v_mul_f32_e32 v145, 0xbfb8aa3b, v41
	v_mul_f32_e32 v146, 0xbfb8aa3b, v42
	v_mul_f32_e32 v147, 0xbfb8aa3b, v43
	v_exp_f32_e32 v140, v140
	v_exp_f32_e32 v141, v141
	v_exp_f32_e32 v142, v142
	v_exp_f32_e32 v143, v143
	v_exp_f32_e32 v144, v144
	v_exp_f32_e32 v145, v145
	v_exp_f32_e32 v146, v146
	v_exp_f32_e32 v147, v147
	v_add_f32_e32 v140, 1.0, v140
	v_add_f32_e32 v141, 1.0, v141
	v_add_f32_e32 v142, 1.0, v142
	v_add_f32_e32 v143, 1.0, v143
	v_add_f32_e32 v144, 1.0, v144
	v_add_f32_e32 v145, 1.0, v145
	v_add_f32_e32 v146, 1.0, v146
	v_add_f32_e32 v147, 1.0, v147
	v_rcp_f32_e32 v140, v140
	v_rcp_f32_e32 v141, v141
	v_rcp_f32_e32 v142, v142
	v_rcp_f32_e32 v143, v143
	v_rcp_f32_e32 v144, v144
	v_rcp_f32_e32 v145, v145
	v_rcp_f32_e32 v146, v146
	v_rcp_f32_e32 v147, v147
	v_mul_f32_e32 v140, v44, v140
	v_mul_f32_e32 v141, v45, v141
	v_mul_f32_e32 v142, v46, v142
	v_mul_f32_e32 v143, v47, v143
	v_mul_f32_e32 v144, v40, v144
	v_mul_f32_e32 v145, v41, v145
	v_mul_f32_e32 v146, v42, v146
	v_mul_f32_e32 v147, v43, v147
	v_cvt_pk_bf16_f32 v132, v140, v141
	v_cvt_pk_bf16_f32 v133, v142, v143
	v_cvt_pk_bf16_f32 v134, v144, v145
	v_cvt_pk_bf16_f32 v135, v146, v147
	global_store_dwordx4 v[128:129], v[132:135], off sc1
	v_mul_f32_e32 v140, 0xbfb8aa3b, v36
	v_mul_f32_e32 v141, 0xbfb8aa3b, v37
	v_mul_f32_e32 v142, 0xbfb8aa3b, v38
	v_mul_f32_e32 v143, 0xbfb8aa3b, v39
	v_mul_f32_e32 v144, 0xbfb8aa3b, v32
	v_mul_f32_e32 v145, 0xbfb8aa3b, v33
	v_mul_f32_e32 v146, 0xbfb8aa3b, v34
	v_mul_f32_e32 v147, 0xbfb8aa3b, v35
	v_exp_f32_e32 v140, v140
	v_exp_f32_e32 v141, v141
	v_exp_f32_e32 v142, v142
	v_exp_f32_e32 v143, v143
	v_exp_f32_e32 v144, v144
	v_exp_f32_e32 v145, v145
	v_exp_f32_e32 v146, v146
	v_exp_f32_e32 v147, v147
	v_add_f32_e32 v140, 1.0, v140
	v_add_f32_e32 v141, 1.0, v141
	v_add_f32_e32 v142, 1.0, v142
	v_add_f32_e32 v143, 1.0, v143
	v_add_f32_e32 v144, 1.0, v144
	v_add_f32_e32 v145, 1.0, v145
	v_add_f32_e32 v146, 1.0, v146
	v_add_f32_e32 v147, 1.0, v147
	v_rcp_f32_e32 v140, v140
	v_rcp_f32_e32 v141, v141
	v_rcp_f32_e32 v142, v142
	v_rcp_f32_e32 v143, v143
	v_rcp_f32_e32 v144, v144
	v_rcp_f32_e32 v145, v145
	v_rcp_f32_e32 v146, v146
	v_rcp_f32_e32 v147, v147
	v_mul_f32_e32 v140, v36, v140
	v_mul_f32_e32 v141, v37, v141
	v_mul_f32_e32 v142, v38, v142
	v_mul_f32_e32 v143, v39, v143
	v_mul_f32_e32 v144, v32, v144
	v_mul_f32_e32 v145, v33, v145
	v_mul_f32_e32 v146, v34, v146
	v_mul_f32_e32 v147, v35, v147
	v_cvt_pk_bf16_f32 v136, v140, v141
	v_cvt_pk_bf16_f32 v137, v142, v143
	v_cvt_pk_bf16_f32 v138, v144, v145
	v_cvt_pk_bf16_f32 v139, v146, v147
	global_store_dwordx4 v[128:129], v[136:139], off offset:256 sc1
	v_lshl_add_u64 v[128:129], v[128:129], 0, s[94:95]
	v_mul_f32_e32 v140, 0xbfb8aa3b, v28
	v_mul_f32_e32 v141, 0xbfb8aa3b, v29
	v_mul_f32_e32 v142, 0xbfb8aa3b, v30
	v_mul_f32_e32 v143, 0xbfb8aa3b, v31
	v_mul_f32_e32 v144, 0xbfb8aa3b, v24
	v_mul_f32_e32 v145, 0xbfb8aa3b, v25
	v_mul_f32_e32 v146, 0xbfb8aa3b, v26
	v_mul_f32_e32 v147, 0xbfb8aa3b, v27
	v_exp_f32_e32 v140, v140
	v_exp_f32_e32 v141, v141
	v_exp_f32_e32 v142, v142
	v_exp_f32_e32 v143, v143
	v_exp_f32_e32 v144, v144
	v_exp_f32_e32 v145, v145
	v_exp_f32_e32 v146, v146
	v_exp_f32_e32 v147, v147
	v_add_f32_e32 v140, 1.0, v140
	v_add_f32_e32 v141, 1.0, v141
	v_add_f32_e32 v142, 1.0, v142
	v_add_f32_e32 v143, 1.0, v143
	v_add_f32_e32 v144, 1.0, v144
	v_add_f32_e32 v145, 1.0, v145
	v_add_f32_e32 v146, 1.0, v146
	v_add_f32_e32 v147, 1.0, v147
	v_rcp_f32_e32 v140, v140
	v_rcp_f32_e32 v141, v141
	v_rcp_f32_e32 v142, v142
	v_rcp_f32_e32 v143, v143
	v_rcp_f32_e32 v144, v144
	v_rcp_f32_e32 v145, v145
	v_rcp_f32_e32 v146, v146
	v_rcp_f32_e32 v147, v147
	v_mul_f32_e32 v140, v28, v140
	v_mul_f32_e32 v141, v29, v141
	v_mul_f32_e32 v142, v30, v142
	v_mul_f32_e32 v143, v31, v143
	v_mul_f32_e32 v144, v24, v144
	v_mul_f32_e32 v145, v25, v145
	v_mul_f32_e32 v146, v26, v146
	v_mul_f32_e32 v147, v27, v147
	v_cvt_pk_bf16_f32 v132, v140, v141
	v_cvt_pk_bf16_f32 v133, v142, v143
	v_cvt_pk_bf16_f32 v134, v144, v145
	v_cvt_pk_bf16_f32 v135, v146, v147
	global_store_dwordx4 v[128:129], v[132:135], off sc1
	v_mul_f32_e32 v140, 0xbfb8aa3b, v20
	v_mul_f32_e32 v141, 0xbfb8aa3b, v21
	v_mul_f32_e32 v142, 0xbfb8aa3b, v22
	v_mul_f32_e32 v143, 0xbfb8aa3b, v23
	v_mul_f32_e32 v144, 0xbfb8aa3b, v16
	v_mul_f32_e32 v145, 0xbfb8aa3b, v17
	v_mul_f32_e32 v146, 0xbfb8aa3b, v18
	v_mul_f32_e32 v147, 0xbfb8aa3b, v19
	v_exp_f32_e32 v140, v140
	v_exp_f32_e32 v141, v141
	v_exp_f32_e32 v142, v142
	v_exp_f32_e32 v143, v143
	v_exp_f32_e32 v144, v144
	v_exp_f32_e32 v145, v145
	v_exp_f32_e32 v146, v146
	v_exp_f32_e32 v147, v147
	v_add_f32_e32 v140, 1.0, v140
	v_add_f32_e32 v141, 1.0, v141
	v_add_f32_e32 v142, 1.0, v142
	v_add_f32_e32 v143, 1.0, v143
	v_add_f32_e32 v144, 1.0, v144
	v_add_f32_e32 v145, 1.0, v145
	v_add_f32_e32 v146, 1.0, v146
	v_add_f32_e32 v147, 1.0, v147
	v_rcp_f32_e32 v140, v140
	v_rcp_f32_e32 v141, v141
	v_rcp_f32_e32 v142, v142
	v_rcp_f32_e32 v143, v143
	v_rcp_f32_e32 v144, v144
	v_rcp_f32_e32 v145, v145
	v_rcp_f32_e32 v146, v146
	v_rcp_f32_e32 v147, v147
	v_mul_f32_e32 v140, v20, v140
	v_mul_f32_e32 v141, v21, v141
	v_mul_f32_e32 v142, v22, v142
	v_mul_f32_e32 v143, v23, v143
	v_mul_f32_e32 v144, v16, v144
	v_mul_f32_e32 v145, v17, v145
	v_mul_f32_e32 v146, v18, v146
	v_mul_f32_e32 v147, v19, v147
	v_cvt_pk_bf16_f32 v136, v140, v141
	v_cvt_pk_bf16_f32 v137, v142, v143
	v_cvt_pk_bf16_f32 v138, v144, v145
	v_cvt_pk_bf16_f32 v139, v146, v147
	global_store_dwordx4 v[128:129], v[136:139], off offset:256 sc1
	v_lshl_add_u64 v[128:129], v[128:129], 0, s[94:95]
	v_mul_f32_e32 v140, 0xbfb8aa3b, v12
	v_mul_f32_e32 v141, 0xbfb8aa3b, v13
	v_mul_f32_e32 v142, 0xbfb8aa3b, v14
	v_mul_f32_e32 v143, 0xbfb8aa3b, v15
	v_mul_f32_e32 v144, 0xbfb8aa3b, v8
	v_mul_f32_e32 v145, 0xbfb8aa3b, v9
	v_mul_f32_e32 v146, 0xbfb8aa3b, v10
	v_mul_f32_e32 v147, 0xbfb8aa3b, v11
	v_exp_f32_e32 v140, v140
	v_exp_f32_e32 v141, v141
	v_exp_f32_e32 v142, v142
	v_exp_f32_e32 v143, v143
	v_exp_f32_e32 v144, v144
	v_exp_f32_e32 v145, v145
	v_exp_f32_e32 v146, v146
	v_exp_f32_e32 v147, v147
	v_add_f32_e32 v140, 1.0, v140
	v_add_f32_e32 v141, 1.0, v141
	v_add_f32_e32 v142, 1.0, v142
	v_add_f32_e32 v143, 1.0, v143
	v_add_f32_e32 v144, 1.0, v144
	v_add_f32_e32 v145, 1.0, v145
	v_add_f32_e32 v146, 1.0, v146
	v_add_f32_e32 v147, 1.0, v147
	v_rcp_f32_e32 v140, v140
	v_rcp_f32_e32 v141, v141
	v_rcp_f32_e32 v142, v142
	v_rcp_f32_e32 v143, v143
	v_rcp_f32_e32 v144, v144
	v_rcp_f32_e32 v145, v145
	v_rcp_f32_e32 v146, v146
	v_rcp_f32_e32 v147, v147
	v_mul_f32_e32 v140, v12, v140
	v_mul_f32_e32 v141, v13, v141
	v_mul_f32_e32 v142, v14, v142
	v_mul_f32_e32 v143, v15, v143
	v_mul_f32_e32 v144, v8, v144
	v_mul_f32_e32 v145, v9, v145
	v_mul_f32_e32 v146, v10, v146
	v_mul_f32_e32 v147, v11, v147
	v_cvt_pk_bf16_f32 v132, v140, v141
	v_cvt_pk_bf16_f32 v133, v142, v143
	v_cvt_pk_bf16_f32 v134, v144, v145
	v_cvt_pk_bf16_f32 v135, v146, v147
	global_store_dwordx4 v[128:129], v[132:135], off sc1
	v_mul_f32_e32 v140, 0xbfb8aa3b, v4
	v_mul_f32_e32 v141, 0xbfb8aa3b, v5
	v_mul_f32_e32 v142, 0xbfb8aa3b, v6
	v_mul_f32_e32 v143, 0xbfb8aa3b, v7
	v_mul_f32_e32 v144, 0xbfb8aa3b, v0
	v_mul_f32_e32 v145, 0xbfb8aa3b, v1
	v_mul_f32_e32 v146, 0xbfb8aa3b, v2
	v_mul_f32_e32 v147, 0xbfb8aa3b, v3
	v_exp_f32_e32 v140, v140
	v_exp_f32_e32 v141, v141
	v_exp_f32_e32 v142, v142
	v_exp_f32_e32 v143, v143
	v_exp_f32_e32 v144, v144
	v_exp_f32_e32 v145, v145
	v_exp_f32_e32 v146, v146
	v_exp_f32_e32 v147, v147
	v_add_f32_e32 v140, 1.0, v140
	v_add_f32_e32 v141, 1.0, v141
	v_add_f32_e32 v142, 1.0, v142
	v_add_f32_e32 v143, 1.0, v143
	v_add_f32_e32 v144, 1.0, v144
	v_add_f32_e32 v145, 1.0, v145
	v_add_f32_e32 v146, 1.0, v146
	v_add_f32_e32 v147, 1.0, v147
	v_rcp_f32_e32 v140, v140
	v_rcp_f32_e32 v141, v141
	v_rcp_f32_e32 v142, v142
	v_rcp_f32_e32 v143, v143
	v_rcp_f32_e32 v144, v144
	v_rcp_f32_e32 v145, v145
	v_rcp_f32_e32 v146, v146
	v_rcp_f32_e32 v147, v147
	v_mul_f32_e32 v140, v4, v140
	v_mul_f32_e32 v141, v5, v141
	v_mul_f32_e32 v142, v6, v142
	v_mul_f32_e32 v143, v7, v143
	v_mul_f32_e32 v144, v0, v144
	v_mul_f32_e32 v145, v1, v145
	v_mul_f32_e32 v146, v2, v146
	v_mul_f32_e32 v147, v3, v147
	v_cvt_pk_bf16_f32 v136, v140, v141
	v_cvt_pk_bf16_f32 v137, v142, v143
	v_cvt_pk_bf16_f32 v138, v144, v145
	v_cvt_pk_bf16_f32 v139, v146, v147
	global_store_dwordx4 v[128:129], v[136:139], off offset:256 sc1
	s_branch .Lp1st_done
.Lp1st_sigmoid:
	v_mul_f32_e32 v140, 0xbfb8aa3b, v124
	v_mul_f32_e32 v141, 0xbfb8aa3b, v125
	v_mul_f32_e32 v142, 0xbfb8aa3b, v126
	v_mul_f32_e32 v143, 0xbfb8aa3b, v127
	v_mul_f32_e32 v144, 0xbfb8aa3b, v120
	v_mul_f32_e32 v145, 0xbfb8aa3b, v121
	v_mul_f32_e32 v146, 0xbfb8aa3b, v122
	v_mul_f32_e32 v147, 0xbfb8aa3b, v123
	v_exp_f32_e32 v140, v140
	v_exp_f32_e32 v141, v141
	v_exp_f32_e32 v142, v142
	v_exp_f32_e32 v143, v143
	v_exp_f32_e32 v144, v144
	v_exp_f32_e32 v145, v145
	v_exp_f32_e32 v146, v146
	v_exp_f32_e32 v147, v147
	v_add_f32_e32 v140, 1.0, v140
	v_add_f32_e32 v141, 1.0, v141
	v_add_f32_e32 v142, 1.0, v142
	v_add_f32_e32 v143, 1.0, v143
	v_add_f32_e32 v144, 1.0, v144
	v_add_f32_e32 v145, 1.0, v145
	v_add_f32_e32 v146, 1.0, v146
	v_add_f32_e32 v147, 1.0, v147
	v_rcp_f32_e32 v140, v140
	v_rcp_f32_e32 v141, v141
	v_rcp_f32_e32 v142, v142
	v_rcp_f32_e32 v143, v143
	v_rcp_f32_e32 v144, v144
	v_rcp_f32_e32 v145, v145
	v_rcp_f32_e32 v146, v146
	v_rcp_f32_e32 v147, v147
	s_nop 0
	v_cvt_pk_bf16_f32 v132, v140, v141
	v_cvt_pk_bf16_f32 v133, v142, v143
	v_cvt_pk_bf16_f32 v134, v144, v145
	v_cvt_pk_bf16_f32 v135, v146, v147
	global_store_dwordx4 v[128:129], v[132:135], off sc1
	v_mul_f32_e32 v140, 0xbfb8aa3b, v116
	v_mul_f32_e32 v141, 0xbfb8aa3b, v117
	v_mul_f32_e32 v142, 0xbfb8aa3b, v118
	v_mul_f32_e32 v143, 0xbfb8aa3b, v119
	v_mul_f32_e32 v144, 0xbfb8aa3b, v112
	v_mul_f32_e32 v145, 0xbfb8aa3b, v113
	v_mul_f32_e32 v146, 0xbfb8aa3b, v114
	v_mul_f32_e32 v147, 0xbfb8aa3b, v115
	v_exp_f32_e32 v140, v140
	v_exp_f32_e32 v141, v141
	v_exp_f32_e32 v142, v142
	v_exp_f32_e32 v143, v143
	v_exp_f32_e32 v144, v144
	v_exp_f32_e32 v145, v145
	v_exp_f32_e32 v146, v146
	v_exp_f32_e32 v147, v147
	v_add_f32_e32 v140, 1.0, v140
	v_add_f32_e32 v141, 1.0, v141
	v_add_f32_e32 v142, 1.0, v142
	v_add_f32_e32 v143, 1.0, v143
	v_add_f32_e32 v144, 1.0, v144
	v_add_f32_e32 v145, 1.0, v145
	v_add_f32_e32 v146, 1.0, v146
	v_add_f32_e32 v147, 1.0, v147
	v_rcp_f32_e32 v140, v140
	v_rcp_f32_e32 v141, v141
	v_rcp_f32_e32 v142, v142
	v_rcp_f32_e32 v143, v143
	v_rcp_f32_e32 v144, v144
	v_rcp_f32_e32 v145, v145
	v_rcp_f32_e32 v146, v146
	v_rcp_f32_e32 v147, v147
	s_nop 0
	v_cvt_pk_bf16_f32 v136, v140, v141
	v_cvt_pk_bf16_f32 v137, v142, v143
	v_cvt_pk_bf16_f32 v138, v144, v145
	v_cvt_pk_bf16_f32 v139, v146, v147
	global_store_dwordx4 v[128:129], v[136:139], off offset:256 sc1
	v_lshl_add_u64 v[128:129], v[128:129], 0, s[94:95]
	v_mul_f32_e32 v140, 0xbfb8aa3b, v108
	v_mul_f32_e32 v141, 0xbfb8aa3b, v109
	v_mul_f32_e32 v142, 0xbfb8aa3b, v110
	v_mul_f32_e32 v143, 0xbfb8aa3b, v111
	v_mul_f32_e32 v144, 0xbfb8aa3b, v104
	v_mul_f32_e32 v145, 0xbfb8aa3b, v105
	v_mul_f32_e32 v146, 0xbfb8aa3b, v106
	v_mul_f32_e32 v147, 0xbfb8aa3b, v107
	v_exp_f32_e32 v140, v140
	v_exp_f32_e32 v141, v141
	v_exp_f32_e32 v142, v142
	v_exp_f32_e32 v143, v143
	v_exp_f32_e32 v144, v144
	v_exp_f32_e32 v145, v145
	v_exp_f32_e32 v146, v146
	v_exp_f32_e32 v147, v147
	v_add_f32_e32 v140, 1.0, v140
	v_add_f32_e32 v141, 1.0, v141
	v_add_f32_e32 v142, 1.0, v142
	v_add_f32_e32 v143, 1.0, v143
	v_add_f32_e32 v144, 1.0, v144
	v_add_f32_e32 v145, 1.0, v145
	v_add_f32_e32 v146, 1.0, v146
	v_add_f32_e32 v147, 1.0, v147
	v_rcp_f32_e32 v140, v140
	v_rcp_f32_e32 v141, v141
	v_rcp_f32_e32 v142, v142
	v_rcp_f32_e32 v143, v143
	v_rcp_f32_e32 v144, v144
	v_rcp_f32_e32 v145, v145
	v_rcp_f32_e32 v146, v146
	v_rcp_f32_e32 v147, v147
	s_nop 0
	v_cvt_pk_bf16_f32 v132, v140, v141
	v_cvt_pk_bf16_f32 v133, v142, v143
	v_cvt_pk_bf16_f32 v134, v144, v145
	v_cvt_pk_bf16_f32 v135, v146, v147
	global_store_dwordx4 v[128:129], v[132:135], off sc1
	v_mul_f32_e32 v140, 0xbfb8aa3b, v100
	v_mul_f32_e32 v141, 0xbfb8aa3b, v101
	v_mul_f32_e32 v142, 0xbfb8aa3b, v102
	v_mul_f32_e32 v143, 0xbfb8aa3b, v103
	v_mul_f32_e32 v144, 0xbfb8aa3b, v96
	v_mul_f32_e32 v145, 0xbfb8aa3b, v97
	v_mul_f32_e32 v146, 0xbfb8aa3b, v98
	v_mul_f32_e32 v147, 0xbfb8aa3b, v99
	v_exp_f32_e32 v140, v140
	v_exp_f32_e32 v141, v141
	v_exp_f32_e32 v142, v142
	v_exp_f32_e32 v143, v143
	v_exp_f32_e32 v144, v144
	v_exp_f32_e32 v145, v145
	v_exp_f32_e32 v146, v146
	v_exp_f32_e32 v147, v147
	v_add_f32_e32 v140, 1.0, v140
	v_add_f32_e32 v141, 1.0, v141
	v_add_f32_e32 v142, 1.0, v142
	v_add_f32_e32 v143, 1.0, v143
	v_add_f32_e32 v144, 1.0, v144
	v_add_f32_e32 v145, 1.0, v145
	v_add_f32_e32 v146, 1.0, v146
	v_add_f32_e32 v147, 1.0, v147
	v_rcp_f32_e32 v140, v140
	v_rcp_f32_e32 v141, v141
	v_rcp_f32_e32 v142, v142
	v_rcp_f32_e32 v143, v143
	v_rcp_f32_e32 v144, v144
	v_rcp_f32_e32 v145, v145
	v_rcp_f32_e32 v146, v146
	v_rcp_f32_e32 v147, v147
	s_nop 0
	v_cvt_pk_bf16_f32 v136, v140, v141
	v_cvt_pk_bf16_f32 v137, v142, v143
	v_cvt_pk_bf16_f32 v138, v144, v145
	v_cvt_pk_bf16_f32 v139, v146, v147
	global_store_dwordx4 v[128:129], v[136:139], off offset:256 sc1
	v_lshl_add_u64 v[128:129], v[128:129], 0, s[94:95]
	v_mul_f32_e32 v140, 0xbfb8aa3b, v92
	v_mul_f32_e32 v141, 0xbfb8aa3b, v93
	v_mul_f32_e32 v142, 0xbfb8aa3b, v94
	v_mul_f32_e32 v143, 0xbfb8aa3b, v95
	v_mul_f32_e32 v144, 0xbfb8aa3b, v88
	v_mul_f32_e32 v145, 0xbfb8aa3b, v89
	v_mul_f32_e32 v146, 0xbfb8aa3b, v90
	v_mul_f32_e32 v147, 0xbfb8aa3b, v91
	v_exp_f32_e32 v140, v140
	v_exp_f32_e32 v141, v141
	v_exp_f32_e32 v142, v142
	v_exp_f32_e32 v143, v143
	v_exp_f32_e32 v144, v144
	v_exp_f32_e32 v145, v145
	v_exp_f32_e32 v146, v146
	v_exp_f32_e32 v147, v147
	v_add_f32_e32 v140, 1.0, v140
	v_add_f32_e32 v141, 1.0, v141
	v_add_f32_e32 v142, 1.0, v142
	v_add_f32_e32 v143, 1.0, v143
	v_add_f32_e32 v144, 1.0, v144
	v_add_f32_e32 v145, 1.0, v145
	v_add_f32_e32 v146, 1.0, v146
	v_add_f32_e32 v147, 1.0, v147
	v_rcp_f32_e32 v140, v140
	v_rcp_f32_e32 v141, v141
	v_rcp_f32_e32 v142, v142
	v_rcp_f32_e32 v143, v143
	v_rcp_f32_e32 v144, v144
	v_rcp_f32_e32 v145, v145
	v_rcp_f32_e32 v146, v146
	v_rcp_f32_e32 v147, v147
	s_nop 0
	v_cvt_pk_bf16_f32 v132, v140, v141
	v_cvt_pk_bf16_f32 v133, v142, v143
	v_cvt_pk_bf16_f32 v134, v144, v145
	v_cvt_pk_bf16_f32 v135, v146, v147
	global_store_dwordx4 v[128:129], v[132:135], off sc1
	v_mul_f32_e32 v140, 0xbfb8aa3b, v84
	v_mul_f32_e32 v141, 0xbfb8aa3b, v85
	v_mul_f32_e32 v142, 0xbfb8aa3b, v86
	v_mul_f32_e32 v143, 0xbfb8aa3b, v87
	v_mul_f32_e32 v144, 0xbfb8aa3b, v80
	v_mul_f32_e32 v145, 0xbfb8aa3b, v81
	v_mul_f32_e32 v146, 0xbfb8aa3b, v82
	v_mul_f32_e32 v147, 0xbfb8aa3b, v83
	v_exp_f32_e32 v140, v140
	v_exp_f32_e32 v141, v141
	v_exp_f32_e32 v142, v142
	v_exp_f32_e32 v143, v143
	v_exp_f32_e32 v144, v144
	v_exp_f32_e32 v145, v145
	v_exp_f32_e32 v146, v146
	v_exp_f32_e32 v147, v147
	v_add_f32_e32 v140, 1.0, v140
	v_add_f32_e32 v141, 1.0, v141
	v_add_f32_e32 v142, 1.0, v142
	v_add_f32_e32 v143, 1.0, v143
	v_add_f32_e32 v144, 1.0, v144
	v_add_f32_e32 v145, 1.0, v145
	v_add_f32_e32 v146, 1.0, v146
	v_add_f32_e32 v147, 1.0, v147
	v_rcp_f32_e32 v140, v140
	v_rcp_f32_e32 v141, v141
	v_rcp_f32_e32 v142, v142
	v_rcp_f32_e32 v143, v143
	v_rcp_f32_e32 v144, v144
	v_rcp_f32_e32 v145, v145
	v_rcp_f32_e32 v146, v146
	v_rcp_f32_e32 v147, v147
	s_nop 0
	v_cvt_pk_bf16_f32 v136, v140, v141
	v_cvt_pk_bf16_f32 v137, v142, v143
	v_cvt_pk_bf16_f32 v138, v144, v145
	v_cvt_pk_bf16_f32 v139, v146, v147
	global_store_dwordx4 v[128:129], v[136:139], off offset:256 sc1
	v_lshl_add_u64 v[128:129], v[128:129], 0, s[94:95]
	v_mul_f32_e32 v140, 0xbfb8aa3b, v76
	v_mul_f32_e32 v141, 0xbfb8aa3b, v77
	v_mul_f32_e32 v142, 0xbfb8aa3b, v78
	v_mul_f32_e32 v143, 0xbfb8aa3b, v79
	v_mul_f32_e32 v144, 0xbfb8aa3b, v72
	v_mul_f32_e32 v145, 0xbfb8aa3b, v73
	v_mul_f32_e32 v146, 0xbfb8aa3b, v74
	v_mul_f32_e32 v147, 0xbfb8aa3b, v75
	v_exp_f32_e32 v140, v140
	v_exp_f32_e32 v141, v141
	v_exp_f32_e32 v142, v142
	v_exp_f32_e32 v143, v143
	v_exp_f32_e32 v144, v144
	v_exp_f32_e32 v145, v145
	v_exp_f32_e32 v146, v146
	v_exp_f32_e32 v147, v147
	v_add_f32_e32 v140, 1.0, v140
	v_add_f32_e32 v141, 1.0, v141
	v_add_f32_e32 v142, 1.0, v142
	v_add_f32_e32 v143, 1.0, v143
	v_add_f32_e32 v144, 1.0, v144
	v_add_f32_e32 v145, 1.0, v145
	v_add_f32_e32 v146, 1.0, v146
	v_add_f32_e32 v147, 1.0, v147
	v_rcp_f32_e32 v140, v140
	v_rcp_f32_e32 v141, v141
	v_rcp_f32_e32 v142, v142
	v_rcp_f32_e32 v143, v143
	v_rcp_f32_e32 v144, v144
	v_rcp_f32_e32 v145, v145
	v_rcp_f32_e32 v146, v146
	v_rcp_f32_e32 v147, v147
	s_nop 0
	v_cvt_pk_bf16_f32 v132, v140, v141
	v_cvt_pk_bf16_f32 v133, v142, v143
	v_cvt_pk_bf16_f32 v134, v144, v145
	v_cvt_pk_bf16_f32 v135, v146, v147
	global_store_dwordx4 v[128:129], v[132:135], off sc1
	v_mul_f32_e32 v140, 0xbfb8aa3b, v68
	v_mul_f32_e32 v141, 0xbfb8aa3b, v69
	v_mul_f32_e32 v142, 0xbfb8aa3b, v70
	v_mul_f32_e32 v143, 0xbfb8aa3b, v71
	v_mul_f32_e32 v144, 0xbfb8aa3b, v64
	v_mul_f32_e32 v145, 0xbfb8aa3b, v65
	v_mul_f32_e32 v146, 0xbfb8aa3b, v66
	v_mul_f32_e32 v147, 0xbfb8aa3b, v67
	v_exp_f32_e32 v140, v140
	v_exp_f32_e32 v141, v141
	v_exp_f32_e32 v142, v142
	v_exp_f32_e32 v143, v143
	v_exp_f32_e32 v144, v144
	v_exp_f32_e32 v145, v145
	v_exp_f32_e32 v146, v146
	v_exp_f32_e32 v147, v147
	v_add_f32_e32 v140, 1.0, v140
	v_add_f32_e32 v141, 1.0, v141
	v_add_f32_e32 v142, 1.0, v142
	v_add_f32_e32 v143, 1.0, v143
	v_add_f32_e32 v144, 1.0, v144
	v_add_f32_e32 v145, 1.0, v145
	v_add_f32_e32 v146, 1.0, v146
	v_add_f32_e32 v147, 1.0, v147
	v_rcp_f32_e32 v140, v140
	v_rcp_f32_e32 v141, v141
	v_rcp_f32_e32 v142, v142
	v_rcp_f32_e32 v143, v143
	v_rcp_f32_e32 v144, v144
	v_rcp_f32_e32 v145, v145
	v_rcp_f32_e32 v146, v146
	v_rcp_f32_e32 v147, v147
	s_nop 0
	v_cvt_pk_bf16_f32 v136, v140, v141
	v_cvt_pk_bf16_f32 v137, v142, v143
	v_cvt_pk_bf16_f32 v138, v144, v145
	v_cvt_pk_bf16_f32 v139, v146, v147
	global_store_dwordx4 v[128:129], v[136:139], off offset:256 sc1
	v_lshl_add_u64 v[128:129], v[128:129], 0, s[96:97]
	v_mul_f32_e32 v140, 0xbfb8aa3b, v60
	v_mul_f32_e32 v141, 0xbfb8aa3b, v61
	v_mul_f32_e32 v142, 0xbfb8aa3b, v62
	v_mul_f32_e32 v143, 0xbfb8aa3b, v63
	v_mul_f32_e32 v144, 0xbfb8aa3b, v56
	v_mul_f32_e32 v145, 0xbfb8aa3b, v57
	v_mul_f32_e32 v146, 0xbfb8aa3b, v58
	v_mul_f32_e32 v147, 0xbfb8aa3b, v59
	v_exp_f32_e32 v140, v140
	v_exp_f32_e32 v141, v141
	v_exp_f32_e32 v142, v142
	v_exp_f32_e32 v143, v143
	v_exp_f32_e32 v144, v144
	v_exp_f32_e32 v145, v145
	v_exp_f32_e32 v146, v146
	v_exp_f32_e32 v147, v147
	v_add_f32_e32 v140, 1.0, v140
	v_add_f32_e32 v141, 1.0, v141
	v_add_f32_e32 v142, 1.0, v142
	v_add_f32_e32 v143, 1.0, v143
	v_add_f32_e32 v144, 1.0, v144
	v_add_f32_e32 v145, 1.0, v145
	v_add_f32_e32 v146, 1.0, v146
	v_add_f32_e32 v147, 1.0, v147
	v_rcp_f32_e32 v140, v140
	v_rcp_f32_e32 v141, v141
	v_rcp_f32_e32 v142, v142
	v_rcp_f32_e32 v143, v143
	v_rcp_f32_e32 v144, v144
	v_rcp_f32_e32 v145, v145
	v_rcp_f32_e32 v146, v146
	v_rcp_f32_e32 v147, v147
	s_nop 0
	v_cvt_pk_bf16_f32 v132, v140, v141
	v_cvt_pk_bf16_f32 v133, v142, v143
	v_cvt_pk_bf16_f32 v134, v144, v145
	v_cvt_pk_bf16_f32 v135, v146, v147
	global_store_dwordx4 v[128:129], v[132:135], off sc1
	v_mul_f32_e32 v140, 0xbfb8aa3b, v52
	v_mul_f32_e32 v141, 0xbfb8aa3b, v53
	v_mul_f32_e32 v142, 0xbfb8aa3b, v54
	v_mul_f32_e32 v143, 0xbfb8aa3b, v55
	v_mul_f32_e32 v144, 0xbfb8aa3b, v48
	v_mul_f32_e32 v145, 0xbfb8aa3b, v49
	v_mul_f32_e32 v146, 0xbfb8aa3b, v50
	v_mul_f32_e32 v147, 0xbfb8aa3b, v51
	v_exp_f32_e32 v140, v140
	v_exp_f32_e32 v141, v141
	v_exp_f32_e32 v142, v142
	v_exp_f32_e32 v143, v143
	v_exp_f32_e32 v144, v144
	v_exp_f32_e32 v145, v145
	v_exp_f32_e32 v146, v146
	v_exp_f32_e32 v147, v147
	v_add_f32_e32 v140, 1.0, v140
	v_add_f32_e32 v141, 1.0, v141
	v_add_f32_e32 v142, 1.0, v142
	v_add_f32_e32 v143, 1.0, v143
	v_add_f32_e32 v144, 1.0, v144
	v_add_f32_e32 v145, 1.0, v145
	v_add_f32_e32 v146, 1.0, v146
	v_add_f32_e32 v147, 1.0, v147
	v_rcp_f32_e32 v140, v140
	v_rcp_f32_e32 v141, v141
	v_rcp_f32_e32 v142, v142
	v_rcp_f32_e32 v143, v143
	v_rcp_f32_e32 v144, v144
	v_rcp_f32_e32 v145, v145
	v_rcp_f32_e32 v146, v146
	v_rcp_f32_e32 v147, v147
	s_nop 0
	v_cvt_pk_bf16_f32 v136, v140, v141
	v_cvt_pk_bf16_f32 v137, v142, v143
	v_cvt_pk_bf16_f32 v138, v144, v145
	v_cvt_pk_bf16_f32 v139, v146, v147
	global_store_dwordx4 v[128:129], v[136:139], off offset:256 sc1
	v_lshl_add_u64 v[128:129], v[128:129], 0, s[94:95]
	v_mul_f32_e32 v140, 0xbfb8aa3b, v44
	v_mul_f32_e32 v141, 0xbfb8aa3b, v45
	v_mul_f32_e32 v142, 0xbfb8aa3b, v46
	v_mul_f32_e32 v143, 0xbfb8aa3b, v47
	v_mul_f32_e32 v144, 0xbfb8aa3b, v40
	v_mul_f32_e32 v145, 0xbfb8aa3b, v41
	v_mul_f32_e32 v146, 0xbfb8aa3b, v42
	v_mul_f32_e32 v147, 0xbfb8aa3b, v43
	v_exp_f32_e32 v140, v140
	v_exp_f32_e32 v141, v141
	v_exp_f32_e32 v142, v142
	v_exp_f32_e32 v143, v143
	v_exp_f32_e32 v144, v144
	v_exp_f32_e32 v145, v145
	v_exp_f32_e32 v146, v146
	v_exp_f32_e32 v147, v147
	v_add_f32_e32 v140, 1.0, v140
	v_add_f32_e32 v141, 1.0, v141
	v_add_f32_e32 v142, 1.0, v142
	v_add_f32_e32 v143, 1.0, v143
	v_add_f32_e32 v144, 1.0, v144
	v_add_f32_e32 v145, 1.0, v145
	v_add_f32_e32 v146, 1.0, v146
	v_add_f32_e32 v147, 1.0, v147
	v_rcp_f32_e32 v140, v140
	v_rcp_f32_e32 v141, v141
	v_rcp_f32_e32 v142, v142
	v_rcp_f32_e32 v143, v143
	v_rcp_f32_e32 v144, v144
	v_rcp_f32_e32 v145, v145
	v_rcp_f32_e32 v146, v146
	v_rcp_f32_e32 v147, v147
	s_nop 0
	v_cvt_pk_bf16_f32 v132, v140, v141
	v_cvt_pk_bf16_f32 v133, v142, v143
	v_cvt_pk_bf16_f32 v134, v144, v145
	v_cvt_pk_bf16_f32 v135, v146, v147
	global_store_dwordx4 v[128:129], v[132:135], off sc1
	v_mul_f32_e32 v140, 0xbfb8aa3b, v36
	v_mul_f32_e32 v141, 0xbfb8aa3b, v37
	v_mul_f32_e32 v142, 0xbfb8aa3b, v38
	v_mul_f32_e32 v143, 0xbfb8aa3b, v39
	v_mul_f32_e32 v144, 0xbfb8aa3b, v32
	v_mul_f32_e32 v145, 0xbfb8aa3b, v33
	v_mul_f32_e32 v146, 0xbfb8aa3b, v34
	v_mul_f32_e32 v147, 0xbfb8aa3b, v35
	v_exp_f32_e32 v140, v140
	v_exp_f32_e32 v141, v141
	v_exp_f32_e32 v142, v142
	v_exp_f32_e32 v143, v143
	v_exp_f32_e32 v144, v144
	v_exp_f32_e32 v145, v145
	v_exp_f32_e32 v146, v146
	v_exp_f32_e32 v147, v147
	v_add_f32_e32 v140, 1.0, v140
	v_add_f32_e32 v141, 1.0, v141
	v_add_f32_e32 v142, 1.0, v142
	v_add_f32_e32 v143, 1.0, v143
	v_add_f32_e32 v144, 1.0, v144
	v_add_f32_e32 v145, 1.0, v145
	v_add_f32_e32 v146, 1.0, v146
	v_add_f32_e32 v147, 1.0, v147
	v_rcp_f32_e32 v140, v140
	v_rcp_f32_e32 v141, v141
	v_rcp_f32_e32 v142, v142
	v_rcp_f32_e32 v143, v143
	v_rcp_f32_e32 v144, v144
	v_rcp_f32_e32 v145, v145
	v_rcp_f32_e32 v146, v146
	v_rcp_f32_e32 v147, v147
	s_nop 0
	v_cvt_pk_bf16_f32 v136, v140, v141
	v_cvt_pk_bf16_f32 v137, v142, v143
	v_cvt_pk_bf16_f32 v138, v144, v145
	v_cvt_pk_bf16_f32 v139, v146, v147
	global_store_dwordx4 v[128:129], v[136:139], off offset:256 sc1
	v_lshl_add_u64 v[128:129], v[128:129], 0, s[94:95]
	v_mul_f32_e32 v140, 0xbfb8aa3b, v28
	v_mul_f32_e32 v141, 0xbfb8aa3b, v29
	v_mul_f32_e32 v142, 0xbfb8aa3b, v30
	v_mul_f32_e32 v143, 0xbfb8aa3b, v31
	v_mul_f32_e32 v144, 0xbfb8aa3b, v24
	v_mul_f32_e32 v145, 0xbfb8aa3b, v25
	v_mul_f32_e32 v146, 0xbfb8aa3b, v26
	v_mul_f32_e32 v147, 0xbfb8aa3b, v27
	v_exp_f32_e32 v140, v140
	v_exp_f32_e32 v141, v141
	v_exp_f32_e32 v142, v142
	v_exp_f32_e32 v143, v143
	v_exp_f32_e32 v144, v144
	v_exp_f32_e32 v145, v145
	v_exp_f32_e32 v146, v146
	v_exp_f32_e32 v147, v147
	v_add_f32_e32 v140, 1.0, v140
	v_add_f32_e32 v141, 1.0, v141
	v_add_f32_e32 v142, 1.0, v142
	v_add_f32_e32 v143, 1.0, v143
	v_add_f32_e32 v144, 1.0, v144
	v_add_f32_e32 v145, 1.0, v145
	v_add_f32_e32 v146, 1.0, v146
	v_add_f32_e32 v147, 1.0, v147
	v_rcp_f32_e32 v140, v140
	v_rcp_f32_e32 v141, v141
	v_rcp_f32_e32 v142, v142
	v_rcp_f32_e32 v143, v143
	v_rcp_f32_e32 v144, v144
	v_rcp_f32_e32 v145, v145
	v_rcp_f32_e32 v146, v146
	v_rcp_f32_e32 v147, v147
	s_nop 0
	v_cvt_pk_bf16_f32 v132, v140, v141
	v_cvt_pk_bf16_f32 v133, v142, v143
	v_cvt_pk_bf16_f32 v134, v144, v145
	v_cvt_pk_bf16_f32 v135, v146, v147
	global_store_dwordx4 v[128:129], v[132:135], off sc1
	v_mul_f32_e32 v140, 0xbfb8aa3b, v20
	v_mul_f32_e32 v141, 0xbfb8aa3b, v21
	v_mul_f32_e32 v142, 0xbfb8aa3b, v22
	v_mul_f32_e32 v143, 0xbfb8aa3b, v23
	v_mul_f32_e32 v144, 0xbfb8aa3b, v16
	v_mul_f32_e32 v145, 0xbfb8aa3b, v17
	v_mul_f32_e32 v146, 0xbfb8aa3b, v18
	v_mul_f32_e32 v147, 0xbfb8aa3b, v19
	v_exp_f32_e32 v140, v140
	v_exp_f32_e32 v141, v141
	v_exp_f32_e32 v142, v142
	v_exp_f32_e32 v143, v143
	v_exp_f32_e32 v144, v144
	v_exp_f32_e32 v145, v145
	v_exp_f32_e32 v146, v146
	v_exp_f32_e32 v147, v147
	v_add_f32_e32 v140, 1.0, v140
	v_add_f32_e32 v141, 1.0, v141
	v_add_f32_e32 v142, 1.0, v142
	v_add_f32_e32 v143, 1.0, v143
	v_add_f32_e32 v144, 1.0, v144
	v_add_f32_e32 v145, 1.0, v145
	v_add_f32_e32 v146, 1.0, v146
	v_add_f32_e32 v147, 1.0, v147
	v_rcp_f32_e32 v140, v140
	v_rcp_f32_e32 v141, v141
	v_rcp_f32_e32 v142, v142
	v_rcp_f32_e32 v143, v143
	v_rcp_f32_e32 v144, v144
	v_rcp_f32_e32 v145, v145
	v_rcp_f32_e32 v146, v146
	v_rcp_f32_e32 v147, v147
	s_nop 0
	v_cvt_pk_bf16_f32 v136, v140, v141
	v_cvt_pk_bf16_f32 v137, v142, v143
	v_cvt_pk_bf16_f32 v138, v144, v145
	v_cvt_pk_bf16_f32 v139, v146, v147
	global_store_dwordx4 v[128:129], v[136:139], off offset:256 sc1
	v_lshl_add_u64 v[128:129], v[128:129], 0, s[94:95]
	v_mul_f32_e32 v140, 0xbfb8aa3b, v12
	v_mul_f32_e32 v141, 0xbfb8aa3b, v13
	v_mul_f32_e32 v142, 0xbfb8aa3b, v14
	v_mul_f32_e32 v143, 0xbfb8aa3b, v15
	v_mul_f32_e32 v144, 0xbfb8aa3b, v8
	v_mul_f32_e32 v145, 0xbfb8aa3b, v9
	v_mul_f32_e32 v146, 0xbfb8aa3b, v10
	v_mul_f32_e32 v147, 0xbfb8aa3b, v11
	v_exp_f32_e32 v140, v140
	v_exp_f32_e32 v141, v141
	v_exp_f32_e32 v142, v142
	v_exp_f32_e32 v143, v143
	v_exp_f32_e32 v144, v144
	v_exp_f32_e32 v145, v145
	v_exp_f32_e32 v146, v146
	v_exp_f32_e32 v147, v147
	v_add_f32_e32 v140, 1.0, v140
	v_add_f32_e32 v141, 1.0, v141
	v_add_f32_e32 v142, 1.0, v142
	v_add_f32_e32 v143, 1.0, v143
	v_add_f32_e32 v144, 1.0, v144
	v_add_f32_e32 v145, 1.0, v145
	v_add_f32_e32 v146, 1.0, v146
	v_add_f32_e32 v147, 1.0, v147
	v_rcp_f32_e32 v140, v140
	v_rcp_f32_e32 v141, v141
	v_rcp_f32_e32 v142, v142
	v_rcp_f32_e32 v143, v143
	v_rcp_f32_e32 v144, v144
	v_rcp_f32_e32 v145, v145
	v_rcp_f32_e32 v146, v146
	v_rcp_f32_e32 v147, v147
	s_nop 0
	v_cvt_pk_bf16_f32 v132, v140, v141
	v_cvt_pk_bf16_f32 v133, v142, v143
	v_cvt_pk_bf16_f32 v134, v144, v145
	v_cvt_pk_bf16_f32 v135, v146, v147
	global_store_dwordx4 v[128:129], v[132:135], off sc1
	v_mul_f32_e32 v140, 0xbfb8aa3b, v4
	v_mul_f32_e32 v141, 0xbfb8aa3b, v5
	v_mul_f32_e32 v142, 0xbfb8aa3b, v6
	v_mul_f32_e32 v143, 0xbfb8aa3b, v7
	v_mul_f32_e32 v144, 0xbfb8aa3b, v0
	v_mul_f32_e32 v145, 0xbfb8aa3b, v1
	v_mul_f32_e32 v146, 0xbfb8aa3b, v2
	v_mul_f32_e32 v147, 0xbfb8aa3b, v3
	v_exp_f32_e32 v140, v140
	v_exp_f32_e32 v141, v141
	v_exp_f32_e32 v142, v142
	v_exp_f32_e32 v143, v143
	v_exp_f32_e32 v144, v144
	v_exp_f32_e32 v145, v145
	v_exp_f32_e32 v146, v146
	v_exp_f32_e32 v147, v147
	v_add_f32_e32 v140, 1.0, v140
	v_add_f32_e32 v141, 1.0, v141
	v_add_f32_e32 v142, 1.0, v142
	v_add_f32_e32 v143, 1.0, v143
	v_add_f32_e32 v144, 1.0, v144
	v_add_f32_e32 v145, 1.0, v145
	v_add_f32_e32 v146, 1.0, v146
	v_add_f32_e32 v147, 1.0, v147
	v_rcp_f32_e32 v140, v140
	v_rcp_f32_e32 v141, v141
	v_rcp_f32_e32 v142, v142
	v_rcp_f32_e32 v143, v143
	v_rcp_f32_e32 v144, v144
	v_rcp_f32_e32 v145, v145
	v_rcp_f32_e32 v146, v146
	v_rcp_f32_e32 v147, v147
	s_nop 0
	v_cvt_pk_bf16_f32 v136, v140, v141
	v_cvt_pk_bf16_f32 v137, v142, v143
	v_cvt_pk_bf16_f32 v138, v144, v145
	v_cvt_pk_bf16_f32 v139, v146, v147
	global_store_dwordx4 v[128:129], v[136:139], off offset:256 sc1
.Lp1st_done:
	s_andn2_b64 vcc, exec, s[8:9]
	s_mov_b64 s[8:9], -1
	s_cbranch_vccnz .LBB0_131
	s_andn2_b64 vcc, exec, s[16:17]
	s_cbranch_vccnz .LBB0_130
	s_barrier
	s_branch .LBB0_130

.LBB0_371:
	s_or_b64 exec, exec, s[6:7]
	s_lshl_b32 s6, s81, 24
	s_and_b32 s6, s6, 0x1000000
	s_waitcnt lgkmcnt(0)
	s_add_u32 s6, s74, s6
	ds_read_b128 v[2:5], v0 offset:128
	ds_read_b128 v[6:9], v0 offset:160
	s_addc_u32 s7, s75, 0
	s_add_u32 s6, s6, s36
	s_addc_u32 s7, s7, s37
	s_add_u32 s8, s6, s51
	s_addc_u32 s9, s7, 0
	s_waitcnt lgkmcnt(1)
	v_rcp_f32_e32 v12, v2
	v_rcp_f32_e32 v13, v3
	v_rcp_f32_e32 v14, v4
	v_rcp_f32_e32 v15, v5
	ds_read_b128 v[2:5], v0 offset:192
	s_lshl_b64 s[6:7], s[38:39], 1
	s_add_u32 s6, s8, s6
	s_addc_u32 s7, s9, s7
	s_lshl_b32 s8, s50, 12
	s_waitcnt lgkmcnt(1)
	v_rcp_f32_e32 v80, v6
	v_rcp_f32_e32 v81, v7
	v_rcp_f32_e32 v82, v8
	v_rcp_f32_e32 v83, v9
	ds_read_b128 v[6:9], v0 offset:224
	s_add_i32 s8, s8, 0
	v_lshlrev_b32_e32 v0, 1, v240
	s_add_i32 s8, s8, 0x12800
	v_and_b32_e32 v0, 0x70, v0
	s_waitcnt lgkmcnt(1)
	v_rcp_f32_e32 v84, v2
	v_lshlrev_b32_e32 v2, 1, v239
	v_add_u32_e32 v93, s8, v0
	v_lshl_add_u64 v[10:11], s[6:7], 0, v[0:1]
	v_lshlrev_b32_e32 v0, 9, v237
	v_add3_u32 v95, s8, v2, v0
	v_mul_f32_e32 v0, v64, v12
	v_cvt_pk_bf16_f32 v0, v0, s0
	ds_write_b16 v95, v0
	v_mul_f32_e32 v0, v48, v12
	v_cvt_pk_bf16_f32 v0, v0, s0
	ds_write_b16 v95, v0 offset:64
	v_mul_f32_e32 v0, v65, v13
	v_cvt_pk_bf16_f32 v0, v0, s0
	ds_write_b16 v95, v0 offset:128
	v_mul_f32_e32 v0, v49, v13
	v_cvt_pk_bf16_f32 v0, v0, s0
	ds_write_b16 v95, v0 offset:192
	v_mul_f32_e32 v0, v66, v14
	v_cvt_pk_bf16_f32 v0, v0, s0
	ds_write_b16 v95, v0 offset:256
	v_mul_f32_e32 v0, v50, v14
	v_cvt_pk_bf16_f32 v0, v0, s0
	ds_write_b16 v95, v0 offset:320
	v_mul_f32_e32 v0, v67, v15
	v_cvt_pk_bf16_f32 v0, v0, s0
	ds_write_b16 v95, v0 offset:384
	v_mul_f32_e32 v0, v51, v15
	v_cvt_pk_bf16_f32 v0, v0, s0
	ds_write_b16 v95, v0 offset:448
	v_mul_f32_e32 v0, v68, v80
	v_cvt_pk_bf16_f32 v0, v0, s0
	ds_write_b16 v95, v0 offset:1024
	v_mul_f32_e32 v0, v52, v80
	v_cvt_pk_bf16_f32 v0, v0, s0
	ds_write_b16 v95, v0 offset:1088
	v_mul_f32_e32 v0, v69, v81
	v_cvt_pk_bf16_f32 v0, v0, s0
	ds_write_b16 v95, v0 offset:1152
	v_mul_f32_e32 v0, v53, v81
	v_cvt_pk_bf16_f32 v0, v0, s0
	ds_write_b16 v95, v0 offset:1216
	v_mul_f32_e32 v0, v70, v82
	v_cvt_pk_bf16_f32 v0, v0, s0
	ds_write_b16 v95, v0 offset:1280
	v_mul_f32_e32 v0, v54, v82
	v_cvt_pk_bf16_f32 v0, v0, s0
	ds_write_b16 v95, v0 offset:1344
	v_mul_f32_e32 v0, v71, v83
	v_cvt_pk_bf16_f32 v0, v0, s0
	ds_write_b16 v95, v0 offset:1408
	v_mul_f32_e32 v0, v55, v83
	v_cvt_pk_bf16_f32 v0, v0, s0
	v_rcp_f32_e32 v85, v3
	ds_write_b16 v95, v0 offset:1472
	v_mul_f32_e32 v0, v72, v84
	v_cvt_pk_bf16_f32 v0, v0, s0
	ds_write_b16 v95, v0 offset:2048
	v_mul_f32_e32 v0, v56, v84
	v_cvt_pk_bf16_f32 v0, v0, s0
	v_rcp_f32_e32 v86, v4
	ds_write_b16 v95, v0 offset:2112
	v_mul_f32_e32 v0, v73, v85
	v_cvt_pk_bf16_f32 v0, v0, s0
	ds_write_b16 v95, v0 offset:2176
	v_mul_f32_e32 v0, v57, v85
	v_cvt_pk_bf16_f32 v0, v0, s0
	v_rcp_f32_e32 v87, v5
	ds_write_b16 v95, v0 offset:2240
	v_mul_f32_e32 v0, v74, v86
	v_cvt_pk_bf16_f32 v0, v0, s0
	ds_write_b16 v95, v0 offset:2304
	v_mul_f32_e32 v0, v58, v86
	v_cvt_pk_bf16_f32 v0, v0, s0
	s_waitcnt lgkmcnt(14)
	v_rcp_f32_e32 v88, v6
	ds_write_b16 v95, v0 offset:2368
	v_mul_f32_e32 v0, v75, v87
	v_cvt_pk_bf16_f32 v0, v0, s0
	ds_write_b16 v95, v0 offset:2432
	v_mul_f32_e32 v0, v59, v87
	v_cvt_pk_bf16_f32 v0, v0, s0
	v_rcp_f32_e32 v89, v7
	ds_write_b16 v95, v0 offset:2496
	v_mul_f32_e32 v0, v76, v88
	v_cvt_pk_bf16_f32 v0, v0, s0
	ds_write_b16 v95, v0 offset:3072
	v_mul_f32_e32 v0, v60, v88
	v_cvt_pk_bf16_f32 v0, v0, s0
	v_rcp_f32_e32 v90, v8
	ds_write_b16 v95, v0 offset:3136
	v_mul_f32_e32 v0, v77, v89
	v_cvt_pk_bf16_f32 v0, v0, s0
	ds_write_b16 v95, v0 offset:3200
	v_mul_f32_e32 v0, v61, v89
	v_cvt_pk_bf16_f32 v0, v0, s0
	v_rcp_f32_e32 v91, v9
	ds_write_b16 v95, v0 offset:3264
	v_mul_f32_e32 v0, v78, v90
	v_cvt_pk_bf16_f32 v0, v0, s0
	ds_write_b16 v95, v0 offset:3328
	v_mul_f32_e32 v0, v62, v90
	v_cvt_pk_bf16_f32 v0, v0, s0
	ds_write_b16 v95, v0 offset:3392
	v_mul_f32_e32 v0, v79, v91
	v_cvt_pk_bf16_f32 v0, v0, s0
	ds_write_b16 v95, v0 offset:3456
	v_mul_f32_e32 v0, v63, v91
	v_lshrrev_b32_e32 v92, 3, v238
	v_cvt_pk_bf16_f32 v0, v0, s0
	ds_write_b16 v95, v0 offset:3520
	v_or_b32_e32 v50, 8, v92
	v_lshl_add_u32 v94, v92, 7, v93
	s_waitcnt lgkmcnt(0)
	v_lshl_add_u32 v56, v50, 7, v93
	ds_read_b128 v[2:5], v94
	ds_read_b128 v[6:9], v56
	v_lshlrev_b32_e32 v0, 10, v92
	v_lshl_add_u64 v[48:49], v[10:11], 0, v[0:1]
	v_lshlrev_b32_e32 v0, 10, v50
	v_lshl_add_u64 v[50:51], v[10:11], 0, v[0:1]
	v_or_b32_e32 v0, 16, v92
	v_or_b32_e32 v54, 24, v92
	v_lshl_add_u32 v57, v0, 7, v93
	v_lshl_add_u32 v58, v54, 7, v93
	s_waitcnt lgkmcnt(1)
	global_store_dwordx4 v[48:49], v[2:5], off sc1
	ds_read_b128 v[2:5], v57
	s_waitcnt lgkmcnt(1)
	global_store_dwordx4 v[50:51], v[6:9], off sc1
	ds_read_b128 v[6:9], v58
	v_lshlrev_b32_e32 v0, 10, v0
	v_lshl_add_u64 v[52:53], v[10:11], 0, v[0:1]
	v_lshlrev_b32_e32 v0, 10, v54
	v_lshl_add_u64 v[54:55], v[10:11], 0, v[0:1]
	v_mul_f32_e32 v0, v32, v12
	s_waitcnt lgkmcnt(1)
	global_store_dwordx4 v[52:53], v[2:5], off sc1
	s_waitcnt lgkmcnt(0)
	global_store_dwordx4 v[54:55], v[6:9], off sc1
	v_cvt_pk_bf16_f32 v0, v0, s0
	s_waitcnt lgkmcnt(0)
	ds_write_b16 v95, v0
	v_mul_f32_e32 v0, v16, v12
	v_cvt_pk_bf16_f32 v0, v0, s0
	ds_write_b16 v95, v0 offset:64
	v_mul_f32_e32 v0, v33, v13
	v_cvt_pk_bf16_f32 v0, v0, s0
	ds_write_b16 v95, v0 offset:128
	v_mul_f32_e32 v0, v17, v13
	v_cvt_pk_bf16_f32 v0, v0, s0
	ds_write_b16 v95, v0 offset:192
	v_mul_f32_e32 v0, v34, v14
	v_cvt_pk_bf16_f32 v0, v0, s0
	ds_write_b16 v95, v0 offset:256
	v_mul_f32_e32 v0, v18, v14
	v_cvt_pk_bf16_f32 v0, v0, s0
	ds_write_b16 v95, v0 offset:320
	v_mul_f32_e32 v0, v35, v15
	v_cvt_pk_bf16_f32 v0, v0, s0
	ds_write_b16 v95, v0 offset:384
	v_mul_f32_e32 v0, v19, v15
	v_cvt_pk_bf16_f32 v0, v0, s0
	ds_write_b16 v95, v0 offset:448
	v_mul_f32_e32 v0, v36, v80
	v_cvt_pk_bf16_f32 v0, v0, s0
	ds_write_b16 v95, v0 offset:1024
	v_mul_f32_e32 v0, v20, v80
	v_cvt_pk_bf16_f32 v0, v0, s0
	ds_write_b16 v95, v0 offset:1088
	v_mul_f32_e32 v0, v37, v81
	v_cvt_pk_bf16_f32 v0, v0, s0
	ds_write_b16 v95, v0 offset:1152
	v_mul_f32_e32 v0, v21, v81
	v_cvt_pk_bf16_f32 v0, v0, s0
	ds_write_b16 v95, v0 offset:1216
	v_mul_f32_e32 v0, v38, v82
	v_cvt_pk_bf16_f32 v0, v0, s0
	ds_write_b16 v95, v0 offset:1280
	v_mul_f32_e32 v0, v22, v82
	v_cvt_pk_bf16_f32 v0, v0, s0
	ds_write_b16 v95, v0 offset:1344
	v_mul_f32_e32 v0, v39, v83
	v_cvt_pk_bf16_f32 v0, v0, s0
	ds_write_b16 v95, v0 offset:1408
	v_mul_f32_e32 v0, v23, v83
	v_cvt_pk_bf16_f32 v0, v0, s0
	ds_write_b16 v95, v0 offset:1472
	v_mul_f32_e32 v0, v40, v84
	v_cvt_pk_bf16_f32 v0, v0, s0
	ds_write_b16 v95, v0 offset:2048
	v_mul_f32_e32 v0, v24, v84
	v_cvt_pk_bf16_f32 v0, v0, s0
	ds_write_b16 v95, v0 offset:2112
	v_mul_f32_e32 v0, v41, v85
	v_cvt_pk_bf16_f32 v0, v0, s0
	ds_write_b16 v95, v0 offset:2176
	v_mul_f32_e32 v0, v25, v85
	v_cvt_pk_bf16_f32 v0, v0, s0
	ds_write_b16 v95, v0 offset:2240
	v_mul_f32_e32 v0, v42, v86
	v_cvt_pk_bf16_f32 v0, v0, s0
	ds_write_b16 v95, v0 offset:2304
	v_mul_f32_e32 v0, v26, v86
	v_cvt_pk_bf16_f32 v0, v0, s0
	ds_write_b16 v95, v0 offset:2368
	v_mul_f32_e32 v0, v43, v87
	v_cvt_pk_bf16_f32 v0, v0, s0
	ds_write_b16 v95, v0 offset:2432
	v_mul_f32_e32 v0, v27, v87
	v_cvt_pk_bf16_f32 v0, v0, s0
	ds_write_b16 v95, v0 offset:2496
	v_mul_f32_e32 v0, v44, v88
	v_cvt_pk_bf16_f32 v0, v0, s0
	ds_write_b16 v95, v0 offset:3072
	v_mul_f32_e32 v0, v28, v88
	v_cvt_pk_bf16_f32 v0, v0, s0
	ds_write_b16 v95, v0 offset:3136
	v_mul_f32_e32 v0, v45, v89
	v_cvt_pk_bf16_f32 v0, v0, s0
	ds_write_b16 v95, v0 offset:3200
	v_mul_f32_e32 v0, v29, v89
	v_cvt_pk_bf16_f32 v0, v0, s0
	ds_write_b16 v95, v0 offset:3264
	v_mul_f32_e32 v0, v46, v90
	v_cvt_pk_bf16_f32 v0, v0, s0
	ds_write_b16 v95, v0 offset:3328
	v_mul_f32_e32 v0, v30, v90
	v_cvt_pk_bf16_f32 v0, v0, s0
	ds_write_b16 v95, v0 offset:3392
	v_mul_f32_e32 v0, v47, v91
	v_cvt_pk_bf16_f32 v0, v0, s0
	ds_write_b16 v95, v0 offset:3456
	v_mul_f32_e32 v0, v31, v91
	v_cvt_pk_bf16_f32 v0, v0, s0
	ds_write_b16 v95, v0 offset:3520
	s_waitcnt lgkmcnt(0)
	ds_read_b128 v[2:5], v94
	ds_read_b128 v[6:9], v56
	ds_read_b128 v[10:13], v57
	ds_read_b128 v[14:17], v58
	s_waitcnt lgkmcnt(3)
	global_store_dwordx4 v[48:49], v[2:5], off offset:128 sc1
	s_waitcnt lgkmcnt(2)
	global_store_dwordx4 v[50:51], v[6:9], off offset:128 sc1
	s_waitcnt lgkmcnt(1)
	global_store_dwordx4 v[52:53], v[10:13], off offset:128 sc1
	s_waitcnt lgkmcnt(0)
	global_store_dwordx4 v[54:55], v[14:17], off offset:128 sc1
	s_waitcnt lgkmcnt(0)
	s_waitcnt lgkmcnt(0)
	s_barrier
	s_mov_b32 s83, 0

.LBB0_477:
	v_add_f32_e32 v68, v50, v51
	v_add_f32_e32 v68, v52, v68
	v_add_f32_e32 v68, v53, v68
	v_add_f32_e32 v68, v54, v68
	v_add_f32_e32 v68, v55, v68
	v_add_f32_e32 v68, v56, v68
	v_add_f32_e32 v68, v57, v68
	v_add_f32_e32 v68, v58, v68
	v_add_f32_e32 v68, v59, v68
	v_add_f32_e32 v68, v60, v68
	v_add_f32_e32 v68, v61, v68
	v_add_f32_e32 v68, v62, v68
	v_add_f32_e32 v68, v63, v68
	v_add_f32_e32 v68, v64, v68
	v_add_f32_e32 v68, v65, v68
	v_add_f32_e32 v68, v34, v68
	v_add_f32_e32 v68, v35, v68
	v_add_f32_e32 v68, v36, v68
	v_add_f32_e32 v68, v37, v68
	v_add_f32_e32 v68, v38, v68
	v_add_f32_e32 v68, v39, v68
	v_add_f32_e32 v68, v40, v68
	v_add_f32_e32 v68, v41, v68
	v_add_f32_e32 v68, v42, v68
	v_add_f32_e32 v68, v43, v68
	v_add_f32_e32 v68, v44, v68
	v_add_f32_e32 v68, v45, v68
	v_add_f32_e32 v68, v46, v68
	v_add_f32_e32 v68, v47, v68
	s_cmp_lg_u32 0, -1
	v_add_f32_e32 v68, v48, v68
	s_cselect_b32 s6, 0, 0
	v_add_f32_e32 v68, v49, v68
	s_addk_i32 s6, 0x6000
	v_add_f32_e32 v0, v0, v68
	v_cvt_pk_bf16_f32 v34, v34, v35
	v_add3_u32 v67, v217, s6, v214
	v_cvt_pk_bf16_f32 v50, v50, v51
	v_cvt_pk_bf16_f32 v51, v52, v53
	v_cvt_pk_bf16_f32 v52, v54, v55
	v_cvt_pk_bf16_f32 v53, v56, v57
	v_cvt_pk_bf16_f32 v54, v58, v59
	v_cvt_pk_bf16_f32 v55, v60, v61
	v_cvt_pk_bf16_f32 v56, v62, v63
	v_cvt_pk_bf16_f32 v57, v64, v65
	v_cvt_pk_bf16_f32 v35, v36, v37
	v_cvt_pk_bf16_f32 v36, v38, v39
	v_cvt_pk_bf16_f32 v37, v40, v41
	v_cvt_pk_bf16_f32 v38, v42, v43
	v_cvt_pk_bf16_f32 v39, v44, v45
	v_cvt_pk_bf16_f32 v40, v46, v47
	v_cvt_pk_bf16_f32 v41, v48, v49
	v_add3_u32 v67, v67, v215, s89
	ds_read_b64_tr_b16 v[42:43],v67 offset:0
	ds_read_b64_tr_b16 v[44:45],v67 offset:512
	ds_read_b64_tr_b16 v[46:47],v67 offset:1024
	ds_read_b64_tr_b16 v[48:49],v67 offset:1536
	ds_read_b64_tr_b16 v[58:59],v67 offset:2048
	ds_read_b64_tr_b16 v[60:61],v67 offset:2560
	ds_read_b64_tr_b16 v[62:63],v67 offset:3072
	ds_read_b64_tr_b16 v[64:65],v67 offset:3584
	s_waitcnt lgkmcnt(0)
	s_nop 0
	v_mfma_f32_32x32x16_bf16 v[18:33], v[50:53], v[42:45], v[18:33]
	ds_read_b64_tr_b16 v[42:43],v67 offset:4096
	ds_read_b64_tr_b16 v[44:45],v67 offset:4608
	v_mfma_f32_32x32x16_bf16 v[18:33], v[54:57], v[46:49], v[18:33]
	ds_read_b64_tr_b16 v[46:47],v67 offset:5120
	ds_read_b64_tr_b16 v[48:49],v67 offset:5632
	v_mfma_f32_32x32x16_bf16 v[18:33], v[34:37], v[58:61], v[18:33]
	ds_read_b64_tr_b16 v[58:59],v67 offset:6144
	ds_read_b64_tr_b16 v[60:61],v67 offset:6656
	ds_read_b64_tr_b16 v[68:69],v67 offset:7168
	ds_read_b64_tr_b16 v[70:71],v67 offset:7680
	s_waitcnt lgkmcnt(0)
	v_mfma_f32_32x32x16_bf16 v[18:33], v[38:41], v[62:65], v[18:33]
	v_mfma_f32_32x32x16_bf16 v[2:17], v[50:53], v[42:45], v[2:17]
	v_cmp_gt_u32_e32 vcc, 32, v210
	v_mfma_f32_32x32x16_bf16 v[2:17], v[54:57], v[46:49], v[2:17]
	v_mfma_f32_32x32x16_bf16 v[2:17], v[34:37], v[58:61], v[2:17]
	v_mov_b32_e32 v34, v0
	s_nop 1
	v_permlane32_swap_b32_e32 v0, v34
	v_mfma_f32_32x32x16_bf16 v[2:17], v[38:41], v[68:71], v[2:17]
	s_and_saveexec_b64 s[6:7], vcc
	v_add_f32_e32 v0, v0, v34
	ds_write_b32 v218, v0 offset:128
	s_or_b64 exec, exec, s[6:7]
	s_waitcnt lgkmcnt(0)
	ds_read_b128 v[34:37], v66 offset:128
	ds_read_b128 v[38:41], v66 offset:160
	s_add_u32 s8, s64, s40
	s_addc_u32 s9, s65, s41
	s_lshl_b64 s[6:7], s[42:43], 1
	s_waitcnt lgkmcnt(1)
	v_rcp_f32_e32 v42, v34
	s_add_u32 s6, s8, s6
	v_rcp_f32_e32 v43, v35
	s_addc_u32 s7, s9, s7
	s_lshl_b32 s8, s84, 12
	s_add_i32 s8, s8, 0
	s_add_i32 s8, s8, 0x12800
	v_lshlrev_b32_e32 v52, 1, v212
	v_lshlrev_b32_e32 v53, 9, v211
	v_mul_f32_e32 v2, v2, v42
	v_add3_u32 v52, s8, v52, v53
	v_cvt_pk_bf16_f32 v2, v2, s0
	v_rcp_f32_e32 v44, v36
	v_rcp_f32_e32 v45, v37
	s_waitcnt lgkmcnt(0)
	v_rcp_f32_e32 v46, v38
	ds_read_b128 v[34:37], v66 offset:192
	v_rcp_f32_e32 v47, v39
	v_rcp_f32_e32 v48, v40
	v_rcp_f32_e32 v49, v41
	ds_read_b128 v[38:41], v66 offset:224
	ds_write_b16 v52, v2 offset:64
	v_mul_f32_e32 v2, v19, v43
	v_cvt_pk_bf16_f32 v2, v2, s0
	ds_write_b16 v52, v2 offset:128
	v_mul_f32_e32 v2, v3, v43
	v_cvt_pk_bf16_f32 v2, v2, s0
	ds_write_b16 v52, v2 offset:192
	v_mul_f32_e32 v2, v20, v44
	v_cvt_pk_bf16_f32 v2, v2, s0
	ds_write_b16 v52, v2 offset:256
	v_mul_f32_e32 v2, v4, v44
	v_cvt_pk_bf16_f32 v2, v2, s0
	ds_write_b16 v52, v2 offset:320
	v_mul_f32_e32 v2, v21, v45
	v_cvt_pk_bf16_f32 v2, v2, s0
	ds_write_b16 v52, v2 offset:384
	v_mul_f32_e32 v2, v5, v45
	v_cvt_pk_bf16_f32 v2, v2, s0
	ds_write_b16 v52, v2 offset:448
	v_mul_f32_e32 v2, v22, v46
	v_cvt_pk_bf16_f32 v2, v2, s0
	ds_write_b16 v52, v2 offset:1024
	v_mul_f32_e32 v2, v6, v46
	v_cvt_pk_bf16_f32 v2, v2, s0
	ds_write_b16 v52, v2 offset:1088
	v_mul_f32_e32 v2, v23, v47
	v_cvt_pk_bf16_f32 v2, v2, s0
	ds_write_b16 v52, v2 offset:1152
	v_mul_f32_e32 v2, v7, v47
	v_cvt_pk_bf16_f32 v2, v2, s0
	ds_write_b16 v52, v2 offset:1216
	v_mul_f32_e32 v2, v24, v48
	v_cvt_pk_bf16_f32 v2, v2, s0
	ds_write_b16 v52, v2 offset:1280
	v_mul_f32_e32 v2, v8, v48
	v_cvt_pk_bf16_f32 v2, v2, s0
	s_waitcnt lgkmcnt(13)
	v_rcp_f32_e32 v50, v34
	ds_write_b16 v52, v2 offset:1344
	v_mul_f32_e32 v2, v25, v49
	v_cvt_pk_bf16_f32 v2, v2, s0
	ds_write_b16 v52, v2 offset:1408
	v_mul_f32_e32 v2, v9, v49
	v_cvt_pk_bf16_f32 v2, v2, s0
	v_rcp_f32_e32 v51, v35
	ds_write_b16 v52, v2 offset:1472
	v_mul_f32_e32 v2, v26, v50
	v_cvt_pk_bf16_f32 v2, v2, s0
	ds_write_b16 v52, v2 offset:2048
	v_mul_f32_e32 v2, v10, v50
	v_cvt_pk_bf16_f32 v2, v2, s0
	v_rcp_f32_e32 v36, v36
	ds_write_b16 v52, v2 offset:2112
	v_mul_f32_e32 v2, v27, v51
	v_cvt_pk_bf16_f32 v2, v2, s0
	ds_write_b16 v52, v2 offset:2176
	v_mul_f32_e32 v2, v11, v51
	v_cvt_pk_bf16_f32 v2, v2, s0
	v_rcp_f32_e32 v37, v37
	ds_write_b16 v52, v2 offset:2240
	v_mul_f32_e32 v2, v28, v36
	v_cvt_pk_bf16_f32 v2, v2, s0
	ds_write_b16 v52, v2 offset:2304
	v_mul_f32_e32 v2, v12, v36
	v_cvt_pk_bf16_f32 v2, v2, s0
	s_waitcnt lgkmcnt(14)
	v_rcp_f32_e32 v38, v38
	ds_write_b16 v52, v2 offset:2368
	v_mul_f32_e32 v2, v29, v37
	v_cvt_pk_bf16_f32 v2, v2, s0
	ds_write_b16 v52, v2 offset:2432
	v_mul_f32_e32 v2, v13, v37
	v_cvt_pk_bf16_f32 v2, v2, s0
	v_rcp_f32_e32 v39, v39
	ds_write_b16 v52, v2 offset:2496
	v_mul_f32_e32 v2, v30, v38
	v_cvt_pk_bf16_f32 v2, v2, s0
	ds_write_b16 v52, v2 offset:3072
	v_mul_f32_e32 v2, v14, v38
	v_cvt_pk_bf16_f32 v2, v2, s0
	v_rcp_f32_e32 v40, v40
	ds_write_b16 v52, v2 offset:3136
	v_mul_f32_e32 v2, v31, v39
	v_cvt_pk_bf16_f32 v2, v2, s0
	ds_write_b16 v52, v2 offset:3200
	v_mul_f32_e32 v2, v15, v39
	v_cvt_pk_bf16_f32 v2, v2, s0
	v_rcp_f32_e32 v41, v41
	ds_write_b16 v52, v2 offset:3264
	v_mul_f32_e32 v2, v32, v40
	v_cvt_pk_bf16_f32 v2, v2, s0
	ds_write_b16 v52, v2 offset:3328
	v_mul_f32_e32 v2, v16, v40
	v_cvt_pk_bf16_f32 v2, v2, s0
	ds_write_b16 v52, v2 offset:3392
	v_mul_f32_e32 v2, v33, v41
	v_cvt_pk_bf16_f32 v2, v2, s0
	v_lshlrev_b32_e32 v0, 1, v213
	v_mul_f32_e32 v18, v18, v42
	ds_write_b16 v52, v2 offset:3456
	v_mul_f32_e32 v2, v17, v41
	v_and_b32_e32 v0, 0x70, v0
	v_cvt_pk_bf16_f32 v18, v18, s0
	v_cvt_pk_bf16_f32 v2, v2, s0
	v_lshrrev_b32_e32 v20, 3, v210
	v_lshl_add_u64 v[34:35], s[6:7], 0, v[0:1]
	ds_write_b16 v52, v18
	ds_write_b16 v52, v2 offset:3520
	v_add_u32_e32 v36, s8, v0
	v_lshl_add_u64 v[2:3], s[38:39], 0, v[0:1]
	v_lshlrev_b32_e32 v0, 10, v20
	s_waitcnt lgkmcnt(0)
	v_lshl_add_u64 v[4:5], v[34:35], 0, v[0:1]
	global_load_dwordx4 v[4:7], v[4:5], off nt
	v_or_b32_e32 v37, 8, v20
	v_lshl_add_u64 v[24:25], v[2:3], 0, v[0:1]
	v_lshlrev_b32_e32 v0, 10, v37
	v_lshl_add_u64 v[8:9], v[34:35], 0, v[0:1]
	global_load_dwordx4 v[8:11], v[8:9], off nt
	v_or_b32_e32 v38, 16, v20
	v_lshl_add_u64 v[26:27], v[2:3], 0, v[0:1]
	v_lshlrev_b32_e32 v0, 10, v38
	v_lshl_add_u64 v[12:13], v[34:35], 0, v[0:1]
	global_load_dwordx4 v[12:15], v[12:13], off nt
	v_or_b32_e32 v39, 24, v20
	v_lshl_add_u64 v[32:33], v[2:3], 0, v[0:1]
	v_lshlrev_b32_e32 v0, 10, v39
	v_lshl_add_u32 v16, v20, 7, v36
	v_lshl_add_u64 v[20:21], v[34:35], 0, v[0:1]
	global_load_dwordx4 v[20:23], v[20:21], off nt
	ds_read_b128 v[16:19], v16
	v_lshl_add_u64 v[2:3], v[2:3], 0, v[0:1]
	s_waitcnt lgkmcnt(0)
	v_lshlrev_b32_e32 v28, 16, v16
	v_and_b32_e32 v29, 0xffff0000, v16
	v_lshlrev_b32_e32 v16, 16, v17
	v_and_b32_e32 v17, 0xffff0000, v17
	s_waitcnt vmcnt(3)
	v_lshlrev_b32_e32 v30, 16, v4
	v_and_b32_e32 v31, 0xffff0000, v4
	v_pk_mul_f32 v[28:29], v[28:29], v[30:31]
	v_lshlrev_b32_e32 v30, 16, v7
	v_cvt_pk_bf16_f32 v4, v28, v29
	v_lshlrev_b32_e32 v28, 16, v5
	v_and_b32_e32 v29, 0xffff0000, v5
	v_pk_mul_f32 v[16:17], v[16:17], v[28:29]
	v_lshlrev_b32_e32 v28, 16, v6
	v_cvt_pk_bf16_f32 v5, v16, v17
	v_lshlrev_b32_e32 v16, 16, v18
	v_and_b32_e32 v17, 0xffff0000, v18
	v_and_b32_e32 v29, 0xffff0000, v6
	v_pk_mul_f32 v[16:17], v[16:17], v[28:29]
	v_lshlrev_b32_e32 v28, 16, v19
	v_cvt_pk_bf16_f32 v6, v16, v17
	v_lshl_add_u32 v16, v37, 7, v36
	v_and_b32_e32 v29, 0xffff0000, v19
	ds_read_b128 v[16:19], v16
	v_and_b32_e32 v31, 0xffff0000, v7
	v_pk_mul_f32 v[28:29], v[28:29], v[30:31]
	s_nop 0
	v_cvt_pk_bf16_f32 v7, v28, v29
	global_store_dwordx4 v[24:25], v[4:7], off sc1
	s_waitcnt lgkmcnt(0)
	s_nop 0
	v_lshlrev_b32_e32 v4, 16, v16
	v_and_b32_e32 v5, 0xffff0000, v16
	s_waitcnt vmcnt(3)
	v_lshlrev_b32_e32 v6, 16, v8
	v_and_b32_e32 v7, 0xffff0000, v8
	v_pk_mul_f32 v[4:5], v[4:5], v[6:7]
	v_lshlrev_b32_e32 v6, 16, v17
	v_and_b32_e32 v7, 0xffff0000, v17
	v_lshlrev_b32_e32 v8, 16, v9
	v_and_b32_e32 v9, 0xffff0000, v9
	v_pk_mul_f32 v[6:7], v[6:7], v[8:9]
	v_cvt_pk_bf16_f32 v4, v4, v5
	v_cvt_pk_bf16_f32 v5, v6, v7
	v_lshlrev_b32_e32 v6, 16, v18
	v_and_b32_e32 v7, 0xffff0000, v18
	v_lshlrev_b32_e32 v8, 16, v10
	v_and_b32_e32 v9, 0xffff0000, v10
	v_pk_mul_f32 v[6:7], v[6:7], v[8:9]
	v_lshlrev_b32_e32 v8, 16, v19
	v_cvt_pk_bf16_f32 v6, v6, v7
	v_lshl_add_u32 v7, v38, 7, v36
	v_and_b32_e32 v9, 0xffff0000, v19
	ds_read_b128 v[16:19], v7
	v_lshlrev_b32_e32 v10, 16, v11
	v_and_b32_e32 v11, 0xffff0000, v11
	v_pk_mul_f32 v[8:9], v[8:9], v[10:11]
	s_nop 0
	v_cvt_pk_bf16_f32 v7, v8, v9
	global_store_dwordx4 v[26:27], v[4:7], off sc1
	s_waitcnt vmcnt(3)
	v_lshlrev_b32_e32 v8, 16, v13
	v_and_b32_e32 v9, 0xffff0000, v13
	s_waitcnt lgkmcnt(0)
	v_lshlrev_b32_e32 v4, 16, v16
	v_and_b32_e32 v5, 0xffff0000, v16
	v_lshlrev_b32_e32 v6, 16, v12
	v_and_b32_e32 v7, 0xffff0000, v12
	v_pk_mul_f32 v[4:5], v[4:5], v[6:7]
	v_lshlrev_b32_e32 v6, 16, v17
	v_and_b32_e32 v7, 0xffff0000, v17
	v_pk_mul_f32 v[6:7], v[6:7], v[8:9]
	v_cvt_pk_bf16_f32 v4, v4, v5
	v_cvt_pk_bf16_f32 v5, v6, v7
	v_lshlrev_b32_e32 v6, 16, v18
	v_and_b32_e32 v7, 0xffff0000, v18
	v_lshlrev_b32_e32 v8, 16, v14
	v_and_b32_e32 v9, 0xffff0000, v14
	v_pk_mul_f32 v[6:7], v[6:7], v[8:9]
	v_lshlrev_b32_e32 v12, 16, v19
	v_cvt_pk_bf16_f32 v6, v6, v7
	v_lshl_add_u32 v7, v39, 7, v36
	ds_read_b128 v[8:11], v7
	v_and_b32_e32 v13, 0xffff0000, v19
	v_lshlrev_b32_e32 v14, 16, v15
	v_and_b32_e32 v15, 0xffff0000, v15
	v_pk_mul_f32 v[12:13], v[12:13], v[14:15]
	s_nop 0
	v_cvt_pk_bf16_f32 v7, v12, v13
	global_store_dwordx4 v[32:33], v[4:7], off sc1
	s_waitcnt lgkmcnt(0)
	s_nop 0
	v_lshlrev_b32_e32 v4, 16, v8
	v_and_b32_e32 v5, 0xffff0000, v8
	s_waitcnt vmcnt(3)
	v_lshlrev_b32_e32 v6, 16, v20
	v_and_b32_e32 v7, 0xffff0000, v20
	v_pk_mul_f32 v[4:5], v[4:5], v[6:7]
	v_lshlrev_b32_e32 v6, 16, v9
	v_and_b32_e32 v7, 0xffff0000, v9
	v_lshlrev_b32_e32 v8, 16, v21
	v_and_b32_e32 v9, 0xffff0000, v21
	v_pk_mul_f32 v[6:7], v[6:7], v[8:9]
	v_cvt_pk_bf16_f32 v4, v4, v5
	v_cvt_pk_bf16_f32 v5, v6, v7
	v_lshlrev_b32_e32 v6, 16, v10
	v_and_b32_e32 v7, 0xffff0000, v10
	v_lshlrev_b32_e32 v8, 16, v22
	v_and_b32_e32 v9, 0xffff0000, v22
	v_pk_mul_f32 v[6:7], v[6:7], v[8:9]
	v_lshlrev_b32_e32 v8, 16, v11
	v_and_b32_e32 v9, 0xffff0000, v11
	v_lshlrev_b32_e32 v10, 16, v23
	v_and_b32_e32 v11, 0xffff0000, v23
	v_pk_mul_f32 v[8:9], v[8:9], v[10:11]
	v_cvt_pk_bf16_f32 v6, v6, v7
	v_cvt_pk_bf16_f32 v7, v8, v9
	global_store_dwordx4 v[2:3], v[4:7], off sc1
	s_waitcnt lgkmcnt(0)
	s_waitcnt lgkmcnt(0)
	s_barrier
	s_branch .LBB0_372

.LBB0_753:
	v_lshl_add_u32 v156, s8, 8, v162
	v_lshl_or_b32 v158, s48, 8, v164
	v_ashrrev_i32_e32 v157, 31, v156
	v_ashrrev_i32_e32 v159, 31, v158
	v_lshlrev_b64 v[160:161], 10, v[156:157]
	v_lshl_add_u64 v[160:161], v[160:161], 0, v[158:159]
	v_lshl_add_u64 v[146:147], v[160:161], 1, s[22:23]
	v_lshl_add_u64 v[150:151], v[160:161], 1, s[20:21]
	v_lshl_add_u64 v[154:155], v[160:161], 1, s[24:25]
	s_mov_b64 s[94:95], 0x8000
	s_mov_b64 s[96:97], 0x28000
	s_cmp_eq_u32 s9, 0
	s_cselect_b64 s[8:9], -1, 0
	s_cbranch_scc0 .Lmerge_g1
	global_load_dwordx4 v[166:169], v[146:147], off
	global_load_dwordx4 v[170:173], v[150:151], off
	global_load_dwordx4 v[174:177], v[146:147], off offset:256
	global_load_dwordx4 v[178:181], v[150:151], off offset:256
	v_lshl_add_u64 v[146:147], v[146:147], 0, s[94:95]
	v_lshl_add_u64 v[150:151], v[150:151], 0, s[94:95]
	global_load_dwordx4 v[182:185], v[146:147], off
	global_load_dwordx4 v[186:189], v[150:151], off
	global_load_dwordx4 v[190:193], v[146:147], off offset:256
	global_load_dwordx4 v[194:197], v[150:151], off offset:256
	v_lshl_add_u64 v[146:147], v[146:147], 0, s[94:95]
	v_lshl_add_u64 v[150:151], v[150:151], 0, s[94:95]
	global_load_dwordx4 v[198:201], v[146:147], off
	global_load_dwordx4 v[202:205], v[150:151], off
	global_load_dwordx4 v[206:209], v[146:147], off offset:256
	global_load_dwordx4 v[210:213], v[150:151], off offset:256
	v_lshl_add_u64 v[146:147], v[146:147], 0, s[94:95]
	v_lshl_add_u64 v[150:151], v[150:151], 0, s[94:95]
	global_load_dwordx4 v[214:217], v[146:147], off
	global_load_dwordx4 v[218:221], v[150:151], off
	global_load_dwordx4 v[222:225], v[146:147], off offset:256
	global_load_dwordx4 v[226:229], v[150:151], off offset:256
	v_lshl_add_u64 v[146:147], v[146:147], 0, s[96:97]
	v_lshl_add_u64 v[150:151], v[150:151], 0, s[96:97]
	s_waitcnt vmcnt(14)
	v_lshlrev_b32_e32 v230, 16, v166
	v_and_b32_e32 v231, 0xffff0000, v166
	v_lshlrev_b32_e32 v232, 16, v167
	v_and_b32_e32 v233, 0xffff0000, v167
	v_lshlrev_b32_e32 v234, 16, v168
	v_and_b32_e32 v235, 0xffff0000, v168
	v_lshlrev_b32_e32 v236, 16, v169
	v_and_b32_e32 v237, 0xffff0000, v169
	v_rcp_f32_e32 v230, v230
	v_rcp_f32_e32 v231, v231
	v_rcp_f32_e32 v232, v232
	v_rcp_f32_e32 v233, v233
	v_rcp_f32_e32 v234, v234
	v_rcp_f32_e32 v235, v235
	v_rcp_f32_e32 v236, v236
	v_rcp_f32_e32 v237, v237
	v_lshlrev_b32_e32 v238, 16, v170
	v_and_b32_e32 v239, 0xffff0000, v170
	v_lshlrev_b32_e32 v240, 16, v171
	v_and_b32_e32 v241, 0xffff0000, v171
	v_lshlrev_b32_e32 v242, 16, v172
	v_and_b32_e32 v243, 0xffff0000, v172
	v_lshlrev_b32_e32 v244, 16, v173
	v_and_b32_e32 v245, 0xffff0000, v173
	v_mul_f32_e32 v230, v230, v238
	v_mul_f32_e32 v231, v231, v239
	v_mul_f32_e32 v232, v232, v240
	v_mul_f32_e32 v233, v233, v241
	v_mul_f32_e32 v234, v234, v242
	v_mul_f32_e32 v235, v235, v243
	v_mul_f32_e32 v236, v236, v244
	v_mul_f32_e32 v237, v237, v245
	v_mul_f32_e32 v128, v128, v230
	v_mul_f32_e32 v129, v129, v231
	v_mul_f32_e32 v130, v130, v232
	v_mul_f32_e32 v131, v131, v233
	v_mul_f32_e32 v124, v124, v234
	v_mul_f32_e32 v125, v125, v235
	v_mul_f32_e32 v126, v126, v236
	v_mul_f32_e32 v127, v127, v237
	global_load_dwordx4 v[166:169], v[146:147], off
	global_load_dwordx4 v[170:173], v[150:151], off
	s_waitcnt vmcnt(14)
	v_lshlrev_b32_e32 v230, 16, v174
	v_and_b32_e32 v231, 0xffff0000, v174
	v_lshlrev_b32_e32 v232, 16, v175
	v_and_b32_e32 v233, 0xffff0000, v175
	v_lshlrev_b32_e32 v234, 16, v176
	v_and_b32_e32 v235, 0xffff0000, v176
	v_lshlrev_b32_e32 v236, 16, v177
	v_and_b32_e32 v237, 0xffff0000, v177
	v_rcp_f32_e32 v230, v230
	v_rcp_f32_e32 v231, v231
	v_rcp_f32_e32 v232, v232
	v_rcp_f32_e32 v233, v233
	v_rcp_f32_e32 v234, v234
	v_rcp_f32_e32 v235, v235
	v_rcp_f32_e32 v236, v236
	v_rcp_f32_e32 v237, v237
	v_lshlrev_b32_e32 v238, 16, v178
	v_and_b32_e32 v239, 0xffff0000, v178
	v_lshlrev_b32_e32 v240, 16, v179
	v_and_b32_e32 v241, 0xffff0000, v179
	v_lshlrev_b32_e32 v242, 16, v180
	v_and_b32_e32 v243, 0xffff0000, v180
	v_lshlrev_b32_e32 v244, 16, v181
	v_and_b32_e32 v245, 0xffff0000, v181
	v_mul_f32_e32 v230, v230, v238
	v_mul_f32_e32 v231, v231, v239
	v_mul_f32_e32 v232, v232, v240
	v_mul_f32_e32 v233, v233, v241
	v_mul_f32_e32 v234, v234, v242
	v_mul_f32_e32 v235, v235, v243
	v_mul_f32_e32 v236, v236, v244
	v_mul_f32_e32 v237, v237, v245
	v_mul_f32_e32 v96, v96, v230
	v_mul_f32_e32 v97, v97, v231
	v_mul_f32_e32 v98, v98, v232
	v_mul_f32_e32 v99, v99, v233
	v_mul_f32_e32 v92, v92, v234
	v_mul_f32_e32 v93, v93, v235
	v_mul_f32_e32 v94, v94, v236
	v_mul_f32_e32 v95, v95, v237
	global_load_dwordx4 v[174:177], v[146:147], off offset:256
	global_load_dwordx4 v[178:181], v[150:151], off offset:256
	v_lshl_add_u64 v[146:147], v[146:147], 0, s[94:95]
	v_lshl_add_u64 v[150:151], v[150:151], 0, s[94:95]
	s_waitcnt vmcnt(14)
	v_lshlrev_b32_e32 v230, 16, v182
	v_and_b32_e32 v231, 0xffff0000, v182
	v_lshlrev_b32_e32 v232, 16, v183
	v_and_b32_e32 v233, 0xffff0000, v183
	v_lshlrev_b32_e32 v234, 16, v184
	v_and_b32_e32 v235, 0xffff0000, v184
	v_lshlrev_b32_e32 v236, 16, v185
	v_and_b32_e32 v237, 0xffff0000, v185
	v_rcp_f32_e32 v230, v230
	v_rcp_f32_e32 v231, v231
	v_rcp_f32_e32 v232, v232
	v_rcp_f32_e32 v233, v233
	v_rcp_f32_e32 v234, v234
	v_rcp_f32_e32 v235, v235
	v_rcp_f32_e32 v236, v236
	v_rcp_f32_e32 v237, v237
	v_lshlrev_b32_e32 v238, 16, v186
	v_and_b32_e32 v239, 0xffff0000, v186
	v_lshlrev_b32_e32 v240, 16, v187
	v_and_b32_e32 v241, 0xffff0000, v187
	v_lshlrev_b32_e32 v242, 16, v188
	v_and_b32_e32 v243, 0xffff0000, v188
	v_lshlrev_b32_e32 v244, 16, v189
	v_and_b32_e32 v245, 0xffff0000, v189
	v_mul_f32_e32 v230, v230, v238
	v_mul_f32_e32 v231, v231, v239
	v_mul_f32_e32 v232, v232, v240
	v_mul_f32_e32 v233, v233, v241
	v_mul_f32_e32 v234, v234, v242
	v_mul_f32_e32 v235, v235, v243
	v_mul_f32_e32 v236, v236, v244
	v_mul_f32_e32 v237, v237, v245
	v_mul_f32_e32 v120, v120, v230
	v_mul_f32_e32 v121, v121, v231
	v_mul_f32_e32 v122, v122, v232
	v_mul_f32_e32 v123, v123, v233
	v_mul_f32_e32 v116, v116, v234
	v_mul_f32_e32 v117, v117, v235
	v_mul_f32_e32 v118, v118, v236
	v_mul_f32_e32 v119, v119, v237
	global_load_dwordx4 v[182:185], v[146:147], off
	global_load_dwordx4 v[186:189], v[150:151], off
	s_waitcnt vmcnt(14)
	v_lshlrev_b32_e32 v230, 16, v190
	v_and_b32_e32 v231, 0xffff0000, v190
	v_lshlrev_b32_e32 v232, 16, v191
	v_and_b32_e32 v233, 0xffff0000, v191
	v_lshlrev_b32_e32 v234, 16, v192
	v_and_b32_e32 v235, 0xffff0000, v192
	v_lshlrev_b32_e32 v236, 16, v193
	v_and_b32_e32 v237, 0xffff0000, v193
	v_rcp_f32_e32 v230, v230
	v_rcp_f32_e32 v231, v231
	v_rcp_f32_e32 v232, v232
	v_rcp_f32_e32 v233, v233
	v_rcp_f32_e32 v234, v234
	v_rcp_f32_e32 v235, v235
	v_rcp_f32_e32 v236, v236
	v_rcp_f32_e32 v237, v237
	v_lshlrev_b32_e32 v238, 16, v194
	v_and_b32_e32 v239, 0xffff0000, v194
	v_lshlrev_b32_e32 v240, 16, v195
	v_and_b32_e32 v241, 0xffff0000, v195
	v_lshlrev_b32_e32 v242, 16, v196
	v_and_b32_e32 v243, 0xffff0000, v196
	v_lshlrev_b32_e32 v244, 16, v197
	v_and_b32_e32 v245, 0xffff0000, v197
	v_mul_f32_e32 v230, v230, v238
	v_mul_f32_e32 v231, v231, v239
	v_mul_f32_e32 v232, v232, v240
	v_mul_f32_e32 v233, v233, v241
	v_mul_f32_e32 v234, v234, v242
	v_mul_f32_e32 v235, v235, v243
	v_mul_f32_e32 v236, v236, v244
	v_mul_f32_e32 v237, v237, v245
	v_mul_f32_e32 v88, v88, v230
	v_mul_f32_e32 v89, v89, v231
	v_mul_f32_e32 v90, v90, v232
	v_mul_f32_e32 v91, v91, v233
	v_mul_f32_e32 v84, v84, v234
	v_mul_f32_e32 v85, v85, v235
	v_mul_f32_e32 v86, v86, v236
	v_mul_f32_e32 v87, v87, v237
	global_load_dwordx4 v[190:193], v[146:147], off offset:256
	global_load_dwordx4 v[194:197], v[150:151], off offset:256
	v_lshl_add_u64 v[146:147], v[146:147], 0, s[94:95]
	v_lshl_add_u64 v[150:151], v[150:151], 0, s[94:95]
	s_waitcnt vmcnt(14)
	v_lshlrev_b32_e32 v230, 16, v198
	v_and_b32_e32 v231, 0xffff0000, v198
	v_lshlrev_b32_e32 v232, 16, v199
	v_and_b32_e32 v233, 0xffff0000, v199
	v_lshlrev_b32_e32 v234, 16, v200
	v_and_b32_e32 v235, 0xffff0000, v200
	v_lshlrev_b32_e32 v236, 16, v201
	v_and_b32_e32 v237, 0xffff0000, v201
	v_rcp_f32_e32 v230, v230
	v_rcp_f32_e32 v231, v231
	v_rcp_f32_e32 v232, v232
	v_rcp_f32_e32 v233, v233
	v_rcp_f32_e32 v234, v234
	v_rcp_f32_e32 v235, v235
	v_rcp_f32_e32 v236, v236
	v_rcp_f32_e32 v237, v237
	v_lshlrev_b32_e32 v238, 16, v202
	v_and_b32_e32 v239, 0xffff0000, v202
	v_lshlrev_b32_e32 v240, 16, v203
	v_and_b32_e32 v241, 0xffff0000, v203
	v_lshlrev_b32_e32 v242, 16, v204
	v_and_b32_e32 v243, 0xffff0000, v204
	v_lshlrev_b32_e32 v244, 16, v205
	v_and_b32_e32 v245, 0xffff0000, v205
	v_mul_f32_e32 v230, v230, v238
	v_mul_f32_e32 v231, v231, v239
	v_mul_f32_e32 v232, v232, v240
	v_mul_f32_e32 v233, v233, v241
	v_mul_f32_e32 v234, v234, v242
	v_mul_f32_e32 v235, v235, v243
	v_mul_f32_e32 v236, v236, v244
	v_mul_f32_e32 v237, v237, v245
	v_mul_f32_e32 v112, v112, v230
	v_mul_f32_e32 v113, v113, v231
	v_mul_f32_e32 v114, v114, v232
	v_mul_f32_e32 v115, v115, v233
	v_mul_f32_e32 v108, v108, v234
	v_mul_f32_e32 v109, v109, v235
	v_mul_f32_e32 v110, v110, v236
	v_mul_f32_e32 v111, v111, v237
	global_load_dwordx4 v[198:201], v[146:147], off
	global_load_dwordx4 v[202:205], v[150:151], off
	s_waitcnt vmcnt(14)
	v_lshlrev_b32_e32 v230, 16, v206
	v_and_b32_e32 v231, 0xffff0000, v206
	v_lshlrev_b32_e32 v232, 16, v207
	v_and_b32_e32 v233, 0xffff0000, v207
	v_lshlrev_b32_e32 v234, 16, v208
	v_and_b32_e32 v235, 0xffff0000, v208
	v_lshlrev_b32_e32 v236, 16, v209
	v_and_b32_e32 v237, 0xffff0000, v209
	v_rcp_f32_e32 v230, v230
	v_rcp_f32_e32 v231, v231
	v_rcp_f32_e32 v232, v232
	v_rcp_f32_e32 v233, v233
	v_rcp_f32_e32 v234, v234
	v_rcp_f32_e32 v235, v235
	v_rcp_f32_e32 v236, v236
	v_rcp_f32_e32 v237, v237
	v_lshlrev_b32_e32 v238, 16, v210
	v_and_b32_e32 v239, 0xffff0000, v210
	v_lshlrev_b32_e32 v240, 16, v211
	v_and_b32_e32 v241, 0xffff0000, v211
	v_lshlrev_b32_e32 v242, 16, v212
	v_and_b32_e32 v243, 0xffff0000, v212
	v_lshlrev_b32_e32 v244, 16, v213
	v_and_b32_e32 v245, 0xffff0000, v213
	v_mul_f32_e32 v230, v230, v238
	v_mul_f32_e32 v231, v231, v239
	v_mul_f32_e32 v232, v232, v240
	v_mul_f32_e32 v233, v233, v241
	v_mul_f32_e32 v234, v234, v242
	v_mul_f32_e32 v235, v235, v243
	v_mul_f32_e32 v236, v236, v244
	v_mul_f32_e32 v237, v237, v245
	v_mul_f32_e32 v80, v80, v230
	v_mul_f32_e32 v81, v81, v231
	v_mul_f32_e32 v82, v82, v232
	v_mul_f32_e32 v83, v83, v233
	v_mul_f32_e32 v76, v76, v234
	v_mul_f32_e32 v77, v77, v235
	v_mul_f32_e32 v78, v78, v236
	v_mul_f32_e32 v79, v79, v237
	global_load_dwordx4 v[206:209], v[146:147], off offset:256
	global_load_dwordx4 v[210:213], v[150:151], off offset:256
	v_lshl_add_u64 v[146:147], v[146:147], 0, s[94:95]
	v_lshl_add_u64 v[150:151], v[150:151], 0, s[94:95]
	s_waitcnt vmcnt(14)
	v_lshlrev_b32_e32 v230, 16, v214
	v_and_b32_e32 v231, 0xffff0000, v214
	v_lshlrev_b32_e32 v232, 16, v215
	v_and_b32_e32 v233, 0xffff0000, v215
	v_lshlrev_b32_e32 v234, 16, v216
	v_and_b32_e32 v235, 0xffff0000, v216
	v_lshlrev_b32_e32 v236, 16, v217
	v_and_b32_e32 v237, 0xffff0000, v217
	v_rcp_f32_e32 v230, v230
	v_rcp_f32_e32 v231, v231
	v_rcp_f32_e32 v232, v232
	v_rcp_f32_e32 v233, v233
	v_rcp_f32_e32 v234, v234
	v_rcp_f32_e32 v235, v235
	v_rcp_f32_e32 v236, v236
	v_rcp_f32_e32 v237, v237
	v_lshlrev_b32_e32 v238, 16, v218
	v_and_b32_e32 v239, 0xffff0000, v218
	v_lshlrev_b32_e32 v240, 16, v219
	v_and_b32_e32 v241, 0xffff0000, v219
	v_lshlrev_b32_e32 v242, 16, v220
	v_and_b32_e32 v243, 0xffff0000, v220
	v_lshlrev_b32_e32 v244, 16, v221
	v_and_b32_e32 v245, 0xffff0000, v221
	v_mul_f32_e32 v230, v230, v238
	v_mul_f32_e32 v231, v231, v239
	v_mul_f32_e32 v232, v232, v240
	v_mul_f32_e32 v233, v233, v241
	v_mul_f32_e32 v234, v234, v242
	v_mul_f32_e32 v235, v235, v243
	v_mul_f32_e32 v236, v236, v244
	v_mul_f32_e32 v237, v237, v245
	v_mul_f32_e32 v104, v104, v230
	v_mul_f32_e32 v105, v105, v231
	v_mul_f32_e32 v106, v106, v232
	v_mul_f32_e32 v107, v107, v233
	v_mul_f32_e32 v100, v100, v234
	v_mul_f32_e32 v101, v101, v235
	v_mul_f32_e32 v102, v102, v236
	v_mul_f32_e32 v103, v103, v237
	global_load_dwordx4 v[214:217], v[146:147], off
	global_load_dwordx4 v[218:221], v[150:151], off
	s_waitcnt vmcnt(14)
	v_lshlrev_b32_e32 v230, 16, v222
	v_and_b32_e32 v231, 0xffff0000, v222
	v_lshlrev_b32_e32 v232, 16, v223
	v_and_b32_e32 v233, 0xffff0000, v223
	v_lshlrev_b32_e32 v234, 16, v224
	v_and_b32_e32 v235, 0xffff0000, v224
	v_lshlrev_b32_e32 v236, 16, v225
	v_and_b32_e32 v237, 0xffff0000, v225
	v_rcp_f32_e32 v230, v230
	v_rcp_f32_e32 v231, v231
	v_rcp_f32_e32 v232, v232
	v_rcp_f32_e32 v233, v233
	v_rcp_f32_e32 v234, v234
	v_rcp_f32_e32 v235, v235
	v_rcp_f32_e32 v236, v236
	v_rcp_f32_e32 v237, v237
	v_lshlrev_b32_e32 v238, 16, v226
	v_and_b32_e32 v239, 0xffff0000, v226
	v_lshlrev_b32_e32 v240, 16, v227
	v_and_b32_e32 v241, 0xffff0000, v227
	v_lshlrev_b32_e32 v242, 16, v228
	v_and_b32_e32 v243, 0xffff0000, v228
	v_lshlrev_b32_e32 v244, 16, v229
	v_and_b32_e32 v245, 0xffff0000, v229
	v_mul_f32_e32 v230, v230, v238
	v_mul_f32_e32 v231, v231, v239
	v_mul_f32_e32 v232, v232, v240
	v_mul_f32_e32 v233, v233, v241
	v_mul_f32_e32 v234, v234, v242
	v_mul_f32_e32 v235, v235, v243
	v_mul_f32_e32 v236, v236, v244
	v_mul_f32_e32 v237, v237, v245
	v_mul_f32_e32 v72, v72, v230
	v_mul_f32_e32 v73, v73, v231
	v_mul_f32_e32 v74, v74, v232
	v_mul_f32_e32 v75, v75, v233
	v_mul_f32_e32 v68, v68, v234
	v_mul_f32_e32 v69, v69, v235
	v_mul_f32_e32 v70, v70, v236
	v_mul_f32_e32 v71, v71, v237
	global_load_dwordx4 v[222:225], v[146:147], off offset:256
	global_load_dwordx4 v[226:229], v[150:151], off offset:256
	s_waitcnt vmcnt(14)
	v_lshlrev_b32_e32 v230, 16, v166
	v_and_b32_e32 v231, 0xffff0000, v166
	v_lshlrev_b32_e32 v232, 16, v167
	v_and_b32_e32 v233, 0xffff0000, v167
	v_lshlrev_b32_e32 v234, 16, v168
	v_and_b32_e32 v235, 0xffff0000, v168
	v_lshlrev_b32_e32 v236, 16, v169
	v_and_b32_e32 v237, 0xffff0000, v169
	v_rcp_f32_e32 v230, v230
	v_rcp_f32_e32 v231, v231
	v_rcp_f32_e32 v232, v232
	v_rcp_f32_e32 v233, v233
	v_rcp_f32_e32 v234, v234
	v_rcp_f32_e32 v235, v235
	v_rcp_f32_e32 v236, v236
	v_rcp_f32_e32 v237, v237
	v_lshlrev_b32_e32 v238, 16, v170
	v_and_b32_e32 v239, 0xffff0000, v170
	v_lshlrev_b32_e32 v240, 16, v171
	v_and_b32_e32 v241, 0xffff0000, v171
	v_lshlrev_b32_e32 v242, 16, v172
	v_and_b32_e32 v243, 0xffff0000, v172
	v_lshlrev_b32_e32 v244, 16, v173
	v_and_b32_e32 v245, 0xffff0000, v173
	v_mul_f32_e32 v230, v230, v238
	v_mul_f32_e32 v231, v231, v239
	v_mul_f32_e32 v232, v232, v240
	v_mul_f32_e32 v233, v233, v241
	v_mul_f32_e32 v234, v234, v242
	v_mul_f32_e32 v235, v235, v243
	v_mul_f32_e32 v236, v236, v244
	v_mul_f32_e32 v237, v237, v245
	v_mul_f32_e32 v64, v64, v230
	v_mul_f32_e32 v65, v65, v231
	v_mul_f32_e32 v66, v66, v232
	v_mul_f32_e32 v67, v67, v233
	v_mul_f32_e32 v60, v60, v234
	v_mul_f32_e32 v61, v61, v235
	v_mul_f32_e32 v62, v62, v236
	v_mul_f32_e32 v63, v63, v237
	s_waitcnt vmcnt(12)
	v_lshlrev_b32_e32 v230, 16, v174
	v_and_b32_e32 v231, 0xffff0000, v174
	v_lshlrev_b32_e32 v232, 16, v175
	v_and_b32_e32 v233, 0xffff0000, v175
	v_lshlrev_b32_e32 v234, 16, v176
	v_and_b32_e32 v235, 0xffff0000, v176
	v_lshlrev_b32_e32 v236, 16, v177
	v_and_b32_e32 v237, 0xffff0000, v177
	v_rcp_f32_e32 v230, v230
	v_rcp_f32_e32 v231, v231
	v_rcp_f32_e32 v232, v232
	v_rcp_f32_e32 v233, v233
	v_rcp_f32_e32 v234, v234
	v_rcp_f32_e32 v235, v235
	v_rcp_f32_e32 v236, v236
	v_rcp_f32_e32 v237, v237
	v_lshlrev_b32_e32 v238, 16, v178
	v_and_b32_e32 v239, 0xffff0000, v178
	v_lshlrev_b32_e32 v240, 16, v179
	v_and_b32_e32 v241, 0xffff0000, v179
	v_lshlrev_b32_e32 v242, 16, v180
	v_and_b32_e32 v243, 0xffff0000, v180
	v_lshlrev_b32_e32 v244, 16, v181
	v_and_b32_e32 v245, 0xffff0000, v181
	v_mul_f32_e32 v230, v230, v238
	v_mul_f32_e32 v231, v231, v239
	v_mul_f32_e32 v232, v232, v240
	v_mul_f32_e32 v233, v233, v241
	v_mul_f32_e32 v234, v234, v242
	v_mul_f32_e32 v235, v235, v243
	v_mul_f32_e32 v236, v236, v244
	v_mul_f32_e32 v237, v237, v245
	v_mul_f32_e32 v32, v32, v230
	v_mul_f32_e32 v33, v33, v231
	v_mul_f32_e32 v34, v34, v232
	v_mul_f32_e32 v35, v35, v233
	v_mul_f32_e32 v28, v28, v234
	v_mul_f32_e32 v29, v29, v235
	v_mul_f32_e32 v30, v30, v236
	v_mul_f32_e32 v31, v31, v237
	s_waitcnt vmcnt(10)
	v_lshlrev_b32_e32 v230, 16, v182
	v_and_b32_e32 v231, 0xffff0000, v182
	v_lshlrev_b32_e32 v232, 16, v183
	v_and_b32_e32 v233, 0xffff0000, v183
	v_lshlrev_b32_e32 v234, 16, v184
	v_and_b32_e32 v235, 0xffff0000, v184
	v_lshlrev_b32_e32 v236, 16, v185
	v_and_b32_e32 v237, 0xffff0000, v185
	v_rcp_f32_e32 v230, v230
	v_rcp_f32_e32 v231, v231
	v_rcp_f32_e32 v232, v232
	v_rcp_f32_e32 v233, v233
	v_rcp_f32_e32 v234, v234
	v_rcp_f32_e32 v235, v235
	v_rcp_f32_e32 v236, v236
	v_rcp_f32_e32 v237, v237
	v_lshlrev_b32_e32 v238, 16, v186
	v_and_b32_e32 v239, 0xffff0000, v186
	v_lshlrev_b32_e32 v240, 16, v187
	v_and_b32_e32 v241, 0xffff0000, v187
	v_lshlrev_b32_e32 v242, 16, v188
	v_and_b32_e32 v243, 0xffff0000, v188
	v_lshlrev_b32_e32 v244, 16, v189
	v_and_b32_e32 v245, 0xffff0000, v189
	v_mul_f32_e32 v230, v230, v238
	v_mul_f32_e32 v231, v231, v239
	v_mul_f32_e32 v232, v232, v240
	v_mul_f32_e32 v233, v233, v241
	v_mul_f32_e32 v234, v234, v242
	v_mul_f32_e32 v235, v235, v243
	v_mul_f32_e32 v236, v236, v244
	v_mul_f32_e32 v237, v237, v245
	v_mul_f32_e32 v56, v56, v230
	v_mul_f32_e32 v57, v57, v231
	v_mul_f32_e32 v58, v58, v232
	v_mul_f32_e32 v59, v59, v233
	v_mul_f32_e32 v52, v52, v234
	v_mul_f32_e32 v53, v53, v235
	v_mul_f32_e32 v54, v54, v236
	v_mul_f32_e32 v55, v55, v237
	s_waitcnt vmcnt(8)
	v_lshlrev_b32_e32 v230, 16, v190
	v_and_b32_e32 v231, 0xffff0000, v190
	v_lshlrev_b32_e32 v232, 16, v191
	v_and_b32_e32 v233, 0xffff0000, v191
	v_lshlrev_b32_e32 v234, 16, v192
	v_and_b32_e32 v235, 0xffff0000, v192
	v_lshlrev_b32_e32 v236, 16, v193
	v_and_b32_e32 v237, 0xffff0000, v193
	v_rcp_f32_e32 v230, v230
	v_rcp_f32_e32 v231, v231
	v_rcp_f32_e32 v232, v232
	v_rcp_f32_e32 v233, v233
	v_rcp_f32_e32 v234, v234
	v_rcp_f32_e32 v235, v235
	v_rcp_f32_e32 v236, v236
	v_rcp_f32_e32 v237, v237
	v_lshlrev_b32_e32 v238, 16, v194
	v_and_b32_e32 v239, 0xffff0000, v194
	v_lshlrev_b32_e32 v240, 16, v195
	v_and_b32_e32 v241, 0xffff0000, v195
	v_lshlrev_b32_e32 v242, 16, v196
	v_and_b32_e32 v243, 0xffff0000, v196
	v_lshlrev_b32_e32 v244, 16, v197
	v_and_b32_e32 v245, 0xffff0000, v197
	v_mul_f32_e32 v230, v230, v238
	v_mul_f32_e32 v231, v231, v239
	v_mul_f32_e32 v232, v232, v240
	v_mul_f32_e32 v233, v233, v241
	v_mul_f32_e32 v234, v234, v242
	v_mul_f32_e32 v235, v235, v243
	v_mul_f32_e32 v236, v236, v244
	v_mul_f32_e32 v237, v237, v245
	v_mul_f32_e32 v24, v24, v230
	v_mul_f32_e32 v25, v25, v231
	v_mul_f32_e32 v26, v26, v232
	v_mul_f32_e32 v27, v27, v233
	v_mul_f32_e32 v20, v20, v234
	v_mul_f32_e32 v21, v21, v235
	v_mul_f32_e32 v22, v22, v236
	v_mul_f32_e32 v23, v23, v237
	s_waitcnt vmcnt(6)
	v_lshlrev_b32_e32 v230, 16, v198
	v_and_b32_e32 v231, 0xffff0000, v198
	v_lshlrev_b32_e32 v232, 16, v199
	v_and_b32_e32 v233, 0xffff0000, v199
	v_lshlrev_b32_e32 v234, 16, v200
	v_and_b32_e32 v235, 0xffff0000, v200
	v_lshlrev_b32_e32 v236, 16, v201
	v_and_b32_e32 v237, 0xffff0000, v201
	v_rcp_f32_e32 v230, v230
	v_rcp_f32_e32 v231, v231
	v_rcp_f32_e32 v232, v232
	v_rcp_f32_e32 v233, v233
	v_rcp_f32_e32 v234, v234
	v_rcp_f32_e32 v235, v235
	v_rcp_f32_e32 v236, v236
	v_rcp_f32_e32 v237, v237
	v_lshlrev_b32_e32 v238, 16, v202
	v_and_b32_e32 v239, 0xffff0000, v202
	v_lshlrev_b32_e32 v240, 16, v203
	v_and_b32_e32 v241, 0xffff0000, v203
	v_lshlrev_b32_e32 v242, 16, v204
	v_and_b32_e32 v243, 0xffff0000, v204
	v_lshlrev_b32_e32 v244, 16, v205
	v_and_b32_e32 v245, 0xffff0000, v205
	v_mul_f32_e32 v230, v230, v238
	v_mul_f32_e32 v231, v231, v239
	v_mul_f32_e32 v232, v232, v240
	v_mul_f32_e32 v233, v233, v241
	v_mul_f32_e32 v234, v234, v242
	v_mul_f32_e32 v235, v235, v243
	v_mul_f32_e32 v236, v236, v244
	v_mul_f32_e32 v237, v237, v245
	v_mul_f32_e32 v48, v48, v230
	v_mul_f32_e32 v49, v49, v231
	v_mul_f32_e32 v50, v50, v232
	v_mul_f32_e32 v51, v51, v233
	v_mul_f32_e32 v44, v44, v234
	v_mul_f32_e32 v45, v45, v235
	v_mul_f32_e32 v46, v46, v236
	v_mul_f32_e32 v47, v47, v237
	s_waitcnt vmcnt(4)
	v_lshlrev_b32_e32 v230, 16, v206
	v_and_b32_e32 v231, 0xffff0000, v206
	v_lshlrev_b32_e32 v232, 16, v207
	v_and_b32_e32 v233, 0xffff0000, v207
	v_lshlrev_b32_e32 v234, 16, v208
	v_and_b32_e32 v235, 0xffff0000, v208
	v_lshlrev_b32_e32 v236, 16, v209
	v_and_b32_e32 v237, 0xffff0000, v209
	v_rcp_f32_e32 v230, v230
	v_rcp_f32_e32 v231, v231
	v_rcp_f32_e32 v232, v232
	v_rcp_f32_e32 v233, v233
	v_rcp_f32_e32 v234, v234
	v_rcp_f32_e32 v235, v235
	v_rcp_f32_e32 v236, v236
	v_rcp_f32_e32 v237, v237
	v_lshlrev_b32_e32 v238, 16, v210
	v_and_b32_e32 v239, 0xffff0000, v210
	v_lshlrev_b32_e32 v240, 16, v211
	v_and_b32_e32 v241, 0xffff0000, v211
	v_lshlrev_b32_e32 v242, 16, v212
	v_and_b32_e32 v243, 0xffff0000, v212
	v_lshlrev_b32_e32 v244, 16, v213
	v_and_b32_e32 v245, 0xffff0000, v213
	v_mul_f32_e32 v230, v230, v238
	v_mul_f32_e32 v231, v231, v239
	v_mul_f32_e32 v232, v232, v240
	v_mul_f32_e32 v233, v233, v241
	v_mul_f32_e32 v234, v234, v242
	v_mul_f32_e32 v235, v235, v243
	v_mul_f32_e32 v236, v236, v244
	v_mul_f32_e32 v237, v237, v245
	v_mul_f32_e32 v16, v16, v230
	v_mul_f32_e32 v17, v17, v231
	v_mul_f32_e32 v18, v18, v232
	v_mul_f32_e32 v19, v19, v233
	v_mul_f32_e32 v12, v12, v234
	v_mul_f32_e32 v13, v13, v235
	v_mul_f32_e32 v14, v14, v236
	v_mul_f32_e32 v15, v15, v237
	s_waitcnt vmcnt(2)
	v_lshlrev_b32_e32 v230, 16, v214
	v_and_b32_e32 v231, 0xffff0000, v214
	v_lshlrev_b32_e32 v232, 16, v215
	v_and_b32_e32 v233, 0xffff0000, v215
	v_lshlrev_b32_e32 v234, 16, v216
	v_and_b32_e32 v235, 0xffff0000, v216
	v_lshlrev_b32_e32 v236, 16, v217
	v_and_b32_e32 v237, 0xffff0000, v217
	v_rcp_f32_e32 v230, v230
	v_rcp_f32_e32 v231, v231
	v_rcp_f32_e32 v232, v232
	v_rcp_f32_e32 v233, v233
	v_rcp_f32_e32 v234, v234
	v_rcp_f32_e32 v235, v235
	v_rcp_f32_e32 v236, v236
	v_rcp_f32_e32 v237, v237
	v_lshlrev_b32_e32 v238, 16, v218
	v_and_b32_e32 v239, 0xffff0000, v218
	v_lshlrev_b32_e32 v240, 16, v219
	v_and_b32_e32 v241, 0xffff0000, v219
	v_lshlrev_b32_e32 v242, 16, v220
	v_and_b32_e32 v243, 0xffff0000, v220
	v_lshlrev_b32_e32 v244, 16, v221
	v_and_b32_e32 v245, 0xffff0000, v221
	v_mul_f32_e32 v230, v230, v238
	v_mul_f32_e32 v231, v231, v239
	v_mul_f32_e32 v232, v232, v240
	v_mul_f32_e32 v233, v233, v241
	v_mul_f32_e32 v234, v234, v242
	v_mul_f32_e32 v235, v235, v243
	v_mul_f32_e32 v236, v236, v244
	v_mul_f32_e32 v237, v237, v245
	v_mul_f32_e32 v40, v40, v230
	v_mul_f32_e32 v41, v41, v231
	v_mul_f32_e32 v42, v42, v232
	v_mul_f32_e32 v43, v43, v233
	v_mul_f32_e32 v36, v36, v234
	v_mul_f32_e32 v37, v37, v235
	v_mul_f32_e32 v38, v38, v236
	v_mul_f32_e32 v39, v39, v237
	s_waitcnt vmcnt(0)
	v_lshlrev_b32_e32 v230, 16, v222
	v_and_b32_e32 v231, 0xffff0000, v222
	v_lshlrev_b32_e32 v232, 16, v223
	v_and_b32_e32 v233, 0xffff0000, v223
	v_lshlrev_b32_e32 v234, 16, v224
	v_and_b32_e32 v235, 0xffff0000, v224
	v_lshlrev_b32_e32 v236, 16, v225
	v_and_b32_e32 v237, 0xffff0000, v225
	v_rcp_f32_e32 v230, v230
	v_rcp_f32_e32 v231, v231
	v_rcp_f32_e32 v232, v232
	v_rcp_f32_e32 v233, v233
	v_rcp_f32_e32 v234, v234
	v_rcp_f32_e32 v235, v235
	v_rcp_f32_e32 v236, v236
	v_rcp_f32_e32 v237, v237
	v_lshlrev_b32_e32 v238, 16, v226
	v_and_b32_e32 v239, 0xffff0000, v226
	v_lshlrev_b32_e32 v240, 16, v227
	v_and_b32_e32 v241, 0xffff0000, v227
	v_lshlrev_b32_e32 v242, 16, v228
	v_and_b32_e32 v243, 0xffff0000, v228
	v_lshlrev_b32_e32 v244, 16, v229
	v_and_b32_e32 v245, 0xffff0000, v229
	v_mul_f32_e32 v230, v230, v238
	v_mul_f32_e32 v231, v231, v239
	v_mul_f32_e32 v232, v232, v240
	v_mul_f32_e32 v233, v233, v241
	v_mul_f32_e32 v234, v234, v242
	v_mul_f32_e32 v235, v235, v243
	v_mul_f32_e32 v236, v236, v244
	v_mul_f32_e32 v237, v237, v245
	v_mul_f32_e32 v8, v8, v230
	v_mul_f32_e32 v9, v9, v231
	v_mul_f32_e32 v10, v10, v232
	v_mul_f32_e32 v11, v11, v233
	v_mul_f32_e32 v4, v4, v234
	v_mul_f32_e32 v5, v5, v235
	v_mul_f32_e32 v6, v6, v236
	v_mul_f32_e32 v7, v7, v237
	s_branch .LBB0_801
.Lmerge_g1:
	global_load_dwordx4 v[166:169], v[146:147], off
	global_load_dwordx4 v[170:173], v[146:147], off offset:256
	v_lshl_add_u64 v[146:147], v[146:147], 0, s[94:95]
	global_load_dwordx4 v[174:177], v[146:147], off
	global_load_dwordx4 v[178:181], v[146:147], off offset:256
	v_lshl_add_u64 v[146:147], v[146:147], 0, s[94:95]
	global_load_dwordx4 v[182:185], v[146:147], off
	global_load_dwordx4 v[186:189], v[146:147], off offset:256
	v_lshl_add_u64 v[146:147], v[146:147], 0, s[94:95]
	global_load_dwordx4 v[190:193], v[146:147], off
	global_load_dwordx4 v[194:197], v[146:147], off offset:256
	v_lshl_add_u64 v[146:147], v[146:147], 0, s[96:97]
	global_load_dwordx4 v[198:201], v[146:147], off
	global_load_dwordx4 v[202:205], v[146:147], off offset:256
	v_lshl_add_u64 v[146:147], v[146:147], 0, s[94:95]
	global_load_dwordx4 v[206:209], v[146:147], off
	global_load_dwordx4 v[210:213], v[146:147], off offset:256
	v_lshl_add_u64 v[146:147], v[146:147], 0, s[94:95]
	global_load_dwordx4 v[214:217], v[146:147], off
	global_load_dwordx4 v[218:221], v[146:147], off offset:256
	v_lshl_add_u64 v[146:147], v[146:147], 0, s[94:95]
	global_load_dwordx4 v[222:225], v[146:147], off
	global_load_dwordx4 v[226:229], v[146:147], off offset:256
	s_waitcnt vmcnt(15)
	v_lshlrev_b32_e32 v230, 16, v166
	v_and_b32_e32 v231, 0xffff0000, v166
	v_lshlrev_b32_e32 v232, 16, v167
	v_and_b32_e32 v233, 0xffff0000, v167
	v_lshlrev_b32_e32 v234, 16, v168
	v_and_b32_e32 v235, 0xffff0000, v168
	v_lshlrev_b32_e32 v236, 16, v169
	v_and_b32_e32 v237, 0xffff0000, v169
	v_mul_f32_e32 v238, v128, v230
	v_mul_f32_e32 v239, v129, v231
	v_mul_f32_e32 v240, v130, v232
	v_mul_f32_e32 v241, v131, v233
	v_mul_f32_e32 v242, v124, v234
	v_mul_f32_e32 v243, v125, v235
	v_mul_f32_e32 v244, v126, v236
	v_mul_f32_e32 v245, v127, v237
	v_cvt_pk_bf16_f32 v246, v238, v239
	v_cvt_pk_bf16_f32 v247, v240, v241
	v_cvt_pk_bf16_f32 v248, v242, v243
	v_cvt_pk_bf16_f32 v249, v244, v245
	global_store_dwordx4 v[154:155], v[246:249], off
	s_waitcnt vmcnt(15)
	v_lshlrev_b32_e32 v230, 16, v170
	v_and_b32_e32 v231, 0xffff0000, v170
	v_lshlrev_b32_e32 v232, 16, v171
	v_and_b32_e32 v233, 0xffff0000, v171
	v_lshlrev_b32_e32 v234, 16, v172
	v_and_b32_e32 v235, 0xffff0000, v172
	v_lshlrev_b32_e32 v236, 16, v173
	v_and_b32_e32 v237, 0xffff0000, v173
	v_mul_f32_e32 v238, v96, v230
	v_mul_f32_e32 v239, v97, v231
	v_mul_f32_e32 v240, v98, v232
	v_mul_f32_e32 v241, v99, v233
	v_mul_f32_e32 v242, v92, v234
	v_mul_f32_e32 v243, v93, v235
	v_mul_f32_e32 v244, v94, v236
	v_mul_f32_e32 v245, v95, v237
	v_cvt_pk_bf16_f32 v246, v238, v239
	v_cvt_pk_bf16_f32 v247, v240, v241
	v_cvt_pk_bf16_f32 v248, v242, v243
	v_cvt_pk_bf16_f32 v249, v244, v245
	global_store_dwordx4 v[154:155], v[246:249], off offset:256
	v_lshl_add_u64 v[154:155], v[154:155], 0, s[94:95]
	s_waitcnt vmcnt(15)
	v_lshlrev_b32_e32 v230, 16, v174
	v_and_b32_e32 v231, 0xffff0000, v174
	v_lshlrev_b32_e32 v232, 16, v175
	v_and_b32_e32 v233, 0xffff0000, v175
	v_lshlrev_b32_e32 v234, 16, v176
	v_and_b32_e32 v235, 0xffff0000, v176
	v_lshlrev_b32_e32 v236, 16, v177
	v_and_b32_e32 v237, 0xffff0000, v177
	v_mul_f32_e32 v238, v120, v230
	v_mul_f32_e32 v239, v121, v231
	v_mul_f32_e32 v240, v122, v232
	v_mul_f32_e32 v241, v123, v233
	v_mul_f32_e32 v242, v116, v234
	v_mul_f32_e32 v243, v117, v235
	v_mul_f32_e32 v244, v118, v236
	v_mul_f32_e32 v245, v119, v237
	v_cvt_pk_bf16_f32 v246, v238, v239
	v_cvt_pk_bf16_f32 v247, v240, v241
	v_cvt_pk_bf16_f32 v248, v242, v243
	v_cvt_pk_bf16_f32 v249, v244, v245
	global_store_dwordx4 v[154:155], v[246:249], off
	s_waitcnt vmcnt(15)
	v_lshlrev_b32_e32 v230, 16, v178
	v_and_b32_e32 v231, 0xffff0000, v178
	v_lshlrev_b32_e32 v232, 16, v179
	v_and_b32_e32 v233, 0xffff0000, v179
	v_lshlrev_b32_e32 v234, 16, v180
	v_and_b32_e32 v235, 0xffff0000, v180
	v_lshlrev_b32_e32 v236, 16, v181
	v_and_b32_e32 v237, 0xffff0000, v181
	v_mul_f32_e32 v238, v88, v230
	v_mul_f32_e32 v239, v89, v231
	v_mul_f32_e32 v240, v90, v232
	v_mul_f32_e32 v241, v91, v233
	v_mul_f32_e32 v242, v84, v234
	v_mul_f32_e32 v243, v85, v235
	v_mul_f32_e32 v244, v86, v236
	v_mul_f32_e32 v245, v87, v237
	v_cvt_pk_bf16_f32 v246, v238, v239
	v_cvt_pk_bf16_f32 v247, v240, v241
	v_cvt_pk_bf16_f32 v248, v242, v243
	v_cvt_pk_bf16_f32 v249, v244, v245
	global_store_dwordx4 v[154:155], v[246:249], off offset:256
	v_lshl_add_u64 v[154:155], v[154:155], 0, s[94:95]
	s_waitcnt vmcnt(15)
	v_lshlrev_b32_e32 v230, 16, v182
	v_and_b32_e32 v231, 0xffff0000, v182
	v_lshlrev_b32_e32 v232, 16, v183
	v_and_b32_e32 v233, 0xffff0000, v183
	v_lshlrev_b32_e32 v234, 16, v184
	v_and_b32_e32 v235, 0xffff0000, v184
	v_lshlrev_b32_e32 v236, 16, v185
	v_and_b32_e32 v237, 0xffff0000, v185
	v_mul_f32_e32 v238, v112, v230
	v_mul_f32_e32 v239, v113, v231
	v_mul_f32_e32 v240, v114, v232
	v_mul_f32_e32 v241, v115, v233
	v_mul_f32_e32 v242, v108, v234
	v_mul_f32_e32 v243, v109, v235
	v_mul_f32_e32 v244, v110, v236
	v_mul_f32_e32 v245, v111, v237
	v_cvt_pk_bf16_f32 v246, v238, v239
	v_cvt_pk_bf16_f32 v247, v240, v241
	v_cvt_pk_bf16_f32 v248, v242, v243
	v_cvt_pk_bf16_f32 v249, v244, v245
	global_store_dwordx4 v[154:155], v[246:249], off
	s_waitcnt vmcnt(15)
	v_lshlrev_b32_e32 v230, 16, v186
	v_and_b32_e32 v231, 0xffff0000, v186
	v_lshlrev_b32_e32 v232, 16, v187
	v_and_b32_e32 v233, 0xffff0000, v187
	v_lshlrev_b32_e32 v234, 16, v188
	v_and_b32_e32 v235, 0xffff0000, v188
	v_lshlrev_b32_e32 v236, 16, v189
	v_and_b32_e32 v237, 0xffff0000, v189
	v_mul_f32_e32 v238, v80, v230
	v_mul_f32_e32 v239, v81, v231
	v_mul_f32_e32 v240, v82, v232
	v_mul_f32_e32 v241, v83, v233
	v_mul_f32_e32 v242, v76, v234
	v_mul_f32_e32 v243, v77, v235
	v_mul_f32_e32 v244, v78, v236
	v_mul_f32_e32 v245, v79, v237
	v_cvt_pk_bf16_f32 v246, v238, v239
	v_cvt_pk_bf16_f32 v247, v240, v241
	v_cvt_pk_bf16_f32 v248, v242, v243
	v_cvt_pk_bf16_f32 v249, v244, v245
	global_store_dwordx4 v[154:155], v[246:249], off offset:256
	v_lshl_add_u64 v[154:155], v[154:155], 0, s[94:95]
	s_waitcnt vmcnt(15)
	v_lshlrev_b32_e32 v230, 16, v190
	v_and_b32_e32 v231, 0xffff0000, v190
	v_lshlrev_b32_e32 v232, 16, v191
	v_and_b32_e32 v233, 0xffff0000, v191
	v_lshlrev_b32_e32 v234, 16, v192
	v_and_b32_e32 v235, 0xffff0000, v192
	v_lshlrev_b32_e32 v236, 16, v193
	v_and_b32_e32 v237, 0xffff0000, v193
	v_mul_f32_e32 v238, v104, v230
	v_mul_f32_e32 v239, v105, v231
	v_mul_f32_e32 v240, v106, v232
	v_mul_f32_e32 v241, v107, v233
	v_mul_f32_e32 v242, v100, v234
	v_mul_f32_e32 v243, v101, v235
	v_mul_f32_e32 v244, v102, v236
	v_mul_f32_e32 v245, v103, v237
	v_cvt_pk_bf16_f32 v246, v238, v239
	v_cvt_pk_bf16_f32 v247, v240, v241
	v_cvt_pk_bf16_f32 v248, v242, v243
	v_cvt_pk_bf16_f32 v249, v244, v245
	global_store_dwordx4 v[154:155], v[246:249], off
	s_waitcnt vmcnt(15)
	v_lshlrev_b32_e32 v230, 16, v194
	v_and_b32_e32 v231, 0xffff0000, v194
	v_lshlrev_b32_e32 v232, 16, v195
	v_and_b32_e32 v233, 0xffff0000, v195
	v_lshlrev_b32_e32 v234, 16, v196
	v_and_b32_e32 v235, 0xffff0000, v196
	v_lshlrev_b32_e32 v236, 16, v197
	v_and_b32_e32 v237, 0xffff0000, v197
	v_mul_f32_e32 v238, v72, v230
	v_mul_f32_e32 v239, v73, v231
	v_mul_f32_e32 v240, v74, v232
	v_mul_f32_e32 v241, v75, v233
	v_mul_f32_e32 v242, v68, v234
	v_mul_f32_e32 v243, v69, v235
	v_mul_f32_e32 v244, v70, v236
	v_mul_f32_e32 v245, v71, v237
	v_cvt_pk_bf16_f32 v246, v238, v239
	v_cvt_pk_bf16_f32 v247, v240, v241
	v_cvt_pk_bf16_f32 v248, v242, v243
	v_cvt_pk_bf16_f32 v249, v244, v245
	global_store_dwordx4 v[154:155], v[246:249], off offset:256
	v_lshl_add_u64 v[154:155], v[154:155], 0, s[96:97]
	s_waitcnt vmcnt(15)
	v_lshlrev_b32_e32 v230, 16, v198
	v_and_b32_e32 v231, 0xffff0000, v198
	v_lshlrev_b32_e32 v232, 16, v199
	v_and_b32_e32 v233, 0xffff0000, v199
	v_lshlrev_b32_e32 v234, 16, v200
	v_and_b32_e32 v235, 0xffff0000, v200
	v_lshlrev_b32_e32 v236, 16, v201
	v_and_b32_e32 v237, 0xffff0000, v201
	v_mul_f32_e32 v238, v64, v230
	v_mul_f32_e32 v239, v65, v231
	v_mul_f32_e32 v240, v66, v232
	v_mul_f32_e32 v241, v67, v233
	v_mul_f32_e32 v242, v60, v234
	v_mul_f32_e32 v243, v61, v235
	v_mul_f32_e32 v244, v62, v236
	v_mul_f32_e32 v245, v63, v237
	v_cvt_pk_bf16_f32 v246, v238, v239
	v_cvt_pk_bf16_f32 v247, v240, v241
	v_cvt_pk_bf16_f32 v248, v242, v243
	v_cvt_pk_bf16_f32 v249, v244, v245
	global_store_dwordx4 v[154:155], v[246:249], off
	s_waitcnt vmcnt(15)
	v_lshlrev_b32_e32 v230, 16, v202
	v_and_b32_e32 v231, 0xffff0000, v202
	v_lshlrev_b32_e32 v232, 16, v203
	v_and_b32_e32 v233, 0xffff0000, v203
	v_lshlrev_b32_e32 v234, 16, v204
	v_and_b32_e32 v235, 0xffff0000, v204
	v_lshlrev_b32_e32 v236, 16, v205
	v_and_b32_e32 v237, 0xffff0000, v205
	v_mul_f32_e32 v238, v32, v230
	v_mul_f32_e32 v239, v33, v231
	v_mul_f32_e32 v240, v34, v232
	v_mul_f32_e32 v241, v35, v233
	v_mul_f32_e32 v242, v28, v234
	v_mul_f32_e32 v243, v29, v235
	v_mul_f32_e32 v244, v30, v236
	v_mul_f32_e32 v245, v31, v237
	v_cvt_pk_bf16_f32 v246, v238, v239
	v_cvt_pk_bf16_f32 v247, v240, v241
	v_cvt_pk_bf16_f32 v248, v242, v243
	v_cvt_pk_bf16_f32 v249, v244, v245
	global_store_dwordx4 v[154:155], v[246:249], off offset:256
	v_lshl_add_u64 v[154:155], v[154:155], 0, s[94:95]
	s_waitcnt vmcnt(15)
	v_lshlrev_b32_e32 v230, 16, v206
	v_and_b32_e32 v231, 0xffff0000, v206
	v_lshlrev_b32_e32 v232, 16, v207
	v_and_b32_e32 v233, 0xffff0000, v207
	v_lshlrev_b32_e32 v234, 16, v208
	v_and_b32_e32 v235, 0xffff0000, v208
	v_lshlrev_b32_e32 v236, 16, v209
	v_and_b32_e32 v237, 0xffff0000, v209
	v_mul_f32_e32 v238, v56, v230
	v_mul_f32_e32 v239, v57, v231
	v_mul_f32_e32 v240, v58, v232
	v_mul_f32_e32 v241, v59, v233
	v_mul_f32_e32 v242, v52, v234
	v_mul_f32_e32 v243, v53, v235
	v_mul_f32_e32 v244, v54, v236
	v_mul_f32_e32 v245, v55, v237
	v_cvt_pk_bf16_f32 v246, v238, v239
	v_cvt_pk_bf16_f32 v247, v240, v241
	v_cvt_pk_bf16_f32 v248, v242, v243
	v_cvt_pk_bf16_f32 v249, v244, v245
	global_store_dwordx4 v[154:155], v[246:249], off
	s_waitcnt vmcnt(15)
	v_lshlrev_b32_e32 v230, 16, v210
	v_and_b32_e32 v231, 0xffff0000, v210
	v_lshlrev_b32_e32 v232, 16, v211
	v_and_b32_e32 v233, 0xffff0000, v211
	v_lshlrev_b32_e32 v234, 16, v212
	v_and_b32_e32 v235, 0xffff0000, v212
	v_lshlrev_b32_e32 v236, 16, v213
	v_and_b32_e32 v237, 0xffff0000, v213
	v_mul_f32_e32 v238, v24, v230
	v_mul_f32_e32 v239, v25, v231
	v_mul_f32_e32 v240, v26, v232
	v_mul_f32_e32 v241, v27, v233
	v_mul_f32_e32 v242, v20, v234
	v_mul_f32_e32 v243, v21, v235
	v_mul_f32_e32 v244, v22, v236
	v_mul_f32_e32 v245, v23, v237
	v_cvt_pk_bf16_f32 v246, v238, v239
	v_cvt_pk_bf16_f32 v247, v240, v241
	v_cvt_pk_bf16_f32 v248, v242, v243
	v_cvt_pk_bf16_f32 v249, v244, v245
	global_store_dwordx4 v[154:155], v[246:249], off offset:256
	v_lshl_add_u64 v[154:155], v[154:155], 0, s[94:95]
	s_waitcnt vmcnt(15)
	v_lshlrev_b32_e32 v230, 16, v214
	v_and_b32_e32 v231, 0xffff0000, v214
	v_lshlrev_b32_e32 v232, 16, v215
	v_and_b32_e32 v233, 0xffff0000, v215
	v_lshlrev_b32_e32 v234, 16, v216
	v_and_b32_e32 v235, 0xffff0000, v216
	v_lshlrev_b32_e32 v236, 16, v217
	v_and_b32_e32 v237, 0xffff0000, v217
	v_mul_f32_e32 v238, v48, v230
	v_mul_f32_e32 v239, v49, v231
	v_mul_f32_e32 v240, v50, v232
	v_mul_f32_e32 v241, v51, v233
	v_mul_f32_e32 v242, v44, v234
	v_mul_f32_e32 v243, v45, v235
	v_mul_f32_e32 v244, v46, v236
	v_mul_f32_e32 v245, v47, v237
	v_cvt_pk_bf16_f32 v246, v238, v239
	v_cvt_pk_bf16_f32 v247, v240, v241
	v_cvt_pk_bf16_f32 v248, v242, v243
	v_cvt_pk_bf16_f32 v249, v244, v245
	global_store_dwordx4 v[154:155], v[246:249], off
	s_waitcnt vmcnt(15)
	v_lshlrev_b32_e32 v230, 16, v218
	v_and_b32_e32 v231, 0xffff0000, v218
	v_lshlrev_b32_e32 v232, 16, v219
	v_and_b32_e32 v233, 0xffff0000, v219
	v_lshlrev_b32_e32 v234, 16, v220
	v_and_b32_e32 v235, 0xffff0000, v220
	v_lshlrev_b32_e32 v236, 16, v221
	v_and_b32_e32 v237, 0xffff0000, v221
	v_mul_f32_e32 v238, v16, v230
	v_mul_f32_e32 v239, v17, v231
	v_mul_f32_e32 v240, v18, v232
	v_mul_f32_e32 v241, v19, v233
	v_mul_f32_e32 v242, v12, v234
	v_mul_f32_e32 v243, v13, v235
	v_mul_f32_e32 v244, v14, v236
	v_mul_f32_e32 v245, v15, v237
	v_cvt_pk_bf16_f32 v246, v238, v239
	v_cvt_pk_bf16_f32 v247, v240, v241
	v_cvt_pk_bf16_f32 v248, v242, v243
	v_cvt_pk_bf16_f32 v249, v244, v245
	global_store_dwordx4 v[154:155], v[246:249], off offset:256
	v_lshl_add_u64 v[154:155], v[154:155], 0, s[94:95]
	s_waitcnt vmcnt(15)
	v_lshlrev_b32_e32 v230, 16, v222
	v_and_b32_e32 v231, 0xffff0000, v222
	v_lshlrev_b32_e32 v232, 16, v223
	v_and_b32_e32 v233, 0xffff0000, v223
	v_lshlrev_b32_e32 v234, 16, v224
	v_and_b32_e32 v235, 0xffff0000, v224
	v_lshlrev_b32_e32 v236, 16, v225
	v_and_b32_e32 v237, 0xffff0000, v225
	v_mul_f32_e32 v238, v40, v230
	v_mul_f32_e32 v239, v41, v231
	v_mul_f32_e32 v240, v42, v232
	v_mul_f32_e32 v241, v43, v233
	v_mul_f32_e32 v242, v36, v234
	v_mul_f32_e32 v243, v37, v235
	v_mul_f32_e32 v244, v38, v236
	v_mul_f32_e32 v245, v39, v237
	v_cvt_pk_bf16_f32 v246, v238, v239
	v_cvt_pk_bf16_f32 v247, v240, v241
	v_cvt_pk_bf16_f32 v248, v242, v243
	v_cvt_pk_bf16_f32 v249, v244, v245
	global_store_dwordx4 v[154:155], v[246:249], off
	s_waitcnt vmcnt(15)
	v_lshlrev_b32_e32 v230, 16, v226
	v_and_b32_e32 v231, 0xffff0000, v226
	v_lshlrev_b32_e32 v232, 16, v227
	v_and_b32_e32 v233, 0xffff0000, v227
	v_lshlrev_b32_e32 v234, 16, v228
	v_and_b32_e32 v235, 0xffff0000, v228
	v_lshlrev_b32_e32 v236, 16, v229
	v_and_b32_e32 v237, 0xffff0000, v229
	v_mul_f32_e32 v238, v8, v230
	v_mul_f32_e32 v239, v9, v231
	v_mul_f32_e32 v240, v10, v232
	v_mul_f32_e32 v241, v11, v233
	v_mul_f32_e32 v242, v4, v234
	v_mul_f32_e32 v243, v5, v235
	v_mul_f32_e32 v244, v6, v236
	v_mul_f32_e32 v245, v7, v237
	v_cvt_pk_bf16_f32 v246, v238, v239
	v_cvt_pk_bf16_f32 v247, v240, v241
	v_cvt_pk_bf16_f32 v248, v242, v243
	v_cvt_pk_bf16_f32 v249, v244, v245
	global_store_dwordx4 v[154:155], v[246:249], off offset:256

.LBB0_804:
	s_andn2_b64 vcc, exec, s[18:19]
	s_cbranch_vccnz .LBB0_737
	s_barrier
	s_branch .LBB0_737
.LBB0_822:
	s_mov_b32 s39, 0
	s_mov_b64 s[46:47], -1
	s_mov_b32 s41, s57
	s_mov_b32 s44, s58
	s_andn2_b64 vcc, exec, s[42:43]
	s_add_i32 s77, s77, 1
	s_cbranch_vccz .LBB0_742
	s_branch .LBB0_749
